# one static s_setprio 1 for waves 4-7 at kernel entry, all 144 per-MFMA-cluster s_setprio flips deleted (asm guide 6.3/7.4)
# speedup vs baseline: 1.0462x; 1.0083x over previous
; #define LAS __attribute__((address_space(3)))
; __global__ void __launch_bounds__(NTHREADS, 2) mega_fwd(Params P) {
;     extern __shared__ __attribute__((aligned(16))) unsigned char lds_raw[];
;     LAS unsigned char* lds = (LAS unsigned char*)lds_raw;
;     LAS float* rs = (LAS float*)(lds + STAGE_LDS);
;     cg::grid_group grid = cg::this_grid();
;     ...
;     volatile LAS unsigned* xbst = (volatile LAS unsigned*)(lds + LDS_BYTES - 16);
;     if (threadIdx.x < 4) xbst[threadIdx.x] = 0u;
;     __syncthreads();
;     const XcdBarrier xbar = xcd_barrier_post((unsigned*)(P.ws + WS_BAR), xbst);
_Z8mega_fwd6Params:
	s_load_dwordx8 s[4:11], s[0:1], 0xc0
	v_and_b32_e32 v162, 0x3ff, v0
	v_writelane_b32 v253, s2, 0
	v_readfirstlane_b32 s98, v162
	s_nop 3
	s_cmpk_lt_u32 s98, 0x100
	s_cbranch_scc1 .Lprio_done
	s_setprio 1
.Lprio_done:
	s_load_dwordx2 s[88:89], s[0:1], 0xe0
	v_cmp_gt_u32_e32 vcc, 4, v162
	v_writelane_b32 v253, s3, 1
	s_waitcnt lgkmcnt(0)
	v_writelane_b32 v253, s4, 2
	s_load_dword s2, s[0:1], 0xe8
	s_nop 0
	v_writelane_b32 v253, s5, 3
	v_writelane_b32 v253, s6, 4
	v_writelane_b32 v253, s7, 5
	v_writelane_b32 v253, s8, 6
	v_writelane_b32 v253, s9, 7
	v_writelane_b32 v253, s10, 8
	v_writelane_b32 v253, s11, 9
	s_waitcnt lgkmcnt(0)
	v_writelane_b32 v253, s2, 10
	s_add_u32 s2, s0, 0xe0
	s_addc_u32 s3, s1, 0
	v_writelane_b32 v253, s2, 11
	s_nop 1
	v_writelane_b32 v253, s3, 12
	s_and_saveexec_b64 s[6:7], vcc
	v_lshl_add_u32 v1, v162, 2, 0
	v_add_u32_e32 v1, 0x25ff0, v1
	v_mov_b32_e32 v2, 0
	ds_write_b32 v1, v2
	s_or_b64 exec, exec, s[6:7]
	s_load_dwordx8 s[4:11], s[0:1], 0xc0
	s_waitcnt lgkmcnt(0)
	s_barrier
	s_add_u32 s2, s10, 0x32920000
	s_addc_u32 s3, s11, 0
	v_writelane_b32 v253, s2, 13
	s_nop 1
	v_writelane_b32 v253, s3, 14
	s_getreg_b32 s2, hwreg(HW_REG_XCC_ID, 0, 4)
	s_and_b32 s2, s2, 15
	v_writelane_b32 v253, s2, 15
	v_cmp_eq_u32_e64 s[2:3], 0, v162
	s_mov_b64 s[6:7], exec
	s_nop 0
	v_writelane_b32 v253, s2, 17
	s_nop 1
	v_writelane_b32 v253, s3, 18
	s_and_b64 s[2:3], s[6:7], s[2:3]
	s_mov_b64 exec, s[2:3]
	s_cbranch_execz .LBB0_5
	s_mov_b64 s[8:9], exec
	v_mbcnt_lo_u32_b32 v1, s8, 0
	v_mbcnt_hi_u32_b32 v1, s9, v1
	v_cmp_eq_u32_e32 vcc, 0, v1
	s_and_b64 s[2:3], exec, vcc
	s_mov_b64 exec, s[2:3]
	s_cbranch_execz .LBB0_5
	v_readlane_b32 s2, v253, 15
	s_lshl_b32 s2, s2, 8
	s_bcnt1_i32_b64 s3, s[8:9]
	v_mov_b32_e32 v1, s2
	v_mov_b32_e32 v2, s3
	v_readlane_b32 s2, v253, 13
	v_readlane_b32 s3, v253, 14
	s_nop 4
	global_atomic_add v1, v2, s[2:3] offset:1024

; #define PG8_STAGE(bufoff, gbase, voff) do { const char* _gb = (const char*)(gbase); asm volatile("" : "+s"(_gb)); _Pragma("unroll") for (int _i = 0; _i < 2; ++_i) { unsigned _vo = (voff)[_i]; asm volatile("" : "+v"(_vo)); \
;         __builtin_amdgcn_global_load_lds((const GAS unsigned*)(_gb + _vo), (LAS unsigned*)(lds + (bufoff) + ldsw + _i * 8192), 16, 0, 0); } } while (0)
; #define PG8_LDA(dst, b, h) do { _Pragma("unroll") for (int m = 0; m < 4; ++m) _Pragma("unroll") for (int k = 0; k < 2; ++k) dst[m][k] = *(const LAS bf16x8*)(lds + PG8_SA(b, h) + aoff + m * 2048 + k * 1024); } while (0)
; #define PG8_LDB(dst, b, h) do { _Pragma("unroll") for (int n = 0; n < 2; ++n) _Pragma("unroll") for (int k = 0; k < 2; ++k) dst[n][k] = *(const LAS bf16x8*)(lds + PG8_SB(b, h) + boff + n * 2048 + k * 1024); } while (0)
; #define PG8_MMA(ai, bj, At, Bt) do { __builtin_amdgcn_s_setprio(1); _Pragma("unroll") for (int m = 0; m < 4; ++m) _Pragma("unroll") for (int n = 0; n < 2; ++n) _Pragma("unroll") for (int k = 0; k < 2; ++k) \
;         acc[ai][bj][m][n] = __builtin_amdgcn_mfma_f32_16x16x32_bf16(Bt[n][k], At[m][k], acc[ai][bj][m][n], 0, 0, 0); __builtin_amdgcn_s_setprio(0); } while (0)
; #define PG8_WAIT_L(n) asm volatile("s_waitcnt lgkmcnt(" #n ")" ::: "memory")
; #define PG8_BAR __builtin_amdgcn_s_barrier()
; #define PG8_SCHED __builtin_amdgcn_sched_barrier(0)
; template <class Epi, class Ord>
; __device__ __forceinline__ void gemm_phase(LAS unsigned char* lds, const Gemm g, const Ord& S, const Epi& E) {
;     ...
;             const bool last = (t == nt - 2);
;             const char* a1 = cA + (size_t)(t + 1) * kstep;
;             const char* a2 = last ? nA : cA + (size_t)(t + 2) * kstep; const char* b2 = last ? nB : cB + (size_t)(t + 2) * kstep;
;             const char* a3 = a2 + kstep; const char* b3 = b2 + kstep;
;             PG8_LDB(B0, 0, 0); PG8_SCHED; PG8_LDA(At, 0, 0); PG8_STAGE(PG8_SA(1, 1), a1 + hstep, voffA);
;             PG8_WAIT_L(8); PG8_BAR; PG8_WAIT_L(0); PG8_MMA(0, 0, At, B0); PG8_BAR; PG8_SCHED;
;             PG8_LDB(B1, 0, 1); PG8_STAGE(PG8_SB(0, 0), b2, voffB);
;             PG8_BAR; PG8_WAIT_L(0); PG8_MMA(0, 1, At, B1); PG8_BAR;
;             PG8_LDA(At, 0, 1); PG8_STAGE(PG8_SA(0, 0), a2, voffA);
;             PG8_BAR; PG8_WAIT_L(0); PG8_MMA(1, 0, At, B0); PG8_BAR; PG8_SCHED;
.LBB0_167:
	s_add_i32 s79, s12, 2
	s_cmp_eq_u32 s73, s12
	s_cselect_b32 s22, s0, s52
	s_cselect_b32 s23, s1, s53
	s_cselect_b32 s20, s44, s46
	s_cselect_b32 s21, s45, s47
	s_add_u32 s12, s22, 0x80
	s_addc_u32 s13, s23, 0
	s_add_i32 s80, 0, 0x10000
	v_add_u32_e32 v135, s80, v133
	ds_read_b128 v[136:139], v135
	ds_read_b128 v[140:143], v135 offset:1024
	ds_read_b128 v[144:147], v135 offset:2048
	ds_read_b128 v[148:151], v135 offset:3072
	s_add_u32 s24, s52, s10
	s_addc_u32 s25, s53, s11
	s_add_u32 s24, s24, 0xffffff80
	s_addc_u32 s25, s25, -1
	v_mov_b32_e32 v135, v128
	ds_read_b128 v[152:155], v134
	ds_read_b128 v[156:159], v134 offset:1024
	ds_read_b128 v[192:195], v134 offset:2048
	ds_read_b128 v[196:199], v134 offset:3072
	ds_read_b128 v[200:203], v134 offset:4096
	ds_read_b128 v[204:207], v134 offset:5120
	ds_read_b128 v[212:215], v134 offset:6144
	ds_read_b128 v[216:219], v134 offset:7168
	s_add_i32 m0, s65, 0xc000
	s_nop 0
	global_load_lds_dwordx4 v135, s[24:25]
	v_mov_b32_e32 v135, v130
	s_add_i32 m0, s65, 0xe000
	s_nop 0
	global_load_lds_dwordx4 v135, s[24:25]
	s_waitcnt lgkmcnt(8)
	s_barrier
	s_waitcnt lgkmcnt(0)
	s_waitcnt lgkmcnt(0)
	v_mfma_f32_16x16x32_bf16 v[120:123], v[136:139], v[152:155], v[120:123]
	v_mfma_f32_16x16x32_bf16 v[124:127], v[144:147], v[152:155], v[124:127]
	v_mfma_f32_16x16x32_bf16 v[108:111], v[136:139], v[192:195], v[108:111]
	v_mfma_f32_16x16x32_bf16 v[104:107], v[144:147], v[192:195], v[104:107]
	v_mfma_f32_16x16x32_bf16 v[92:95], v[136:139], v[200:203], v[92:95]
	v_mfma_f32_16x16x32_bf16 v[88:91], v[144:147], v[200:203], v[88:91]
	v_mfma_f32_16x16x32_bf16 v[76:79], v[136:139], v[212:215], v[76:79]
	v_mfma_f32_16x16x32_bf16 v[72:75], v[144:147], v[212:215], v[72:75]
	v_mfma_f32_16x16x32_bf16 v[120:123], v[140:143], v[156:159], v[120:123]
	v_mfma_f32_16x16x32_bf16 v[124:127], v[148:151], v[156:159], v[124:127]
	v_mfma_f32_16x16x32_bf16 v[108:111], v[140:143], v[196:199], v[108:111]
	v_mfma_f32_16x16x32_bf16 v[104:107], v[148:151], v[196:199], v[104:107]
	v_mfma_f32_16x16x32_bf16 v[92:95], v[140:143], v[204:207], v[92:95]
	v_mfma_f32_16x16x32_bf16 v[88:91], v[148:151], v[204:207], v[88:91]
	v_mfma_f32_16x16x32_bf16 v[76:79], v[140:143], v[216:219], v[76:79]
	v_mfma_f32_16x16x32_bf16 v[72:75], v[148:151], v[216:219], v[72:75]
	s_barrier
	s_add_i32 s82, 0, 0x14000
	v_add_u32_e32 v135, s82, v133
	ds_read_b128 v[220:223], v135
	ds_read_b128 v[224:227], v135 offset:1024
	ds_read_b128 v[228:231], v135 offset:2048
	ds_read_b128 v[232:235], v135 offset:3072
	s_mov_b64 s[24:25], s[20:21]
	v_mov_b32_e32 v135, v129
	s_add_i32 s80, s80, s64
	s_mov_b32 m0, s80
	s_nop 0
	global_load_lds_dwordx4 v135, s[24:25]
	v_mov_b32_e32 v135, v131
	s_add_i32 m0, s80, 0x2000
	s_nop 0
	global_load_lds_dwordx4 v135, s[24:25]
	s_barrier
	s_waitcnt lgkmcnt(0)
	s_waitcnt lgkmcnt(0)
	v_mfma_f32_16x16x32_bf16 v[116:119], v[220:223], v[152:155], v[116:119]
	v_mfma_f32_16x16x32_bf16 v[112:115], v[228:231], v[152:155], v[112:115]
	v_mfma_f32_16x16x32_bf16 v[100:103], v[220:223], v[192:195], v[100:103]
	v_mfma_f32_16x16x32_bf16 v[96:99], v[228:231], v[192:195], v[96:99]
	v_mfma_f32_16x16x32_bf16 v[84:87], v[220:223], v[200:203], v[84:87]
	v_mfma_f32_16x16x32_bf16 v[80:83], v[228:231], v[200:203], v[80:83]
	v_mfma_f32_16x16x32_bf16 v[68:71], v[220:223], v[212:215], v[68:71]
	v_mfma_f32_16x16x32_bf16 v[64:67], v[228:231], v[212:215], v[64:67]
	v_mfma_f32_16x16x32_bf16 v[116:119], v[224:227], v[156:159], v[116:119]
	v_mfma_f32_16x16x32_bf16 v[112:115], v[232:235], v[156:159], v[112:115]
	v_mfma_f32_16x16x32_bf16 v[100:103], v[224:227], v[196:199], v[100:103]
	v_mfma_f32_16x16x32_bf16 v[96:99], v[232:235], v[196:199], v[96:99]
	v_mfma_f32_16x16x32_bf16 v[84:87], v[224:227], v[204:207], v[84:87]
	v_mfma_f32_16x16x32_bf16 v[80:83], v[232:235], v[204:207], v[80:83]
	v_mfma_f32_16x16x32_bf16 v[68:71], v[224:227], v[216:219], v[68:71]
	v_mfma_f32_16x16x32_bf16 v[64:67], v[232:235], v[216:219], v[64:67]
	s_mov_b64 s[24:25], s[22:23]
	v_mov_b32_e32 v135, v128
	s_mov_b32 m0, s65
	s_barrier
	ds_read_b128 v[152:155], v134 offset:16384
	ds_read_b128 v[156:159], v134 offset:17408
	ds_read_b128 v[192:195], v134 offset:18432
	ds_read_b128 v[196:199], v134 offset:19456
	ds_read_b128 v[200:203], v134 offset:20480
	ds_read_b128 v[204:207], v134 offset:21504
	ds_read_b128 v[212:215], v134 offset:22528
	ds_read_b128 v[216:219], v134 offset:23552
	s_nop 0
	global_load_lds_dwordx4 v135, s[24:25]
	v_mov_b32_e32 v135, v130
	s_mov_b32 m0, s66
	s_nop 0
	global_load_lds_dwordx4 v135, s[24:25]
	s_barrier
	s_waitcnt lgkmcnt(0)
	s_waitcnt lgkmcnt(0)
	v_mfma_f32_16x16x32_bf16 v[60:63], v[136:139], v[152:155], v[60:63]
	v_mfma_f32_16x16x32_bf16 v[56:59], v[144:147], v[152:155], v[56:59]
	v_mfma_f32_16x16x32_bf16 v[44:47], v[136:139], v[192:195], v[44:47]
	v_mfma_f32_16x16x32_bf16 v[40:43], v[144:147], v[192:195], v[40:43]
	v_mfma_f32_16x16x32_bf16 v[28:31], v[136:139], v[200:203], v[28:31]
	v_mfma_f32_16x16x32_bf16 v[24:27], v[144:147], v[200:203], v[24:27]
	v_mfma_f32_16x16x32_bf16 v[12:15], v[136:139], v[212:215], v[12:15]
	v_mfma_f32_16x16x32_bf16 v[8:11], v[144:147], v[212:215], v[8:11]
	v_mfma_f32_16x16x32_bf16 v[60:63], v[140:143], v[156:159], v[60:63]
	v_mfma_f32_16x16x32_bf16 v[56:59], v[148:151], v[156:159], v[56:59]
	v_mfma_f32_16x16x32_bf16 v[44:47], v[140:143], v[196:199], v[44:47]
	v_mfma_f32_16x16x32_bf16 v[40:43], v[148:151], v[196:199], v[40:43]
	v_mfma_f32_16x16x32_bf16 v[28:31], v[140:143], v[204:207], v[28:31]
	v_mfma_f32_16x16x32_bf16 v[24:27], v[148:151], v[204:207], v[24:27]
	v_mfma_f32_16x16x32_bf16 v[12:15], v[140:143], v[216:219], v[12:15]
	v_mfma_f32_16x16x32_bf16 v[8:11], v[148:151], v[216:219], v[8:11]
	s_barrier
; #define PG8_STAGE(bufoff, gbase, voff) do { const char* _gb = (const char*)(gbase); asm volatile("" : "+s"(_gb)); _Pragma("unroll") for (int _i = 0; _i < 2; ++_i) { unsigned _vo = (voff)[_i]; asm volatile("" : "+v"(_vo)); \
;         __builtin_amdgcn_global_load_lds((const GAS unsigned*)(_gb + _vo), (LAS unsigned*)(lds + (bufoff) + ldsw + _i * 8192), 16, 0, 0); } } while (0)
; #define PG8_LDA(dst, b, h) do { _Pragma("unroll") for (int m = 0; m < 4; ++m) _Pragma("unroll") for (int k = 0; k < 2; ++k) dst[m][k] = *(const LAS bf16x8*)(lds + PG8_SA(b, h) + aoff + m * 2048 + k * 1024); } while (0)
; #define PG8_LDB(dst, b, h) do { _Pragma("unroll") for (int n = 0; n < 2; ++n) _Pragma("unroll") for (int k = 0; k < 2; ++k) dst[n][k] = *(const LAS bf16x8*)(lds + PG8_SB(b, h) + boff + n * 2048 + k * 1024); } while (0)
; #define PG8_MMA(ai, bj, At, Bt) do { __builtin_amdgcn_s_setprio(1); _Pragma("unroll") for (int m = 0; m < 4; ++m) _Pragma("unroll") for (int n = 0; n < 2; ++n) _Pragma("unroll") for (int k = 0; k < 2; ++k) \
;         acc[ai][bj][m][n] = __builtin_amdgcn_mfma_f32_16x16x32_bf16(Bt[n][k], At[m][k], acc[ai][bj][m][n], 0, 0, 0); __builtin_amdgcn_s_setprio(0); } while (0)
; #define PG8_WAIT_V(n) asm volatile("s_waitcnt vmcnt(" #n ")" ::: "memory")
; #define PG8_WAIT_L(n) asm volatile("s_waitcnt lgkmcnt(" #n ")" ::: "memory")
; #define PG8_BAR __builtin_amdgcn_s_barrier()
; #define PG8_SCHED __builtin_amdgcn_sched_barrier(0)
; template <class Epi, class Ord>
; __device__ __forceinline__ void gemm_phase(LAS unsigned char* lds, const Gemm g, const Ord& S, const Epi& E) {
;     ...
;             PG8_STAGE(PG8_SB(0, 1), b2 + hstep, voffB);
;             PG8_WAIT_V(6); PG8_BAR; PG8_MMA(1, 1, At, B1); PG8_BAR;
;             PG8_LDB(B0, 1, 0); PG8_SCHED; PG8_LDA(At, 1, 0); PG8_STAGE(PG8_SA(0, 1), a2 + hstep, voffA);
;             PG8_WAIT_L(8); PG8_BAR; PG8_WAIT_L(0); PG8_MMA(0, 0, At, B0); PG8_BAR; PG8_SCHED;
;             PG8_LDB(B1, 1, 1); PG8_STAGE(PG8_SB(1, 0), b3, voffB);
;             PG8_BAR; PG8_WAIT_L(0); PG8_MMA(0, 1, At, B1); PG8_BAR;
	s_add_u32 s24, s20, s10
	s_addc_u32 s25, s21, s11
	s_mov_b64 s[80:81], s[24:25]
	v_mov_b32_e32 v135, v129
	s_add_i32 s82, s82, s64
	s_mov_b32 m0, s82
	s_nop 0
	global_load_lds_dwordx4 v135, s[80:81]
	v_mov_b32_e32 v135, v131
	s_add_i32 m0, s82, 0x2000
	s_nop 0
	global_load_lds_dwordx4 v135, s[80:81]
	s_waitcnt vmcnt(6)
	s_barrier
	v_mfma_f32_16x16x32_bf16 v[52:55], v[220:223], v[152:155], v[52:55]
	v_mfma_f32_16x16x32_bf16 v[48:51], v[228:231], v[152:155], v[48:51]
	v_mfma_f32_16x16x32_bf16 v[36:39], v[220:223], v[192:195], v[36:39]
	v_mfma_f32_16x16x32_bf16 v[32:35], v[228:231], v[192:195], v[32:35]
	v_mfma_f32_16x16x32_bf16 v[20:23], v[220:223], v[200:203], v[20:23]
	v_mfma_f32_16x16x32_bf16 v[16:19], v[228:231], v[200:203], v[16:19]
	v_mfma_f32_16x16x32_bf16 v[4:7], v[220:223], v[212:215], v[4:7]
	v_mfma_f32_16x16x32_bf16 v[0:3], v[228:231], v[212:215], v[0:3]
	v_mfma_f32_16x16x32_bf16 v[52:55], v[224:227], v[156:159], v[52:55]
	v_mfma_f32_16x16x32_bf16 v[48:51], v[232:235], v[156:159], v[48:51]
	v_mfma_f32_16x16x32_bf16 v[36:39], v[224:227], v[196:199], v[36:39]
	v_mfma_f32_16x16x32_bf16 v[32:35], v[232:235], v[196:199], v[32:35]
	v_mfma_f32_16x16x32_bf16 v[20:23], v[224:227], v[204:207], v[20:23]
	v_mfma_f32_16x16x32_bf16 v[16:19], v[232:235], v[204:207], v[16:19]
	v_mfma_f32_16x16x32_bf16 v[4:7], v[224:227], v[216:219], v[4:7]
	v_mfma_f32_16x16x32_bf16 v[0:3], v[232:235], v[216:219], v[0:3]
	s_add_i32 s80, 0, 0x18000
	v_add_u32_e32 v135, s80, v133
	s_barrier
	ds_read_b128 v[136:139], v135
	ds_read_b128 v[140:143], v135 offset:1024
	ds_read_b128 v[144:147], v135 offset:2048
	ds_read_b128 v[148:151], v135 offset:3072
	s_add_u32 s22, s22, s10
	s_addc_u32 s23, s23, s11
	v_mov_b32_e32 v135, v128
	s_mov_b32 m0, s67
	ds_read_b128 v[152:155], v134 offset:32768
	ds_read_b128 v[156:159], v134 offset:33792
	ds_read_b128 v[192:195], v134 offset:34816
	ds_read_b128 v[196:199], v134 offset:35840
	ds_read_b128 v[200:203], v134 offset:36864
	ds_read_b128 v[204:207], v134 offset:37888
	ds_read_b128 v[212:215], v134 offset:38912
	ds_read_b128 v[216:219], v134 offset:39936
	s_nop 0
	global_load_lds_dwordx4 v135, s[22:23]
	v_mov_b32_e32 v135, v130
	s_mov_b32 m0, s68
	s_nop 0
	global_load_lds_dwordx4 v135, s[22:23]
	s_waitcnt lgkmcnt(8)
	s_barrier
	s_waitcnt lgkmcnt(0)
	s_waitcnt lgkmcnt(0)
	v_mfma_f32_16x16x32_bf16 v[120:123], v[136:139], v[152:155], v[120:123]
	v_mfma_f32_16x16x32_bf16 v[124:127], v[144:147], v[152:155], v[124:127]
	v_mfma_f32_16x16x32_bf16 v[108:111], v[136:139], v[192:195], v[108:111]
	v_mfma_f32_16x16x32_bf16 v[104:107], v[144:147], v[192:195], v[104:107]
	v_mfma_f32_16x16x32_bf16 v[92:95], v[136:139], v[200:203], v[92:95]
	v_mfma_f32_16x16x32_bf16 v[88:91], v[144:147], v[200:203], v[88:91]
	v_mfma_f32_16x16x32_bf16 v[76:79], v[136:139], v[212:215], v[76:79]
	v_mfma_f32_16x16x32_bf16 v[72:75], v[144:147], v[212:215], v[72:75]
	v_mfma_f32_16x16x32_bf16 v[120:123], v[140:143], v[156:159], v[120:123]
	v_mfma_f32_16x16x32_bf16 v[124:127], v[148:151], v[156:159], v[124:127]
	v_mfma_f32_16x16x32_bf16 v[108:111], v[140:143], v[196:199], v[108:111]
	v_mfma_f32_16x16x32_bf16 v[104:107], v[148:151], v[196:199], v[104:107]
	v_mfma_f32_16x16x32_bf16 v[92:95], v[140:143], v[204:207], v[92:95]
	v_mfma_f32_16x16x32_bf16 v[88:91], v[148:151], v[204:207], v[88:91]
	v_mfma_f32_16x16x32_bf16 v[76:79], v[140:143], v[216:219], v[76:79]
	v_mfma_f32_16x16x32_bf16 v[72:75], v[148:151], v[216:219], v[72:75]
	s_barrier
	s_add_i32 s22, 0, 0x1c000
	v_add_u32_e32 v135, s22, v133
	s_add_u32 s20, s20, 0x80
	ds_read_b128 v[220:223], v135
	ds_read_b128 v[224:227], v135 offset:1024
	ds_read_b128 v[228:231], v135 offset:2048
	ds_read_b128 v[232:235], v135 offset:3072
	s_addc_u32 s21, s21, 0
	v_mov_b32_e32 v135, v129
	s_add_i32 s23, s80, s64
	s_mov_b32 m0, s23
	s_nop 0
	global_load_lds_dwordx4 v135, s[20:21]
	v_mov_b32_e32 v135, v131
	s_add_i32 m0, s23, 0x2000
	s_nop 0
	global_load_lds_dwordx4 v135, s[20:21]
	s_barrier
; #define PG8_STAGE(bufoff, gbase, voff) do { const char* _gb = (const char*)(gbase); asm volatile("" : "+s"(_gb)); _Pragma("unroll") for (int _i = 0; _i < 2; ++_i) { unsigned _vo = (voff)[_i]; asm volatile("" : "+v"(_vo)); \
;         __builtin_amdgcn_global_load_lds((const GAS unsigned*)(_gb + _vo), (LAS unsigned*)(lds + (bufoff) + ldsw + _i * 8192), 16, 0, 0); } } while (0)
; #define PG8_LDA(dst, b, h) do { _Pragma("unroll") for (int m = 0; m < 4; ++m) _Pragma("unroll") for (int k = 0; k < 2; ++k) dst[m][k] = *(const LAS bf16x8*)(lds + PG8_SA(b, h) + aoff + m * 2048 + k * 1024); } while (0)
; #define PG8_MMA(ai, bj, At, Bt) do { __builtin_amdgcn_s_setprio(1); _Pragma("unroll") for (int m = 0; m < 4; ++m) _Pragma("unroll") for (int n = 0; n < 2; ++n) _Pragma("unroll") for (int k = 0; k < 2; ++k) \
;         acc[ai][bj][m][n] = __builtin_amdgcn_mfma_f32_16x16x32_bf16(Bt[n][k], At[m][k], acc[ai][bj][m][n], 0, 0, 0); __builtin_amdgcn_s_setprio(0); } while (0)
; #define PG8_WAIT_V(n) asm volatile("s_waitcnt vmcnt(" #n ")" ::: "memory")
; #define PG8_WAIT_L(n) asm volatile("s_waitcnt lgkmcnt(" #n ")" ::: "memory")
; #define PG8_BAR __builtin_amdgcn_s_barrier()
; #define PG8_SCHED __builtin_amdgcn_sched_barrier(0)
; template <class Epi, class Ord>
; __device__ __forceinline__ void gemm_phase(LAS unsigned char* lds, const Gemm g, const Ord& S, const Epi& E) {
;     ...
;             PG8_BAR; PG8_WAIT_L(0); PG8_MMA(0, 1, At, B1); PG8_BAR;
;             PG8_LDA(At, 1, 1); PG8_STAGE(PG8_SA(1, 0), a3, voffA);
;             PG8_BAR; PG8_WAIT_L(0); PG8_MMA(1, 0, At, B0); PG8_BAR; PG8_SCHED;
;             PG8_STAGE(PG8_SB(1, 1), b3 + hstep, voffB);
;             PG8_WAIT_V(6); PG8_BAR; PG8_MMA(1, 1, At, B1); PG8_BAR;
;         }
	s_waitcnt lgkmcnt(0)
	s_waitcnt lgkmcnt(0)
	v_mfma_f32_16x16x32_bf16 v[116:119], v[220:223], v[152:155], v[116:119]
	v_mfma_f32_16x16x32_bf16 v[112:115], v[228:231], v[152:155], v[112:115]
	v_mfma_f32_16x16x32_bf16 v[100:103], v[220:223], v[192:195], v[100:103]
	v_mfma_f32_16x16x32_bf16 v[96:99], v[228:231], v[192:195], v[96:99]
	v_mfma_f32_16x16x32_bf16 v[84:87], v[220:223], v[200:203], v[84:87]
	v_mfma_f32_16x16x32_bf16 v[80:83], v[228:231], v[200:203], v[80:83]
	v_mfma_f32_16x16x32_bf16 v[68:71], v[220:223], v[212:215], v[68:71]
	v_mfma_f32_16x16x32_bf16 v[64:67], v[228:231], v[212:215], v[64:67]
	v_mfma_f32_16x16x32_bf16 v[116:119], v[224:227], v[156:159], v[116:119]
	v_mfma_f32_16x16x32_bf16 v[112:115], v[232:235], v[156:159], v[112:115]
	v_mfma_f32_16x16x32_bf16 v[100:103], v[224:227], v[196:199], v[100:103]
	v_mfma_f32_16x16x32_bf16 v[96:99], v[232:235], v[196:199], v[96:99]
	v_mfma_f32_16x16x32_bf16 v[84:87], v[224:227], v[204:207], v[84:87]
	v_mfma_f32_16x16x32_bf16 v[80:83], v[232:235], v[204:207], v[80:83]
	v_mfma_f32_16x16x32_bf16 v[68:71], v[224:227], v[216:219], v[68:71]
	v_mfma_f32_16x16x32_bf16 v[64:67], v[232:235], v[216:219], v[64:67]
	v_mov_b32_e32 v135, v128
	s_mov_b32 m0, s70
	s_barrier
	ds_read_b128 v[152:155], v134 offset:49152
	ds_read_b128 v[156:159], v134 offset:50176
	ds_read_b128 v[192:195], v134 offset:51200
	ds_read_b128 v[196:199], v134 offset:52224
	ds_read_b128 v[200:203], v134 offset:53248
	ds_read_b128 v[204:207], v134 offset:54272
	ds_read_b128 v[212:215], v134 offset:55296
	ds_read_b128 v[216:219], v134 offset:56320
	s_nop 0
	global_load_lds_dwordx4 v135, s[12:13]
	v_mov_b32_e32 v135, v130
	s_mov_b32 m0, s71
	s_nop 0
	global_load_lds_dwordx4 v135, s[12:13]
	s_barrier
	s_waitcnt lgkmcnt(0)
	s_waitcnt lgkmcnt(0)
	v_mfma_f32_16x16x32_bf16 v[60:63], v[136:139], v[152:155], v[60:63]
	v_mfma_f32_16x16x32_bf16 v[56:59], v[144:147], v[152:155], v[56:59]
	v_mfma_f32_16x16x32_bf16 v[44:47], v[136:139], v[192:195], v[44:47]
	v_mfma_f32_16x16x32_bf16 v[40:43], v[144:147], v[192:195], v[40:43]
	v_mfma_f32_16x16x32_bf16 v[28:31], v[136:139], v[200:203], v[28:31]
	v_mfma_f32_16x16x32_bf16 v[24:27], v[144:147], v[200:203], v[24:27]
	v_mfma_f32_16x16x32_bf16 v[12:15], v[136:139], v[212:215], v[12:15]
	v_mfma_f32_16x16x32_bf16 v[8:11], v[144:147], v[212:215], v[8:11]
	v_mfma_f32_16x16x32_bf16 v[60:63], v[140:143], v[156:159], v[60:63]
	v_mfma_f32_16x16x32_bf16 v[56:59], v[148:151], v[156:159], v[56:59]
	v_mfma_f32_16x16x32_bf16 v[44:47], v[140:143], v[196:199], v[44:47]
	v_mfma_f32_16x16x32_bf16 v[40:43], v[148:151], v[196:199], v[40:43]
	v_mfma_f32_16x16x32_bf16 v[28:31], v[140:143], v[204:207], v[28:31]
	v_mfma_f32_16x16x32_bf16 v[24:27], v[148:151], v[204:207], v[24:27]
	v_mfma_f32_16x16x32_bf16 v[12:15], v[140:143], v[216:219], v[12:15]
	v_mfma_f32_16x16x32_bf16 v[8:11], v[148:151], v[216:219], v[8:11]
	s_barrier
	s_add_u32 s12, s24, 0x80
	s_addc_u32 s13, s25, 0
	v_mov_b32_e32 v135, v129
	s_add_i32 s20, s22, s64
	s_mov_b32 m0, s20
	s_nop 0
	global_load_lds_dwordx4 v135, s[12:13]
	v_mov_b32_e32 v135, v131
	s_add_i32 m0, s20, 0x2000
	s_nop 0
	global_load_lds_dwordx4 v135, s[12:13]
	s_waitcnt vmcnt(6)
	s_barrier
	v_mfma_f32_16x16x32_bf16 v[52:55], v[220:223], v[152:155], v[52:55]
	v_mfma_f32_16x16x32_bf16 v[48:51], v[228:231], v[152:155], v[48:51]
	v_mfma_f32_16x16x32_bf16 v[36:39], v[220:223], v[192:195], v[36:39]
	v_mfma_f32_16x16x32_bf16 v[32:35], v[228:231], v[192:195], v[32:35]
	v_mfma_f32_16x16x32_bf16 v[20:23], v[220:223], v[200:203], v[20:23]
	v_mfma_f32_16x16x32_bf16 v[16:19], v[228:231], v[200:203], v[16:19]
	v_mfma_f32_16x16x32_bf16 v[4:7], v[220:223], v[212:215], v[4:7]
	v_mfma_f32_16x16x32_bf16 v[0:3], v[228:231], v[212:215], v[0:3]
	v_mfma_f32_16x16x32_bf16 v[52:55], v[224:227], v[156:159], v[52:55]
	v_mfma_f32_16x16x32_bf16 v[48:51], v[232:235], v[156:159], v[48:51]
	v_mfma_f32_16x16x32_bf16 v[36:39], v[224:227], v[196:199], v[36:39]
	v_mfma_f32_16x16x32_bf16 v[32:35], v[232:235], v[196:199], v[32:35]
	v_mfma_f32_16x16x32_bf16 v[20:23], v[224:227], v[204:207], v[20:23]
	v_mfma_f32_16x16x32_bf16 v[16:19], v[232:235], v[204:207], v[16:19]
	v_mfma_f32_16x16x32_bf16 v[4:7], v[224:227], v[216:219], v[4:7]
	v_mfma_f32_16x16x32_bf16 v[0:3], v[232:235], v[216:219], v[0:3]
	s_add_u32 s46, s46, 0x100
	s_addc_u32 s47, s47, 0
	s_add_u32 s52, s52, 0x100
	s_addc_u32 s53, s53, 0
	s_cmp_ge_i32 s79, s69
	s_mov_b32 s12, s79
	s_barrier
	s_cbranch_scc0 .LBB0_167
	s_branch .LBB0_154

; #define PG8_STAGE(bufoff, gbase, voff) do { const char* _gb = (const char*)(gbase); asm volatile("" : "+s"(_gb)); _Pragma("unroll") for (int _i = 0; _i < 2; ++_i) { unsigned _vo = (voff)[_i]; asm volatile("" : "+v"(_vo)); \
;         __builtin_amdgcn_global_load_lds((const GAS unsigned*)(_gb + _vo), (LAS unsigned*)(lds + (bufoff) + ldsw + _i * 8192), 16, 0, 0); } } while (0)
; #define PG8_LDA(dst, b, h) do { _Pragma("unroll") for (int m = 0; m < 4; ++m) _Pragma("unroll") for (int k = 0; k < 2; ++k) dst[m][k] = *(const LAS bf16x8*)(lds + PG8_SA(b, h) + aoff + m * 2048 + k * 1024); } while (0)
; #define PG8_LDB(dst, b, h) do { _Pragma("unroll") for (int n = 0; n < 2; ++n) _Pragma("unroll") for (int k = 0; k < 2; ++k) dst[n][k] = *(const LAS bf16x8*)(lds + PG8_SB(b, h) + boff + n * 2048 + k * 1024); } while (0)
; #define PG8_MMA(ai, bj, At, Bt) do { __builtin_amdgcn_s_setprio(1); _Pragma("unroll") for (int m = 0; m < 4; ++m) _Pragma("unroll") for (int n = 0; n < 2; ++n) _Pragma("unroll") for (int k = 0; k < 2; ++k) \
;         acc[ai][bj][m][n] = __builtin_amdgcn_mfma_f32_16x16x32_bf16(Bt[n][k], At[m][k], acc[ai][bj][m][n], 0, 0, 0); __builtin_amdgcn_s_setprio(0); } while (0)
; #define PG8_WAIT_L(n) asm volatile("s_waitcnt lgkmcnt(" #n ")" ::: "memory")
; #define PG8_BAR __builtin_amdgcn_s_barrier()
; #define PG8_SCHED __builtin_amdgcn_sched_barrier(0)
; template <class Epi, class Ord>
; __device__ __forceinline__ void gemm_phase(LAS unsigned char* lds, const Gemm g, const Ord& S, const Epi& E) {
;     ...
;             const bool last = (t == nt - 2);
;             const char* a1 = cA + (size_t)(t + 1) * kstep;
;             const char* a2 = last ? nA : cA + (size_t)(t + 2) * kstep; const char* b2 = last ? nB : cB + (size_t)(t + 2) * kstep;
;             const char* a3 = a2 + kstep; const char* b3 = b2 + kstep;
;             PG8_LDB(B0, 0, 0); PG8_SCHED; PG8_LDA(At, 0, 0); PG8_STAGE(PG8_SA(1, 1), a1 + hstep, voffA);
;             PG8_WAIT_L(8); PG8_BAR; PG8_WAIT_L(0); PG8_MMA(0, 0, At, B0); PG8_BAR; PG8_SCHED;
;             PG8_LDB(B1, 0, 1); PG8_STAGE(PG8_SB(0, 0), b2, voffB);
;             PG8_BAR; PG8_WAIT_L(0); PG8_MMA(0, 1, At, B1); PG8_BAR;
;             PG8_LDA(At, 0, 1); PG8_STAGE(PG8_SA(0, 0), a2, voffA);
;             PG8_BAR; PG8_WAIT_L(0); PG8_MMA(1, 0, At, B0); PG8_BAR; PG8_SCHED;
.LBB0_200:
	s_add_i32 s94, s12, 2
	s_cmp_eq_u32 s81, s12
	s_cselect_b32 s22, s44, s56
	s_cselect_b32 s23, s45, s57
	s_cselect_b32 s20, s46, s52
	s_cselect_b32 s21, s47, s53
	s_add_u32 s12, s22, 0x80
	s_addc_u32 s13, s23, 0
	s_add_i32 s82, 0, 0x10000
	v_add_u32_e32 v144, s82, v204
	ds_read_b128 v[132:135], v144
	ds_read_b128 v[136:139], v144 offset:1024
	ds_read_b128 v[140:143], v144 offset:2048
	ds_read_b128 v[144:147], v144 offset:3072
	s_add_u32 s24, s56, s0
	s_addc_u32 s25, s57, s1
	s_add_u32 s24, s24, 0xffffff80
	s_addc_u32 s25, s25, -1
	v_mov_b32_e32 v168, v129
	ds_read_b128 v[148:151], v206
	ds_read_b128 v[152:155], v206 offset:1024
	ds_read_b128 v[156:159], v206 offset:2048
	ds_read_b128 v[192:195], v206 offset:3072
	ds_read_b128 v[196:199], v206 offset:4096
	ds_read_b128 v[212:215], v206 offset:5120
	ds_read_b128 v[216:219], v206 offset:6144
	ds_read_b128 v[220:223], v206 offset:7168
	s_add_i32 m0, s70, 0xc000
	s_nop 0
	global_load_lds_dwordx4 v168, s[24:25]
	v_mov_b32_e32 v168, v201
	s_add_i32 m0, s70, 0xe000
	s_nop 0
	global_load_lds_dwordx4 v168, s[24:25]
	s_waitcnt lgkmcnt(8)
	s_barrier
	s_waitcnt lgkmcnt(0)
	s_waitcnt lgkmcnt(0)
	v_mfma_f32_16x16x32_bf16 v[124:127], v[132:135], v[148:151], v[124:127]
	v_mfma_f32_16x16x32_bf16 v[120:123], v[140:143], v[148:151], v[120:123]
	v_mfma_f32_16x16x32_bf16 v[116:119], v[132:135], v[156:159], v[116:119]
	v_mfma_f32_16x16x32_bf16 v[112:115], v[140:143], v[156:159], v[112:115]
	v_mfma_f32_16x16x32_bf16 v[100:103], v[132:135], v[196:199], v[100:103]
	v_mfma_f32_16x16x32_bf16 v[96:99], v[140:143], v[196:199], v[96:99]
	v_mfma_f32_16x16x32_bf16 v[84:87], v[132:135], v[216:219], v[84:87]
	v_mfma_f32_16x16x32_bf16 v[80:83], v[140:143], v[216:219], v[80:83]
	v_mfma_f32_16x16x32_bf16 v[124:127], v[136:139], v[152:155], v[124:127]
	v_mfma_f32_16x16x32_bf16 v[120:123], v[144:147], v[152:155], v[120:123]
	v_mfma_f32_16x16x32_bf16 v[116:119], v[136:139], v[192:195], v[116:119]
	v_mfma_f32_16x16x32_bf16 v[112:115], v[144:147], v[192:195], v[112:115]
	v_mfma_f32_16x16x32_bf16 v[100:103], v[136:139], v[212:215], v[100:103]
	v_mfma_f32_16x16x32_bf16 v[96:99], v[144:147], v[212:215], v[96:99]
	v_mfma_f32_16x16x32_bf16 v[84:87], v[136:139], v[220:223], v[84:87]
	v_mfma_f32_16x16x32_bf16 v[80:83], v[144:147], v[220:223], v[80:83]
	s_barrier
	s_add_i32 s84, 0, 0x14000
	v_add_u32_e32 v168, s84, v204
	ds_read_b128 v[224:227], v168
	ds_read_b128 v[228:231], v168 offset:1024
	ds_read_b128 v[232:235], v168 offset:2048
	ds_read_b128 v[236:239], v168 offset:3072
	s_mov_b64 s[24:25], s[20:21]
	v_mov_b32_e32 v168, v200
	s_add_i32 s82, s82, s69
	s_mov_b32 m0, s82
	s_nop 0
	global_load_lds_dwordx4 v168, s[24:25]
	v_mov_b32_e32 v168, v202
	s_add_i32 m0, s82, 0x2000
	s_nop 0
	global_load_lds_dwordx4 v168, s[24:25]
	s_barrier
	s_waitcnt lgkmcnt(0)
	s_waitcnt lgkmcnt(0)
	v_mfma_f32_16x16x32_bf16 v[108:111], v[224:227], v[148:151], v[108:111]
	v_mfma_f32_16x16x32_bf16 v[104:107], v[232:235], v[148:151], v[104:107]
	v_mfma_f32_16x16x32_bf16 v[92:95], v[224:227], v[156:159], v[92:95]
	v_mfma_f32_16x16x32_bf16 v[88:91], v[232:235], v[156:159], v[88:91]
	v_mfma_f32_16x16x32_bf16 v[76:79], v[224:227], v[196:199], v[76:79]
	v_mfma_f32_16x16x32_bf16 v[72:75], v[232:235], v[196:199], v[72:75]
	v_mfma_f32_16x16x32_bf16 v[68:71], v[224:227], v[216:219], v[68:71]
	v_mfma_f32_16x16x32_bf16 v[64:67], v[232:235], v[216:219], v[64:67]
	v_mfma_f32_16x16x32_bf16 v[108:111], v[228:231], v[152:155], v[108:111]
	v_mfma_f32_16x16x32_bf16 v[104:107], v[236:239], v[152:155], v[104:107]
	v_mfma_f32_16x16x32_bf16 v[92:95], v[228:231], v[192:195], v[92:95]
	v_mfma_f32_16x16x32_bf16 v[88:91], v[236:239], v[192:195], v[88:91]
	v_mfma_f32_16x16x32_bf16 v[76:79], v[228:231], v[212:215], v[76:79]
	v_mfma_f32_16x16x32_bf16 v[72:75], v[236:239], v[212:215], v[72:75]
	v_mfma_f32_16x16x32_bf16 v[68:71], v[228:231], v[220:223], v[68:71]
	v_mfma_f32_16x16x32_bf16 v[64:67], v[236:239], v[220:223], v[64:67]
	s_mov_b64 s[24:25], s[22:23]
	v_mov_b32_e32 v168, v129
	s_mov_b32 m0, s70
	s_barrier
	ds_read_b128 v[148:151], v206 offset:16384
	ds_read_b128 v[152:155], v206 offset:17408
	ds_read_b128 v[156:159], v206 offset:18432
	ds_read_b128 v[192:195], v206 offset:19456
	ds_read_b128 v[196:199], v206 offset:20480
	ds_read_b128 v[212:215], v206 offset:21504
	ds_read_b128 v[216:219], v206 offset:22528
	ds_read_b128 v[220:223], v206 offset:23552
	s_nop 0
	global_load_lds_dwordx4 v168, s[24:25]
	v_mov_b32_e32 v168, v201
	s_mov_b32 m0, s71
	s_nop 0
	global_load_lds_dwordx4 v168, s[24:25]
	s_barrier
	s_waitcnt lgkmcnt(0)
	s_waitcnt lgkmcnt(0)
	v_mfma_f32_16x16x32_bf16 v[60:63], v[132:135], v[148:151], v[60:63]
	v_mfma_f32_16x16x32_bf16 v[56:59], v[140:143], v[148:151], v[56:59]
	v_mfma_f32_16x16x32_bf16 v[52:55], v[132:135], v[156:159], v[52:55]
	v_mfma_f32_16x16x32_bf16 v[48:51], v[140:143], v[156:159], v[48:51]
	v_mfma_f32_16x16x32_bf16 v[40:43], v[132:135], v[196:199], v[40:43]
	v_mfma_f32_16x16x32_bf16 v[32:35], v[140:143], v[196:199], v[32:35]
	v_mfma_f32_16x16x32_bf16 v[24:27], v[132:135], v[216:219], v[24:27]
	v_mfma_f32_16x16x32_bf16 v[16:19], v[140:143], v[216:219], v[16:19]
	v_mfma_f32_16x16x32_bf16 v[60:63], v[136:139], v[152:155], v[60:63]
	v_mfma_f32_16x16x32_bf16 v[56:59], v[144:147], v[152:155], v[56:59]
	v_mfma_f32_16x16x32_bf16 v[52:55], v[136:139], v[192:195], v[52:55]
	v_mfma_f32_16x16x32_bf16 v[48:51], v[144:147], v[192:195], v[48:51]
	v_mfma_f32_16x16x32_bf16 v[40:43], v[136:139], v[212:215], v[40:43]
	v_mfma_f32_16x16x32_bf16 v[32:35], v[144:147], v[212:215], v[32:35]
	v_mfma_f32_16x16x32_bf16 v[24:27], v[136:139], v[220:223], v[24:27]
	v_mfma_f32_16x16x32_bf16 v[16:19], v[144:147], v[220:223], v[16:19]
	s_barrier
; #define PG8_STAGE(bufoff, gbase, voff) do { const char* _gb = (const char*)(gbase); asm volatile("" : "+s"(_gb)); _Pragma("unroll") for (int _i = 0; _i < 2; ++_i) { unsigned _vo = (voff)[_i]; asm volatile("" : "+v"(_vo)); \
;         __builtin_amdgcn_global_load_lds((const GAS unsigned*)(_gb + _vo), (LAS unsigned*)(lds + (bufoff) + ldsw + _i * 8192), 16, 0, 0); } } while (0)
; #define PG8_LDA(dst, b, h) do { _Pragma("unroll") for (int m = 0; m < 4; ++m) _Pragma("unroll") for (int k = 0; k < 2; ++k) dst[m][k] = *(const LAS bf16x8*)(lds + PG8_SA(b, h) + aoff + m * 2048 + k * 1024); } while (0)
; #define PG8_LDB(dst, b, h) do { _Pragma("unroll") for (int n = 0; n < 2; ++n) _Pragma("unroll") for (int k = 0; k < 2; ++k) dst[n][k] = *(const LAS bf16x8*)(lds + PG8_SB(b, h) + boff + n * 2048 + k * 1024); } while (0)
; #define PG8_MMA(ai, bj, At, Bt) do { __builtin_amdgcn_s_setprio(1); _Pragma("unroll") for (int m = 0; m < 4; ++m) _Pragma("unroll") for (int n = 0; n < 2; ++n) _Pragma("unroll") for (int k = 0; k < 2; ++k) \
;         acc[ai][bj][m][n] = __builtin_amdgcn_mfma_f32_16x16x32_bf16(Bt[n][k], At[m][k], acc[ai][bj][m][n], 0, 0, 0); __builtin_amdgcn_s_setprio(0); } while (0)
; #define PG8_WAIT_V(n) asm volatile("s_waitcnt vmcnt(" #n ")" ::: "memory")
; #define PG8_WAIT_L(n) asm volatile("s_waitcnt lgkmcnt(" #n ")" ::: "memory")
; #define PG8_BAR __builtin_amdgcn_s_barrier()
; #define PG8_SCHED __builtin_amdgcn_sched_barrier(0)
; template <class Epi, class Ord>
; __device__ __forceinline__ void gemm_phase(LAS unsigned char* lds, const Gemm g, const Ord& S, const Epi& E) {
;     ...
;             PG8_STAGE(PG8_SB(0, 1), b2 + hstep, voffB);
;             PG8_WAIT_V(6); PG8_BAR; PG8_MMA(1, 1, At, B1); PG8_BAR;
;             PG8_LDB(B0, 1, 0); PG8_SCHED; PG8_LDA(At, 1, 0); PG8_STAGE(PG8_SA(0, 1), a2 + hstep, voffA);
;             PG8_WAIT_L(8); PG8_BAR; PG8_WAIT_L(0); PG8_MMA(0, 0, At, B0); PG8_BAR; PG8_SCHED;
;             PG8_LDB(B1, 1, 1); PG8_STAGE(PG8_SB(1, 0), b3, voffB);
;             PG8_BAR; PG8_WAIT_L(0); PG8_MMA(0, 1, At, B1); PG8_BAR;
;             PG8_LDA(At, 1, 1); PG8_STAGE(PG8_SA(1, 0), a3, voffA);
	s_add_u32 s24, s20, s0
	s_addc_u32 s25, s21, s1
	s_mov_b64 s[82:83], s[24:25]
	v_mov_b32_e32 v132, v200
	s_add_i32 s84, s84, s69
	s_mov_b32 m0, s84
	s_nop 0
	global_load_lds_dwordx4 v132, s[82:83]
	v_mov_b32_e32 v132, v202
	s_add_i32 m0, s84, 0x2000
	s_nop 0
	global_load_lds_dwordx4 v132, s[82:83]
	s_waitcnt vmcnt(6)
	s_barrier
	v_mfma_f32_16x16x32_bf16 v[44:47], v[224:227], v[148:151], v[44:47]
	v_mfma_f32_16x16x32_bf16 v[36:39], v[232:235], v[148:151], v[36:39]
	v_mfma_f32_16x16x32_bf16 v[28:31], v[224:227], v[156:159], v[28:31]
	v_mfma_f32_16x16x32_bf16 v[20:23], v[232:235], v[156:159], v[20:23]
	v_mfma_f32_16x16x32_bf16 v[12:15], v[224:227], v[196:199], v[12:15]
	v_mfma_f32_16x16x32_bf16 v[8:11], v[232:235], v[196:199], v[8:11]
	v_mfma_f32_16x16x32_bf16 v[4:7], v[224:227], v[216:219], v[4:7]
	v_mfma_f32_16x16x32_bf16 v[0:3], v[232:235], v[216:219], v[0:3]
	v_mfma_f32_16x16x32_bf16 v[44:47], v[228:231], v[152:155], v[44:47]
	v_mfma_f32_16x16x32_bf16 v[36:39], v[236:239], v[152:155], v[36:39]
	v_mfma_f32_16x16x32_bf16 v[28:31], v[228:231], v[192:195], v[28:31]
	v_mfma_f32_16x16x32_bf16 v[20:23], v[236:239], v[192:195], v[20:23]
	v_mfma_f32_16x16x32_bf16 v[12:15], v[228:231], v[212:215], v[12:15]
	v_mfma_f32_16x16x32_bf16 v[8:11], v[236:239], v[212:215], v[8:11]
	v_mfma_f32_16x16x32_bf16 v[4:7], v[228:231], v[220:223], v[4:7]
	v_mfma_f32_16x16x32_bf16 v[0:3], v[236:239], v[220:223], v[0:3]
	s_add_i32 s82, 0, 0x18000
	v_add_u32_e32 v144, s82, v204
	s_barrier
	ds_read_b128 v[132:135], v144
	ds_read_b128 v[136:139], v144 offset:1024
	ds_read_b128 v[140:143], v144 offset:2048
	ds_read_b128 v[144:147], v144 offset:3072
	s_add_u32 s22, s22, s0
	s_addc_u32 s23, s23, s1
	v_mov_b32_e32 v168, v129
	s_mov_b32 m0, s72
	ds_read_b128 v[148:151], v206 offset:32768
	ds_read_b128 v[152:155], v206 offset:33792
	ds_read_b128 v[156:159], v206 offset:34816
	ds_read_b128 v[192:195], v206 offset:35840
	ds_read_b128 v[196:199], v206 offset:36864
	ds_read_b128 v[212:215], v206 offset:37888
	ds_read_b128 v[216:219], v206 offset:38912
	ds_read_b128 v[220:223], v206 offset:39936
	s_nop 0
	global_load_lds_dwordx4 v168, s[22:23]
	v_mov_b32_e32 v168, v201
	s_mov_b32 m0, s73
	s_nop 0
	global_load_lds_dwordx4 v168, s[22:23]
	s_waitcnt lgkmcnt(8)
	s_barrier
	s_waitcnt lgkmcnt(0)
	s_waitcnt lgkmcnt(0)
	v_mfma_f32_16x16x32_bf16 v[124:127], v[132:135], v[148:151], v[124:127]
	v_mfma_f32_16x16x32_bf16 v[120:123], v[140:143], v[148:151], v[120:123]
	v_mfma_f32_16x16x32_bf16 v[116:119], v[132:135], v[156:159], v[116:119]
	v_mfma_f32_16x16x32_bf16 v[112:115], v[140:143], v[156:159], v[112:115]
	v_mfma_f32_16x16x32_bf16 v[100:103], v[132:135], v[196:199], v[100:103]
	v_mfma_f32_16x16x32_bf16 v[96:99], v[140:143], v[196:199], v[96:99]
	v_mfma_f32_16x16x32_bf16 v[84:87], v[132:135], v[216:219], v[84:87]
	v_mfma_f32_16x16x32_bf16 v[80:83], v[140:143], v[216:219], v[80:83]
	v_mfma_f32_16x16x32_bf16 v[124:127], v[136:139], v[152:155], v[124:127]
	v_mfma_f32_16x16x32_bf16 v[120:123], v[144:147], v[152:155], v[120:123]
	v_mfma_f32_16x16x32_bf16 v[116:119], v[136:139], v[192:195], v[116:119]
	v_mfma_f32_16x16x32_bf16 v[112:115], v[144:147], v[192:195], v[112:115]
	v_mfma_f32_16x16x32_bf16 v[100:103], v[136:139], v[212:215], v[100:103]
	v_mfma_f32_16x16x32_bf16 v[96:99], v[144:147], v[212:215], v[96:99]
	v_mfma_f32_16x16x32_bf16 v[84:87], v[136:139], v[220:223], v[84:87]
	v_mfma_f32_16x16x32_bf16 v[80:83], v[144:147], v[220:223], v[80:83]
	s_barrier
	s_add_i32 s22, 0, 0x1c000
	v_add_u32_e32 v168, s22, v204
	s_add_u32 s20, s20, 0x80
	ds_read_b128 v[224:227], v168
	ds_read_b128 v[228:231], v168 offset:1024
	ds_read_b128 v[232:235], v168 offset:2048
	ds_read_b128 v[236:239], v168 offset:3072
	s_addc_u32 s21, s21, 0
	v_mov_b32_e32 v168, v200
	s_add_i32 s23, s82, s69
	s_mov_b32 m0, s23
	s_nop 0
	global_load_lds_dwordx4 v168, s[20:21]
	v_mov_b32_e32 v168, v202
	s_add_i32 m0, s23, 0x2000
	s_nop 0
	global_load_lds_dwordx4 v168, s[20:21]
	s_barrier
	s_waitcnt lgkmcnt(0)
	s_waitcnt lgkmcnt(0)
	v_mfma_f32_16x16x32_bf16 v[108:111], v[224:227], v[148:151], v[108:111]
	v_mfma_f32_16x16x32_bf16 v[104:107], v[232:235], v[148:151], v[104:107]
	v_mfma_f32_16x16x32_bf16 v[92:95], v[224:227], v[156:159], v[92:95]
	v_mfma_f32_16x16x32_bf16 v[88:91], v[232:235], v[156:159], v[88:91]
	v_mfma_f32_16x16x32_bf16 v[76:79], v[224:227], v[196:199], v[76:79]
	v_mfma_f32_16x16x32_bf16 v[72:75], v[232:235], v[196:199], v[72:75]
	v_mfma_f32_16x16x32_bf16 v[68:71], v[224:227], v[216:219], v[68:71]
	v_mfma_f32_16x16x32_bf16 v[64:67], v[232:235], v[216:219], v[64:67]
	v_mfma_f32_16x16x32_bf16 v[108:111], v[228:231], v[152:155], v[108:111]
	v_mfma_f32_16x16x32_bf16 v[104:107], v[236:239], v[152:155], v[104:107]
	v_mfma_f32_16x16x32_bf16 v[92:95], v[228:231], v[192:195], v[92:95]
	v_mfma_f32_16x16x32_bf16 v[88:91], v[236:239], v[192:195], v[88:91]
	v_mfma_f32_16x16x32_bf16 v[76:79], v[228:231], v[212:215], v[76:79]
	v_mfma_f32_16x16x32_bf16 v[72:75], v[236:239], v[212:215], v[72:75]
	v_mfma_f32_16x16x32_bf16 v[68:71], v[228:231], v[220:223], v[68:71]
	v_mfma_f32_16x16x32_bf16 v[64:67], v[236:239], v[220:223], v[64:67]
	v_mov_b32_e32 v168, v129
	s_mov_b32 m0, s79
	s_barrier
	ds_read_b128 v[148:151], v206 offset:49152
	ds_read_b128 v[152:155], v206 offset:50176
	ds_read_b128 v[156:159], v206 offset:51200
	ds_read_b128 v[192:195], v206 offset:52224
	ds_read_b128 v[196:199], v206 offset:53248
	ds_read_b128 v[212:215], v206 offset:54272
	ds_read_b128 v[216:219], v206 offset:55296
	ds_read_b128 v[220:223], v206 offset:56320
	s_nop 0
	global_load_lds_dwordx4 v168, s[12:13]
	v_mov_b32_e32 v168, v201
	s_mov_b32 m0, s80
	s_nop 0
	global_load_lds_dwordx4 v168, s[12:13]
	s_barrier
; #define PG8_STAGE(bufoff, gbase, voff) do { const char* _gb = (const char*)(gbase); asm volatile("" : "+s"(_gb)); _Pragma("unroll") for (int _i = 0; _i < 2; ++_i) { unsigned _vo = (voff)[_i]; asm volatile("" : "+v"(_vo)); \
;         __builtin_amdgcn_global_load_lds((const GAS unsigned*)(_gb + _vo), (LAS unsigned*)(lds + (bufoff) + ldsw + _i * 8192), 16, 0, 0); } } while (0)
; #define PG8_MMA(ai, bj, At, Bt) do { __builtin_amdgcn_s_setprio(1); _Pragma("unroll") for (int m = 0; m < 4; ++m) _Pragma("unroll") for (int n = 0; n < 2; ++n) _Pragma("unroll") for (int k = 0; k < 2; ++k) \
;         acc[ai][bj][m][n] = __builtin_amdgcn_mfma_f32_16x16x32_bf16(Bt[n][k], At[m][k], acc[ai][bj][m][n], 0, 0, 0); __builtin_amdgcn_s_setprio(0); } while (0)
; #define PG8_WAIT_V(n) asm volatile("s_waitcnt vmcnt(" #n ")" ::: "memory")
; #define PG8_WAIT_L(n) asm volatile("s_waitcnt lgkmcnt(" #n ")" ::: "memory")
; #define PG8_BAR __builtin_amdgcn_s_barrier()
; #define PG8_SCHED __builtin_amdgcn_sched_barrier(0)
; template <class Epi, class Ord>
; __device__ __forceinline__ void gemm_phase(LAS unsigned char* lds, const Gemm g, const Ord& S, const Epi& E) {
;     ...
;             PG8_BAR; PG8_WAIT_L(0); PG8_MMA(1, 0, At, B0); PG8_BAR; PG8_SCHED;
;             PG8_STAGE(PG8_SB(1, 1), b3 + hstep, voffB);
;             PG8_WAIT_V(6); PG8_BAR; PG8_MMA(1, 1, At, B1); PG8_BAR;
;         }
;     template <int NM> __device__ __forceinline__ void round(const AccT& acc, const Unit& u, int ai, int m0, int wr, int wc, int fr, int fq) const {
;     ...
;                 if (MODE == 0) { d0 = acc[ai][bj][m][0] * alpha; d1 = acc[ai][bj][m][1] * alpha; }
	s_waitcnt lgkmcnt(0)
	s_waitcnt lgkmcnt(0)
	v_mfma_f32_16x16x32_bf16 v[60:63], v[132:135], v[148:151], v[60:63]
	v_mfma_f32_16x16x32_bf16 v[56:59], v[140:143], v[148:151], v[56:59]
	v_mfma_f32_16x16x32_bf16 v[52:55], v[132:135], v[156:159], v[52:55]
	v_mfma_f32_16x16x32_bf16 v[48:51], v[140:143], v[156:159], v[48:51]
	v_mfma_f32_16x16x32_bf16 v[40:43], v[132:135], v[196:199], v[40:43]
	v_mfma_f32_16x16x32_bf16 v[32:35], v[140:143], v[196:199], v[32:35]
	v_mfma_f32_16x16x32_bf16 v[24:27], v[132:135], v[216:219], v[24:27]
	v_mfma_f32_16x16x32_bf16 v[16:19], v[140:143], v[216:219], v[16:19]
	v_mfma_f32_16x16x32_bf16 v[60:63], v[136:139], v[152:155], v[60:63]
	v_mfma_f32_16x16x32_bf16 v[56:59], v[144:147], v[152:155], v[56:59]
	v_mfma_f32_16x16x32_bf16 v[52:55], v[136:139], v[192:195], v[52:55]
	v_mfma_f32_16x16x32_bf16 v[48:51], v[144:147], v[192:195], v[48:51]
	v_mfma_f32_16x16x32_bf16 v[40:43], v[136:139], v[212:215], v[40:43]
	v_mfma_f32_16x16x32_bf16 v[32:35], v[144:147], v[212:215], v[32:35]
	v_mfma_f32_16x16x32_bf16 v[24:27], v[136:139], v[220:223], v[24:27]
	v_mfma_f32_16x16x32_bf16 v[16:19], v[144:147], v[220:223], v[16:19]
	s_barrier
	s_add_u32 s12, s24, 0x80
	s_addc_u32 s13, s25, 0
	v_mov_b32_e32 v132, v200
	s_add_i32 s20, s22, s69
	s_mov_b32 m0, s20
	s_nop 0
	global_load_lds_dwordx4 v132, s[12:13]
	v_mov_b32_e32 v132, v202
	s_add_i32 m0, s20, 0x2000
	s_nop 0
	global_load_lds_dwordx4 v132, s[12:13]
	s_waitcnt vmcnt(6)
	s_barrier
	v_mfma_f32_16x16x32_bf16 v[44:47], v[224:227], v[148:151], v[44:47]
	v_mfma_f32_16x16x32_bf16 v[36:39], v[232:235], v[148:151], v[36:39]
	v_mfma_f32_16x16x32_bf16 v[28:31], v[224:227], v[156:159], v[28:31]
	v_mfma_f32_16x16x32_bf16 v[20:23], v[232:235], v[156:159], v[20:23]
	v_mfma_f32_16x16x32_bf16 v[12:15], v[224:227], v[196:199], v[12:15]
	v_mfma_f32_16x16x32_bf16 v[8:11], v[232:235], v[196:199], v[8:11]
	v_mfma_f32_16x16x32_bf16 v[4:7], v[224:227], v[216:219], v[4:7]
	v_mfma_f32_16x16x32_bf16 v[0:3], v[232:235], v[216:219], v[0:3]
	v_mfma_f32_16x16x32_bf16 v[44:47], v[228:231], v[152:155], v[44:47]
	v_mfma_f32_16x16x32_bf16 v[36:39], v[236:239], v[152:155], v[36:39]
	v_mfma_f32_16x16x32_bf16 v[28:31], v[228:231], v[192:195], v[28:31]
	v_mfma_f32_16x16x32_bf16 v[20:23], v[236:239], v[192:195], v[20:23]
	v_mfma_f32_16x16x32_bf16 v[12:15], v[228:231], v[212:215], v[12:15]
	v_mfma_f32_16x16x32_bf16 v[8:11], v[236:239], v[212:215], v[8:11]
	v_mfma_f32_16x16x32_bf16 v[4:7], v[228:231], v[220:223], v[4:7]
	v_mfma_f32_16x16x32_bf16 v[0:3], v[236:239], v[220:223], v[0:3]
	s_add_u32 s52, s52, 0x100
	s_addc_u32 s53, s53, 0
	s_add_u32 s56, s56, 0x100
	s_addc_u32 s57, s57, 0
	s_cmp_ge_i32 s94, s77
	s_mov_b32 s12, s94
	s_barrier
	s_cbranch_scc0 .LBB0_200
	v_readlane_b32 s94, v252, 31
	v_pk_mul_f32 v[154:155], v[126:127], 0.5 op_sel_hi:[1,0]
	v_pk_mul_f32 v[192:193], v[124:125], 0.5 op_sel_hi:[1,0]
	v_pk_mul_f32 v[156:157], v[122:123], 0.5 op_sel_hi:[1,0]
	v_pk_mul_f32 v[158:159], v[120:121], 0.5 op_sel_hi:[1,0]
	v_pk_mul_f32 v[150:151], v[110:111], 0.5 op_sel_hi:[1,0]
	v_pk_mul_f32 v[152:153], v[108:109], 0.5 op_sel_hi:[1,0]
	v_pk_mul_f32 v[126:127], v[106:107], 0.5 op_sel_hi:[1,0]
	v_pk_mul_f32 v[124:125], v[104:105], 0.5 op_sel_hi:[1,0]
	v_pk_mul_f32 v[146:147], v[118:119], 0.5 op_sel_hi:[1,0]
	v_pk_mul_f32 v[144:145], v[116:117], 0.5 op_sel_hi:[1,0]
	v_pk_mul_f32 v[142:143], v[114:115], 0.5 op_sel_hi:[1,0]
	v_pk_mul_f32 v[140:141], v[112:113], 0.5 op_sel_hi:[1,0]
	v_pk_mul_f32 v[138:139], v[94:95], 0.5 op_sel_hi:[1,0]
	v_pk_mul_f32 v[136:137], v[92:93], 0.5 op_sel_hi:[1,0]
	v_pk_mul_f32 v[134:135], v[90:91], 0.5 op_sel_hi:[1,0]
	v_pk_mul_f32 v[132:133], v[88:89], 0.5 op_sel_hi:[1,0]
	v_pk_mul_f32 v[122:123], v[102:103], 0.5 op_sel_hi:[1,0]
	v_pk_mul_f32 v[120:121], v[100:101], 0.5 op_sel_hi:[1,0]
	v_pk_mul_f32 v[118:119], v[98:99], 0.5 op_sel_hi:[1,0]
	v_pk_mul_f32 v[116:117], v[96:97], 0.5 op_sel_hi:[1,0]
	v_pk_mul_f32 v[114:115], v[78:79], 0.5 op_sel_hi:[1,0]
	v_pk_mul_f32 v[112:113], v[76:77], 0.5 op_sel_hi:[1,0]
	v_pk_mul_f32 v[110:111], v[74:75], 0.5 op_sel_hi:[1,0]
	v_pk_mul_f32 v[108:109], v[72:73], 0.5 op_sel_hi:[1,0]
	v_pk_mul_f32 v[106:107], v[86:87], 0.5 op_sel_hi:[1,0]
	v_pk_mul_f32 v[104:105], v[84:85], 0.5 op_sel_hi:[1,0]
	v_pk_mul_f32 v[102:103], v[82:83], 0.5 op_sel_hi:[1,0]
	v_pk_mul_f32 v[100:101], v[80:81], 0.5 op_sel_hi:[1,0]
	v_pk_mul_f32 v[98:99], v[70:71], 0.5 op_sel_hi:[1,0]
	v_pk_mul_f32 v[96:97], v[68:69], 0.5 op_sel_hi:[1,0]
	v_pk_mul_f32 v[94:95], v[66:67], 0.5 op_sel_hi:[1,0]
	v_pk_mul_f32 v[92:93], v[64:65], 0.5 op_sel_hi:[1,0]
	v_pk_mul_f32 v[86:87], v[62:63], 0.5 op_sel_hi:[1,0]
	v_pk_mul_f32 v[90:91], v[60:61], 0.5 op_sel_hi:[1,0]
	v_pk_mul_f32 v[84:85], v[58:59], 0.5 op_sel_hi:[1,0]
	v_pk_mul_f32 v[88:89], v[56:57], 0.5 op_sel_hi:[1,0]
	v_pk_mul_f32 v[80:81], v[46:47], 0.5 op_sel_hi:[1,0]
	v_pk_mul_f32 v[82:83], v[44:45], 0.5 op_sel_hi:[1,0]
	v_pk_mul_f32 v[78:79], v[38:39], 0.5 op_sel_hi:[1,0]
	v_pk_mul_f32 v[76:77], v[36:37], 0.5 op_sel_hi:[1,0]
	v_pk_mul_f32 v[74:75], v[54:55], 0.5 op_sel_hi:[1,0]
	v_pk_mul_f32 v[72:73], v[52:53], 0.5 op_sel_hi:[1,0]
	v_pk_mul_f32 v[70:71], v[50:51], 0.5 op_sel_hi:[1,0]
	v_pk_mul_f32 v[68:69], v[48:49], 0.5 op_sel_hi:[1,0]
	v_pk_mul_f32 v[66:67], v[30:31], 0.5 op_sel_hi:[1,0]
	v_pk_mul_f32 v[64:65], v[28:29], 0.5 op_sel_hi:[1,0]
	v_pk_mul_f32 v[62:63], v[22:23], 0.5 op_sel_hi:[1,0]
	v_pk_mul_f32 v[60:61], v[20:21], 0.5 op_sel_hi:[1,0]
	v_pk_mul_f32 v[58:59], v[42:43], 0.5 op_sel_hi:[1,0]
	v_pk_mul_f32 v[56:57], v[40:41], 0.5 op_sel_hi:[1,0]
	v_pk_mul_f32 v[54:55], v[34:35], 0.5 op_sel_hi:[1,0]
	v_pk_mul_f32 v[52:53], v[32:33], 0.5 op_sel_hi:[1,0]
	v_pk_mul_f32 v[50:51], v[14:15], 0.5 op_sel_hi:[1,0]
	v_pk_mul_f32 v[48:49], v[12:13], 0.5 op_sel_hi:[1,0]
	v_pk_mul_f32 v[46:47], v[10:11], 0.5 op_sel_hi:[1,0]
	v_pk_mul_f32 v[44:45], v[8:9], 0.5 op_sel_hi:[1,0]
	v_pk_mul_f32 v[42:43], v[26:27], 0.5 op_sel_hi:[1,0]
	v_pk_mul_f32 v[40:41], v[24:25], 0.5 op_sel_hi:[1,0]
	v_pk_mul_f32 v[38:39], v[18:19], 0.5 op_sel_hi:[1,0]
	v_pk_mul_f32 v[36:37], v[16:17], 0.5 op_sel_hi:[1,0]
	v_pk_mul_f32 v[34:35], v[6:7], 0.5 op_sel_hi:[1,0]
	v_pk_mul_f32 v[32:33], v[4:5], 0.5 op_sel_hi:[1,0]
	v_pk_mul_f32 v[30:31], v[2:3], 0.5 op_sel_hi:[1,0]
	v_pk_mul_f32 v[28:29], v[0:1], 0.5 op_sel_hi:[1,0]
	v_readlane_b32 s95, v252, 32

; #define PG8_STAGE(bufoff, gbase, voff) do { const char* _gb = (const char*)(gbase); asm volatile("" : "+s"(_gb)); _Pragma("unroll") for (int _i = 0; _i < 2; ++_i) { unsigned _vo = (voff)[_i]; asm volatile("" : "+v"(_vo)); \
;         __builtin_amdgcn_global_load_lds((const GAS unsigned*)(_gb + _vo), (LAS unsigned*)(lds + (bufoff) + ldsw + _i * 8192), 16, 0, 0); } } while (0)
; #define PG8_LDA(dst, b, h) do { _Pragma("unroll") for (int m = 0; m < 4; ++m) _Pragma("unroll") for (int k = 0; k < 2; ++k) dst[m][k] = *(const LAS bf16x8*)(lds + PG8_SA(b, h) + aoff + m * 2048 + k * 1024); } while (0)
; #define PG8_LDB(dst, b, h) do { _Pragma("unroll") for (int n = 0; n < 2; ++n) _Pragma("unroll") for (int k = 0; k < 2; ++k) dst[n][k] = *(const LAS bf16x8*)(lds + PG8_SB(b, h) + boff + n * 2048 + k * 1024); } while (0)
; #define PG8_MMA(ai, bj, At, Bt) do { __builtin_amdgcn_s_setprio(1); _Pragma("unroll") for (int m = 0; m < 4; ++m) _Pragma("unroll") for (int n = 0; n < 2; ++n) _Pragma("unroll") for (int k = 0; k < 2; ++k) \
;         acc[ai][bj][m][n] = __builtin_amdgcn_mfma_f32_16x16x32_bf16(Bt[n][k], At[m][k], acc[ai][bj][m][n], 0, 0, 0); __builtin_amdgcn_s_setprio(0); } while (0)
; #define PG8_WAIT_L(n) asm volatile("s_waitcnt lgkmcnt(" #n ")" ::: "memory")
; #define PG8_BAR __builtin_amdgcn_s_barrier()
; #define PG8_SCHED __builtin_amdgcn_sched_barrier(0)
; template <class Epi, class Ord>
; __device__ __forceinline__ void gemm_phase(LAS unsigned char* lds, const Gemm g, const Ord& S, const Epi& E) {
;     ...
;             const bool last = (t == nt - 2);
;             const char* a1 = cA + (size_t)(t + 1) * kstep;
;             const char* a2 = last ? nA : cA + (size_t)(t + 2) * kstep; const char* b2 = last ? nB : cB + (size_t)(t + 2) * kstep;
;             const char* a3 = a2 + kstep; const char* b3 = b2 + kstep;
;             PG8_LDB(B0, 0, 0); PG8_SCHED; PG8_LDA(At, 0, 0); PG8_STAGE(PG8_SA(1, 1), a1 + hstep, voffA);
;             PG8_WAIT_L(8); PG8_BAR; PG8_WAIT_L(0); PG8_MMA(0, 0, At, B0); PG8_BAR; PG8_SCHED;
;             PG8_LDB(B1, 0, 1); PG8_STAGE(PG8_SB(0, 0), b2, voffB);
;             PG8_BAR; PG8_WAIT_L(0); PG8_MMA(0, 1, At, B1); PG8_BAR;
;             PG8_LDA(At, 0, 1); PG8_STAGE(PG8_SA(0, 0), a2, voffA);
;             PG8_BAR; PG8_WAIT_L(0); PG8_MMA(1, 0, At, B0); PG8_BAR; PG8_SCHED;
.LBB0_236:
	s_add_i32 s80, s12, 2
	s_cmp_eq_u32 s73, s12
	s_cselect_b32 s22, s0, s52
	s_cselect_b32 s23, s1, s53
	s_cselect_b32 s20, s44, s46
	s_cselect_b32 s21, s45, s47
	s_add_u32 s12, s22, 0x80
	s_addc_u32 s13, s23, 0
	s_add_i32 s81, 0, 0x10000
	v_add_u32_e32 v152, s81, v133
	ds_read_b128 v[140:143], v152
	ds_read_b128 v[144:147], v152 offset:1024
	ds_read_b128 v[148:151], v152 offset:2048
	ds_read_b128 v[152:155], v152 offset:3072
	s_add_u32 s24, s52, s10
	s_addc_u32 s25, s53, s11
	s_add_u32 s24, s24, 0xffffff80
	s_addc_u32 s25, s25, -1
	v_mov_b32_e32 v168, v128
	ds_read_b128 v[156:159], v139
	ds_read_b128 v[192:195], v139 offset:1024
	ds_read_b128 v[196:199], v139 offset:2048
	ds_read_b128 v[200:203], v139 offset:3072
	ds_read_b128 v[204:207], v139 offset:4096
	ds_read_b128 v[212:215], v139 offset:5120
	ds_read_b128 v[216:219], v139 offset:6144
	ds_read_b128 v[220:223], v139 offset:7168
	s_add_i32 m0, s64, 0xc000
	s_nop 0
	global_load_lds_dwordx4 v168, s[24:25]
	v_mov_b32_e32 v168, v130
	s_add_i32 m0, s64, 0xe000
	s_nop 0
	global_load_lds_dwordx4 v168, s[24:25]
	s_waitcnt lgkmcnt(8)
	s_barrier
	s_waitcnt lgkmcnt(0)
	s_waitcnt lgkmcnt(0)
	v_mfma_f32_16x16x32_bf16 v[120:123], v[140:143], v[156:159], v[120:123]
	v_mfma_f32_16x16x32_bf16 v[112:115], v[148:151], v[156:159], v[112:115]
	v_mfma_f32_16x16x32_bf16 v[104:107], v[140:143], v[196:199], v[104:107]
	v_mfma_f32_16x16x32_bf16 v[96:99], v[148:151], v[196:199], v[96:99]
	v_mfma_f32_16x16x32_bf16 v[88:91], v[140:143], v[204:207], v[88:91]
	v_mfma_f32_16x16x32_bf16 v[80:83], v[148:151], v[204:207], v[80:83]
	v_mfma_f32_16x16x32_bf16 v[72:75], v[140:143], v[216:219], v[72:75]
	v_mfma_f32_16x16x32_bf16 v[64:67], v[148:151], v[216:219], v[64:67]
	v_mfma_f32_16x16x32_bf16 v[120:123], v[144:147], v[192:195], v[120:123]
	v_mfma_f32_16x16x32_bf16 v[112:115], v[152:155], v[192:195], v[112:115]
	v_mfma_f32_16x16x32_bf16 v[104:107], v[144:147], v[200:203], v[104:107]
	v_mfma_f32_16x16x32_bf16 v[96:99], v[152:155], v[200:203], v[96:99]
	v_mfma_f32_16x16x32_bf16 v[88:91], v[144:147], v[212:215], v[88:91]
	v_mfma_f32_16x16x32_bf16 v[80:83], v[152:155], v[212:215], v[80:83]
	v_mfma_f32_16x16x32_bf16 v[72:75], v[144:147], v[220:223], v[72:75]
	v_mfma_f32_16x16x32_bf16 v[64:67], v[152:155], v[220:223], v[64:67]
	s_barrier
	s_add_i32 s84, 0, 0x14000
	v_add_u32_e32 v168, s84, v133
	ds_read_b128 v[224:227], v168
	ds_read_b128 v[228:231], v168 offset:1024
	ds_read_b128 v[232:235], v168 offset:2048
	ds_read_b128 v[236:239], v168 offset:3072
	s_mov_b64 s[24:25], s[20:21]
	v_mov_b32_e32 v168, v129
	s_add_i32 s81, s81, s57
	s_mov_b32 m0, s81
	s_nop 0
	global_load_lds_dwordx4 v168, s[24:25]
	v_mov_b32_e32 v168, v131
	s_add_i32 m0, s81, 0x2000
	s_nop 0
	global_load_lds_dwordx4 v168, s[24:25]
	s_barrier
	s_waitcnt lgkmcnt(0)
	s_waitcnt lgkmcnt(0)
	v_mfma_f32_16x16x32_bf16 v[124:127], v[224:227], v[156:159], v[124:127]
	v_mfma_f32_16x16x32_bf16 v[116:119], v[232:235], v[156:159], v[116:119]
	v_mfma_f32_16x16x32_bf16 v[108:111], v[224:227], v[196:199], v[108:111]
	v_mfma_f32_16x16x32_bf16 v[100:103], v[232:235], v[196:199], v[100:103]
	v_mfma_f32_16x16x32_bf16 v[92:95], v[224:227], v[204:207], v[92:95]
	v_mfma_f32_16x16x32_bf16 v[84:87], v[232:235], v[204:207], v[84:87]
	v_mfma_f32_16x16x32_bf16 v[76:79], v[224:227], v[216:219], v[76:79]
	v_mfma_f32_16x16x32_bf16 v[68:71], v[232:235], v[216:219], v[68:71]
	v_mfma_f32_16x16x32_bf16 v[124:127], v[228:231], v[192:195], v[124:127]
	v_mfma_f32_16x16x32_bf16 v[116:119], v[236:239], v[192:195], v[116:119]
	v_mfma_f32_16x16x32_bf16 v[108:111], v[228:231], v[200:203], v[108:111]
	v_mfma_f32_16x16x32_bf16 v[100:103], v[236:239], v[200:203], v[100:103]
	v_mfma_f32_16x16x32_bf16 v[92:95], v[228:231], v[212:215], v[92:95]
	v_mfma_f32_16x16x32_bf16 v[84:87], v[236:239], v[212:215], v[84:87]
	v_mfma_f32_16x16x32_bf16 v[76:79], v[228:231], v[220:223], v[76:79]
	v_mfma_f32_16x16x32_bf16 v[68:71], v[236:239], v[220:223], v[68:71]
	s_mov_b64 s[24:25], s[22:23]
	v_mov_b32_e32 v168, v128
	s_mov_b32 m0, s64
	s_barrier
	ds_read_b128 v[156:159], v139 offset:16384
	ds_read_b128 v[192:195], v139 offset:17408
	ds_read_b128 v[196:199], v139 offset:18432
	ds_read_b128 v[200:203], v139 offset:19456
	ds_read_b128 v[204:207], v139 offset:20480
	ds_read_b128 v[212:215], v139 offset:21504
	ds_read_b128 v[216:219], v139 offset:22528
	ds_read_b128 v[220:223], v139 offset:23552
	s_nop 0
	global_load_lds_dwordx4 v168, s[24:25]
	v_mov_b32_e32 v168, v130
	s_mov_b32 m0, s65
	s_nop 0
	global_load_lds_dwordx4 v168, s[24:25]
	s_barrier
	s_waitcnt lgkmcnt(0)
	s_waitcnt lgkmcnt(0)
	v_mfma_f32_16x16x32_bf16 v[56:59], v[140:143], v[156:159], v[56:59]
	v_mfma_f32_16x16x32_bf16 v[48:51], v[148:151], v[156:159], v[48:51]
	v_mfma_f32_16x16x32_bf16 v[40:43], v[140:143], v[196:199], v[40:43]
	v_mfma_f32_16x16x32_bf16 v[32:35], v[148:151], v[196:199], v[32:35]
	v_mfma_f32_16x16x32_bf16 v[24:27], v[140:143], v[204:207], v[24:27]
	v_mfma_f32_16x16x32_bf16 v[16:19], v[148:151], v[204:207], v[16:19]
	v_mfma_f32_16x16x32_bf16 v[8:11], v[140:143], v[216:219], v[8:11]
	v_mfma_f32_16x16x32_bf16 v[0:3], v[148:151], v[216:219], v[0:3]
	v_mfma_f32_16x16x32_bf16 v[56:59], v[144:147], v[192:195], v[56:59]
	v_mfma_f32_16x16x32_bf16 v[48:51], v[152:155], v[192:195], v[48:51]
	v_mfma_f32_16x16x32_bf16 v[40:43], v[144:147], v[200:203], v[40:43]
	v_mfma_f32_16x16x32_bf16 v[32:35], v[152:155], v[200:203], v[32:35]
	v_mfma_f32_16x16x32_bf16 v[24:27], v[144:147], v[212:215], v[24:27]
	v_mfma_f32_16x16x32_bf16 v[16:19], v[152:155], v[212:215], v[16:19]
	v_mfma_f32_16x16x32_bf16 v[8:11], v[144:147], v[220:223], v[8:11]
	v_mfma_f32_16x16x32_bf16 v[0:3], v[152:155], v[220:223], v[0:3]
	s_barrier
; #define PG8_STAGE(bufoff, gbase, voff) do { const char* _gb = (const char*)(gbase); asm volatile("" : "+s"(_gb)); _Pragma("unroll") for (int _i = 0; _i < 2; ++_i) { unsigned _vo = (voff)[_i]; asm volatile("" : "+v"(_vo)); \
;         __builtin_amdgcn_global_load_lds((const GAS unsigned*)(_gb + _vo), (LAS unsigned*)(lds + (bufoff) + ldsw + _i * 8192), 16, 0, 0); } } while (0)
; #define PG8_LDA(dst, b, h) do { _Pragma("unroll") for (int m = 0; m < 4; ++m) _Pragma("unroll") for (int k = 0; k < 2; ++k) dst[m][k] = *(const LAS bf16x8*)(lds + PG8_SA(b, h) + aoff + m * 2048 + k * 1024); } while (0)
; #define PG8_LDB(dst, b, h) do { _Pragma("unroll") for (int n = 0; n < 2; ++n) _Pragma("unroll") for (int k = 0; k < 2; ++k) dst[n][k] = *(const LAS bf16x8*)(lds + PG8_SB(b, h) + boff + n * 2048 + k * 1024); } while (0)
; #define PG8_MMA(ai, bj, At, Bt) do { __builtin_amdgcn_s_setprio(1); _Pragma("unroll") for (int m = 0; m < 4; ++m) _Pragma("unroll") for (int n = 0; n < 2; ++n) _Pragma("unroll") for (int k = 0; k < 2; ++k) \
;         acc[ai][bj][m][n] = __builtin_amdgcn_mfma_f32_16x16x32_bf16(Bt[n][k], At[m][k], acc[ai][bj][m][n], 0, 0, 0); __builtin_amdgcn_s_setprio(0); } while (0)
; #define PG8_WAIT_V(n) asm volatile("s_waitcnt vmcnt(" #n ")" ::: "memory")
; #define PG8_WAIT_L(n) asm volatile("s_waitcnt lgkmcnt(" #n ")" ::: "memory")
; #define PG8_BAR __builtin_amdgcn_s_barrier()
; #define PG8_SCHED __builtin_amdgcn_sched_barrier(0)
; template <class Epi, class Ord>
; __device__ __forceinline__ void gemm_phase(LAS unsigned char* lds, const Gemm g, const Ord& S, const Epi& E) {
;     ...
;             PG8_STAGE(PG8_SB(0, 1), b2 + hstep, voffB);
;             PG8_WAIT_V(6); PG8_BAR; PG8_MMA(1, 1, At, B1); PG8_BAR;
;             PG8_LDB(B0, 1, 0); PG8_SCHED; PG8_LDA(At, 1, 0); PG8_STAGE(PG8_SA(0, 1), a2 + hstep, voffA);
;             PG8_WAIT_L(8); PG8_BAR; PG8_WAIT_L(0); PG8_MMA(0, 0, At, B0); PG8_BAR; PG8_SCHED;
;             PG8_LDB(B1, 1, 1); PG8_STAGE(PG8_SB(1, 0), b3, voffB);
;             PG8_BAR; PG8_WAIT_L(0); PG8_MMA(0, 1, At, B1); PG8_BAR;
	s_add_u32 s24, s20, s10
	s_addc_u32 s25, s21, s11
	s_mov_b64 s[82:83], s[24:25]
	v_mov_b32_e32 v140, v129
	s_add_i32 s81, s84, s57
	s_mov_b32 m0, s81
	s_nop 0
	global_load_lds_dwordx4 v140, s[82:83]
	v_mov_b32_e32 v140, v131
	s_add_i32 m0, s81, 0x2000
	s_nop 0
	global_load_lds_dwordx4 v140, s[82:83]
	s_waitcnt vmcnt(6)
	s_barrier
	v_mfma_f32_16x16x32_bf16 v[60:63], v[224:227], v[156:159], v[60:63]
	v_mfma_f32_16x16x32_bf16 v[52:55], v[232:235], v[156:159], v[52:55]
	v_mfma_f32_16x16x32_bf16 v[44:47], v[224:227], v[196:199], v[44:47]
	v_mfma_f32_16x16x32_bf16 v[36:39], v[232:235], v[196:199], v[36:39]
	v_mfma_f32_16x16x32_bf16 v[28:31], v[224:227], v[204:207], v[28:31]
	v_mfma_f32_16x16x32_bf16 v[20:23], v[232:235], v[204:207], v[20:23]
	v_mfma_f32_16x16x32_bf16 v[12:15], v[224:227], v[216:219], v[12:15]
	v_mfma_f32_16x16x32_bf16 v[4:7], v[232:235], v[216:219], v[4:7]
	v_mfma_f32_16x16x32_bf16 v[60:63], v[228:231], v[192:195], v[60:63]
	v_mfma_f32_16x16x32_bf16 v[52:55], v[236:239], v[192:195], v[52:55]
	v_mfma_f32_16x16x32_bf16 v[44:47], v[228:231], v[200:203], v[44:47]
	v_mfma_f32_16x16x32_bf16 v[36:39], v[236:239], v[200:203], v[36:39]
	v_mfma_f32_16x16x32_bf16 v[28:31], v[228:231], v[212:215], v[28:31]
	v_mfma_f32_16x16x32_bf16 v[20:23], v[236:239], v[212:215], v[20:23]
	v_mfma_f32_16x16x32_bf16 v[12:15], v[228:231], v[220:223], v[12:15]
	v_mfma_f32_16x16x32_bf16 v[4:7], v[236:239], v[220:223], v[4:7]
	s_add_i32 s81, 0, 0x18000
	v_add_u32_e32 v152, s81, v133
	s_barrier
	ds_read_b128 v[140:143], v152
	ds_read_b128 v[144:147], v152 offset:1024
	ds_read_b128 v[148:151], v152 offset:2048
	ds_read_b128 v[152:155], v152 offset:3072
	s_add_u32 s22, s22, s10
	s_addc_u32 s23, s23, s11
	v_mov_b32_e32 v168, v128
	s_mov_b32 m0, s68
	ds_read_b128 v[156:159], v139 offset:32768
	ds_read_b128 v[192:195], v139 offset:33792
	ds_read_b128 v[196:199], v139 offset:34816
	ds_read_b128 v[200:203], v139 offset:35840
	ds_read_b128 v[204:207], v139 offset:36864
	ds_read_b128 v[212:215], v139 offset:37888
	ds_read_b128 v[216:219], v139 offset:38912
	ds_read_b128 v[220:223], v139 offset:39936
	s_nop 0
	global_load_lds_dwordx4 v168, s[22:23]
	v_mov_b32_e32 v168, v130
	s_mov_b32 m0, s69
	s_nop 0
	global_load_lds_dwordx4 v168, s[22:23]
	s_waitcnt lgkmcnt(8)
	s_barrier
	s_waitcnt lgkmcnt(0)
	s_waitcnt lgkmcnt(0)
	v_mfma_f32_16x16x32_bf16 v[120:123], v[140:143], v[156:159], v[120:123]
	v_mfma_f32_16x16x32_bf16 v[112:115], v[148:151], v[156:159], v[112:115]
	v_mfma_f32_16x16x32_bf16 v[104:107], v[140:143], v[196:199], v[104:107]
	v_mfma_f32_16x16x32_bf16 v[96:99], v[148:151], v[196:199], v[96:99]
	v_mfma_f32_16x16x32_bf16 v[88:91], v[140:143], v[204:207], v[88:91]
	v_mfma_f32_16x16x32_bf16 v[80:83], v[148:151], v[204:207], v[80:83]
	v_mfma_f32_16x16x32_bf16 v[72:75], v[140:143], v[216:219], v[72:75]
	v_mfma_f32_16x16x32_bf16 v[64:67], v[148:151], v[216:219], v[64:67]
	v_mfma_f32_16x16x32_bf16 v[120:123], v[144:147], v[192:195], v[120:123]
	v_mfma_f32_16x16x32_bf16 v[112:115], v[152:155], v[192:195], v[112:115]
	v_mfma_f32_16x16x32_bf16 v[104:107], v[144:147], v[200:203], v[104:107]
	v_mfma_f32_16x16x32_bf16 v[96:99], v[152:155], v[200:203], v[96:99]
	v_mfma_f32_16x16x32_bf16 v[88:91], v[144:147], v[212:215], v[88:91]
	v_mfma_f32_16x16x32_bf16 v[80:83], v[152:155], v[212:215], v[80:83]
	v_mfma_f32_16x16x32_bf16 v[72:75], v[144:147], v[220:223], v[72:75]
	v_mfma_f32_16x16x32_bf16 v[64:67], v[152:155], v[220:223], v[64:67]
	s_barrier
	s_add_i32 s22, 0, 0x1c000
	v_add_u32_e32 v168, s22, v133
	s_add_u32 s20, s20, 0x80
	ds_read_b128 v[224:227], v168
	ds_read_b128 v[228:231], v168 offset:1024
	ds_read_b128 v[232:235], v168 offset:2048
	ds_read_b128 v[236:239], v168 offset:3072
	s_addc_u32 s21, s21, 0
	v_mov_b32_e32 v168, v129
	s_add_i32 s23, s81, s57
	s_mov_b32 m0, s23
	s_nop 0
	global_load_lds_dwordx4 v168, s[20:21]
	v_mov_b32_e32 v168, v131
	s_add_i32 m0, s23, 0x2000
	s_nop 0
	global_load_lds_dwordx4 v168, s[20:21]
	s_barrier
; #define PG8_STAGE(bufoff, gbase, voff) do { const char* _gb = (const char*)(gbase); asm volatile("" : "+s"(_gb)); _Pragma("unroll") for (int _i = 0; _i < 2; ++_i) { unsigned _vo = (voff)[_i]; asm volatile("" : "+v"(_vo)); \
;         __builtin_amdgcn_global_load_lds((const GAS unsigned*)(_gb + _vo), (LAS unsigned*)(lds + (bufoff) + ldsw + _i * 8192), 16, 0, 0); } } while (0)
; #define PG8_LDA(dst, b, h) do { _Pragma("unroll") for (int m = 0; m < 4; ++m) _Pragma("unroll") for (int k = 0; k < 2; ++k) dst[m][k] = *(const LAS bf16x8*)(lds + PG8_SA(b, h) + aoff + m * 2048 + k * 1024); } while (0)
; #define PG8_MMA(ai, bj, At, Bt) do { __builtin_amdgcn_s_setprio(1); _Pragma("unroll") for (int m = 0; m < 4; ++m) _Pragma("unroll") for (int n = 0; n < 2; ++n) _Pragma("unroll") for (int k = 0; k < 2; ++k) \
;         acc[ai][bj][m][n] = __builtin_amdgcn_mfma_f32_16x16x32_bf16(Bt[n][k], At[m][k], acc[ai][bj][m][n], 0, 0, 0); __builtin_amdgcn_s_setprio(0); } while (0)
; #define PG8_WAIT_V(n) asm volatile("s_waitcnt vmcnt(" #n ")" ::: "memory")
; #define PG8_WAIT_L(n) asm volatile("s_waitcnt lgkmcnt(" #n ")" ::: "memory")
; #define PG8_BAR __builtin_amdgcn_s_barrier()
; #define PG8_SCHED __builtin_amdgcn_sched_barrier(0)
; template <class Epi, class Ord>
; __device__ __forceinline__ void gemm_phase(LAS unsigned char* lds, const Gemm g, const Ord& S, const Epi& E) {
;     ...
;             PG8_BAR; PG8_WAIT_L(0); PG8_MMA(0, 1, At, B1); PG8_BAR;
;             PG8_LDA(At, 1, 1); PG8_STAGE(PG8_SA(1, 0), a3, voffA);
;             PG8_BAR; PG8_WAIT_L(0); PG8_MMA(1, 0, At, B0); PG8_BAR; PG8_SCHED;
;             PG8_STAGE(PG8_SB(1, 1), b3 + hstep, voffB);
;             PG8_WAIT_V(6); PG8_BAR; PG8_MMA(1, 1, At, B1); PG8_BAR;
;         }
	s_waitcnt lgkmcnt(0)
	s_waitcnt lgkmcnt(0)
	v_mfma_f32_16x16x32_bf16 v[124:127], v[224:227], v[156:159], v[124:127]
	v_mfma_f32_16x16x32_bf16 v[116:119], v[232:235], v[156:159], v[116:119]
	v_mfma_f32_16x16x32_bf16 v[108:111], v[224:227], v[196:199], v[108:111]
	v_mfma_f32_16x16x32_bf16 v[100:103], v[232:235], v[196:199], v[100:103]
	v_mfma_f32_16x16x32_bf16 v[92:95], v[224:227], v[204:207], v[92:95]
	v_mfma_f32_16x16x32_bf16 v[84:87], v[232:235], v[204:207], v[84:87]
	v_mfma_f32_16x16x32_bf16 v[76:79], v[224:227], v[216:219], v[76:79]
	v_mfma_f32_16x16x32_bf16 v[68:71], v[232:235], v[216:219], v[68:71]
	v_mfma_f32_16x16x32_bf16 v[124:127], v[228:231], v[192:195], v[124:127]
	v_mfma_f32_16x16x32_bf16 v[116:119], v[236:239], v[192:195], v[116:119]
	v_mfma_f32_16x16x32_bf16 v[108:111], v[228:231], v[200:203], v[108:111]
	v_mfma_f32_16x16x32_bf16 v[100:103], v[236:239], v[200:203], v[100:103]
	v_mfma_f32_16x16x32_bf16 v[92:95], v[228:231], v[212:215], v[92:95]
	v_mfma_f32_16x16x32_bf16 v[84:87], v[236:239], v[212:215], v[84:87]
	v_mfma_f32_16x16x32_bf16 v[76:79], v[228:231], v[220:223], v[76:79]
	v_mfma_f32_16x16x32_bf16 v[68:71], v[236:239], v[220:223], v[68:71]
	v_mov_b32_e32 v168, v128
	s_mov_b32 m0, s71
	s_barrier
	ds_read_b128 v[156:159], v139 offset:49152
	ds_read_b128 v[192:195], v139 offset:50176
	ds_read_b128 v[196:199], v139 offset:51200
	ds_read_b128 v[200:203], v139 offset:52224
	ds_read_b128 v[204:207], v139 offset:53248
	ds_read_b128 v[212:215], v139 offset:54272
	ds_read_b128 v[216:219], v139 offset:55296
	ds_read_b128 v[220:223], v139 offset:56320
	s_nop 0
	global_load_lds_dwordx4 v168, s[12:13]
	v_mov_b32_e32 v168, v130
	s_mov_b32 m0, s72
	s_nop 0
	global_load_lds_dwordx4 v168, s[12:13]
	s_barrier
	s_waitcnt lgkmcnt(0)
	s_waitcnt lgkmcnt(0)
	v_mfma_f32_16x16x32_bf16 v[56:59], v[140:143], v[156:159], v[56:59]
	v_mfma_f32_16x16x32_bf16 v[48:51], v[148:151], v[156:159], v[48:51]
	v_mfma_f32_16x16x32_bf16 v[40:43], v[140:143], v[196:199], v[40:43]
	v_mfma_f32_16x16x32_bf16 v[32:35], v[148:151], v[196:199], v[32:35]
	v_mfma_f32_16x16x32_bf16 v[24:27], v[140:143], v[204:207], v[24:27]
	v_mfma_f32_16x16x32_bf16 v[16:19], v[148:151], v[204:207], v[16:19]
	v_mfma_f32_16x16x32_bf16 v[8:11], v[140:143], v[216:219], v[8:11]
	v_mfma_f32_16x16x32_bf16 v[0:3], v[148:151], v[216:219], v[0:3]
	v_mfma_f32_16x16x32_bf16 v[56:59], v[144:147], v[192:195], v[56:59]
	v_mfma_f32_16x16x32_bf16 v[48:51], v[152:155], v[192:195], v[48:51]
	v_mfma_f32_16x16x32_bf16 v[40:43], v[144:147], v[200:203], v[40:43]
	v_mfma_f32_16x16x32_bf16 v[32:35], v[152:155], v[200:203], v[32:35]
	v_mfma_f32_16x16x32_bf16 v[24:27], v[144:147], v[212:215], v[24:27]
	v_mfma_f32_16x16x32_bf16 v[16:19], v[152:155], v[212:215], v[16:19]
	v_mfma_f32_16x16x32_bf16 v[8:11], v[144:147], v[220:223], v[8:11]
	v_mfma_f32_16x16x32_bf16 v[0:3], v[152:155], v[220:223], v[0:3]
	s_barrier
	s_add_u32 s12, s24, 0x80
	s_addc_u32 s13, s25, 0
	v_mov_b32_e32 v140, v129
	s_add_i32 s20, s22, s57
	s_mov_b32 m0, s20
	s_nop 0
	global_load_lds_dwordx4 v140, s[12:13]
	v_mov_b32_e32 v140, v131
	s_add_i32 m0, s20, 0x2000
	s_nop 0
	global_load_lds_dwordx4 v140, s[12:13]
	s_waitcnt vmcnt(6)
	s_barrier
	v_mfma_f32_16x16x32_bf16 v[60:63], v[224:227], v[156:159], v[60:63]
	v_mfma_f32_16x16x32_bf16 v[52:55], v[232:235], v[156:159], v[52:55]
	v_mfma_f32_16x16x32_bf16 v[44:47], v[224:227], v[196:199], v[44:47]
	v_mfma_f32_16x16x32_bf16 v[36:39], v[232:235], v[196:199], v[36:39]
	v_mfma_f32_16x16x32_bf16 v[28:31], v[224:227], v[204:207], v[28:31]
	v_mfma_f32_16x16x32_bf16 v[20:23], v[232:235], v[204:207], v[20:23]
	v_mfma_f32_16x16x32_bf16 v[12:15], v[224:227], v[216:219], v[12:15]
	v_mfma_f32_16x16x32_bf16 v[4:7], v[232:235], v[216:219], v[4:7]
	v_mfma_f32_16x16x32_bf16 v[60:63], v[228:231], v[192:195], v[60:63]
	v_mfma_f32_16x16x32_bf16 v[52:55], v[236:239], v[192:195], v[52:55]
	v_mfma_f32_16x16x32_bf16 v[44:47], v[228:231], v[200:203], v[44:47]
	v_mfma_f32_16x16x32_bf16 v[36:39], v[236:239], v[200:203], v[36:39]
	v_mfma_f32_16x16x32_bf16 v[28:31], v[228:231], v[212:215], v[28:31]
	v_mfma_f32_16x16x32_bf16 v[20:23], v[236:239], v[212:215], v[20:23]
	v_mfma_f32_16x16x32_bf16 v[12:15], v[228:231], v[220:223], v[12:15]
	v_mfma_f32_16x16x32_bf16 v[4:7], v[236:239], v[220:223], v[4:7]
	s_add_u32 s46, s46, 0x100
	s_addc_u32 s47, s47, 0
	s_add_u32 s52, s52, 0x100
	s_addc_u32 s53, s53, 0
	s_cmp_ge_i32 s80, s70
	s_mov_b32 s12, s80
	s_barrier
	s_cbranch_scc0 .LBB0_236
	s_branch .LBB0_227

; #define PG8_STAGE(bufoff, gbase, voff) do { const char* _gb = (const char*)(gbase); asm volatile("" : "+s"(_gb)); _Pragma("unroll") for (int _i = 0; _i < 2; ++_i) { unsigned _vo = (voff)[_i]; asm volatile("" : "+v"(_vo)); \
;         __builtin_amdgcn_global_load_lds((const GAS unsigned*)(_gb + _vo), (LAS unsigned*)(lds + (bufoff) + ldsw + _i * 8192), 16, 0, 0); } } while (0)
; #define PG8_LDA(dst, b, h) do { _Pragma("unroll") for (int m = 0; m < 4; ++m) _Pragma("unroll") for (int k = 0; k < 2; ++k) dst[m][k] = *(const LAS bf16x8*)(lds + PG8_SA(b, h) + aoff + m * 2048 + k * 1024); } while (0)
; #define PG8_LDB(dst, b, h) do { _Pragma("unroll") for (int n = 0; n < 2; ++n) _Pragma("unroll") for (int k = 0; k < 2; ++k) dst[n][k] = *(const LAS bf16x8*)(lds + PG8_SB(b, h) + boff + n * 2048 + k * 1024); } while (0)
; #define PG8_MMA(ai, bj, At, Bt) do { __builtin_amdgcn_s_setprio(1); _Pragma("unroll") for (int m = 0; m < 4; ++m) _Pragma("unroll") for (int n = 0; n < 2; ++n) _Pragma("unroll") for (int k = 0; k < 2; ++k) \
;         acc[ai][bj][m][n] = __builtin_amdgcn_mfma_f32_16x16x32_bf16(Bt[n][k], At[m][k], acc[ai][bj][m][n], 0, 0, 0); __builtin_amdgcn_s_setprio(0); } while (0)
; #define PG8_WAIT_L(n) asm volatile("s_waitcnt lgkmcnt(" #n ")" ::: "memory")
; #define PG8_BAR __builtin_amdgcn_s_barrier()
; #define PG8_SCHED __builtin_amdgcn_sched_barrier(0)
; template <class Epi, class Ord>
; __device__ __forceinline__ void gemm_phase(LAS unsigned char* lds, const Gemm g, const Ord& S, const Epi& E) {
;     ...
;             const bool last = (t == nt - 2);
;             const char* a1 = cA + (size_t)(t + 1) * kstep;
;             const char* a2 = last ? nA : cA + (size_t)(t + 2) * kstep; const char* b2 = last ? nB : cB + (size_t)(t + 2) * kstep;
;             const char* a3 = a2 + kstep; const char* b3 = b2 + kstep;
;             PG8_LDB(B0, 0, 0); PG8_SCHED; PG8_LDA(At, 0, 0); PG8_STAGE(PG8_SA(1, 1), a1 + hstep, voffA);
;             PG8_WAIT_L(8); PG8_BAR; PG8_WAIT_L(0); PG8_MMA(0, 0, At, B0); PG8_BAR; PG8_SCHED;
;             PG8_LDB(B1, 0, 1); PG8_STAGE(PG8_SB(0, 0), b2, voffB);
;             PG8_BAR; PG8_WAIT_L(0); PG8_MMA(0, 1, At, B1); PG8_BAR;
;             PG8_LDA(At, 0, 1); PG8_STAGE(PG8_SA(0, 0), a2, voffA);
;             PG8_BAR; PG8_WAIT_L(0); PG8_MMA(1, 0, At, B0); PG8_BAR; PG8_SCHED;
.LBB0_269:
	s_add_i32 s95, s12, 2
	s_cmp_eq_u32 s81, s12
	s_cselect_b32 s22, s44, s56
	s_cselect_b32 s23, s45, s57
	s_cselect_b32 s20, s46, s52
	s_cselect_b32 s21, s47, s53
	s_add_u32 s12, s22, 0x80
	s_addc_u32 s13, s23, 0
	s_add_i32 s82, 0, 0x10000
	v_add_u32_e32 v140, s82, v204
	ds_read_b128 v[128:131], v140
	ds_read_b128 v[132:135], v140 offset:1024
	ds_read_b128 v[136:139], v140 offset:2048
	ds_read_b128 v[140:143], v140 offset:3072
	s_add_u32 s24, s56, s0
	s_addc_u32 s25, s57, s1
	s_add_u32 s24, s24, 0xffffff80
	s_addc_u32 s25, s25, -1
	v_mov_b32_e32 v168, v157
	ds_read_b128 v[144:147], v206
	ds_read_b128 v[148:151], v206 offset:1024
	ds_read_b128 v[152:155], v206 offset:2048
	ds_read_b128 v[192:195], v206 offset:3072
	ds_read_b128 v[196:199], v206 offset:4096
	ds_read_b128 v[212:215], v206 offset:5120
	ds_read_b128 v[216:219], v206 offset:6144
	ds_read_b128 v[220:223], v206 offset:7168
	s_add_i32 m0, s70, 0xc000
	s_nop 0
	global_load_lds_dwordx4 v168, s[24:25]
	v_mov_b32_e32 v168, v201
	s_add_i32 m0, s70, 0xe000
	s_nop 0
	global_load_lds_dwordx4 v168, s[24:25]
	s_waitcnt lgkmcnt(8)
	s_barrier
	s_waitcnt lgkmcnt(0)
	s_waitcnt lgkmcnt(0)
	v_mfma_f32_16x16x32_bf16 v[124:127], v[128:131], v[144:147], v[124:127]
	v_mfma_f32_16x16x32_bf16 v[120:123], v[136:139], v[144:147], v[120:123]
	v_mfma_f32_16x16x32_bf16 v[108:111], v[128:131], v[152:155], v[108:111]
	v_mfma_f32_16x16x32_bf16 v[104:107], v[136:139], v[152:155], v[104:107]
	v_mfma_f32_16x16x32_bf16 v[92:95], v[128:131], v[196:199], v[92:95]
	v_mfma_f32_16x16x32_bf16 v[88:91], v[136:139], v[196:199], v[88:91]
	v_mfma_f32_16x16x32_bf16 v[76:79], v[128:131], v[216:219], v[76:79]
	v_mfma_f32_16x16x32_bf16 v[72:75], v[136:139], v[216:219], v[72:75]
	v_mfma_f32_16x16x32_bf16 v[124:127], v[132:135], v[148:151], v[124:127]
	v_mfma_f32_16x16x32_bf16 v[120:123], v[140:143], v[148:151], v[120:123]
	v_mfma_f32_16x16x32_bf16 v[108:111], v[132:135], v[192:195], v[108:111]
	v_mfma_f32_16x16x32_bf16 v[104:107], v[140:143], v[192:195], v[104:107]
	v_mfma_f32_16x16x32_bf16 v[92:95], v[132:135], v[212:215], v[92:95]
	v_mfma_f32_16x16x32_bf16 v[88:91], v[140:143], v[212:215], v[88:91]
	v_mfma_f32_16x16x32_bf16 v[76:79], v[132:135], v[220:223], v[76:79]
	v_mfma_f32_16x16x32_bf16 v[72:75], v[140:143], v[220:223], v[72:75]
	s_barrier
	s_add_i32 s84, 0, 0x14000
	v_add_u32_e32 v168, s84, v204
	ds_read_b128 v[224:227], v168
	ds_read_b128 v[228:231], v168 offset:1024
	ds_read_b128 v[232:235], v168 offset:2048
	ds_read_b128 v[236:239], v168 offset:3072
	s_mov_b64 s[24:25], s[20:21]
	v_mov_b32_e32 v168, v200
	s_add_i32 s82, s82, s69
	s_mov_b32 m0, s82
	s_nop 0
	global_load_lds_dwordx4 v168, s[24:25]
	v_mov_b32_e32 v168, v202
	s_add_i32 m0, s82, 0x2000
	s_nop 0
	global_load_lds_dwordx4 v168, s[24:25]
	s_barrier
	s_waitcnt lgkmcnt(0)
	s_waitcnt lgkmcnt(0)
	v_mfma_f32_16x16x32_bf16 v[116:119], v[224:227], v[144:147], v[116:119]
	v_mfma_f32_16x16x32_bf16 v[112:115], v[232:235], v[144:147], v[112:115]
	v_mfma_f32_16x16x32_bf16 v[100:103], v[224:227], v[152:155], v[100:103]
	v_mfma_f32_16x16x32_bf16 v[96:99], v[232:235], v[152:155], v[96:99]
	v_mfma_f32_16x16x32_bf16 v[84:87], v[224:227], v[196:199], v[84:87]
	v_mfma_f32_16x16x32_bf16 v[80:83], v[232:235], v[196:199], v[80:83]
	v_mfma_f32_16x16x32_bf16 v[68:71], v[224:227], v[216:219], v[68:71]
	v_mfma_f32_16x16x32_bf16 v[64:67], v[232:235], v[216:219], v[64:67]
	v_mfma_f32_16x16x32_bf16 v[116:119], v[228:231], v[148:151], v[116:119]
	v_mfma_f32_16x16x32_bf16 v[112:115], v[236:239], v[148:151], v[112:115]
	v_mfma_f32_16x16x32_bf16 v[100:103], v[228:231], v[192:195], v[100:103]
	v_mfma_f32_16x16x32_bf16 v[96:99], v[236:239], v[192:195], v[96:99]
	v_mfma_f32_16x16x32_bf16 v[84:87], v[228:231], v[212:215], v[84:87]
	v_mfma_f32_16x16x32_bf16 v[80:83], v[236:239], v[212:215], v[80:83]
	v_mfma_f32_16x16x32_bf16 v[68:71], v[228:231], v[220:223], v[68:71]
	v_mfma_f32_16x16x32_bf16 v[64:67], v[236:239], v[220:223], v[64:67]
	s_mov_b64 s[24:25], s[22:23]
	v_mov_b32_e32 v168, v157
	s_mov_b32 m0, s70
	s_barrier
	ds_read_b128 v[144:147], v206 offset:16384
	ds_read_b128 v[148:151], v206 offset:17408
	ds_read_b128 v[152:155], v206 offset:18432
	ds_read_b128 v[192:195], v206 offset:19456
	ds_read_b128 v[196:199], v206 offset:20480
	ds_read_b128 v[212:215], v206 offset:21504
	ds_read_b128 v[216:219], v206 offset:22528
	ds_read_b128 v[220:223], v206 offset:23552
	s_nop 0
	global_load_lds_dwordx4 v168, s[24:25]
	v_mov_b32_e32 v168, v201
	s_mov_b32 m0, s71
	s_nop 0
	global_load_lds_dwordx4 v168, s[24:25]
	s_barrier
	s_waitcnt lgkmcnt(0)
	s_waitcnt lgkmcnt(0)
	v_mfma_f32_16x16x32_bf16 v[60:63], v[128:131], v[144:147], v[60:63]
	v_mfma_f32_16x16x32_bf16 v[56:59], v[136:139], v[144:147], v[56:59]
	v_mfma_f32_16x16x32_bf16 v[44:47], v[128:131], v[152:155], v[44:47]
	v_mfma_f32_16x16x32_bf16 v[40:43], v[136:139], v[152:155], v[40:43]
	v_mfma_f32_16x16x32_bf16 v[28:31], v[128:131], v[196:199], v[28:31]
	v_mfma_f32_16x16x32_bf16 v[24:27], v[136:139], v[196:199], v[24:27]
	v_mfma_f32_16x16x32_bf16 v[12:15], v[128:131], v[216:219], v[12:15]
	v_mfma_f32_16x16x32_bf16 v[8:11], v[136:139], v[216:219], v[8:11]
	v_mfma_f32_16x16x32_bf16 v[60:63], v[132:135], v[148:151], v[60:63]
	v_mfma_f32_16x16x32_bf16 v[56:59], v[140:143], v[148:151], v[56:59]
	v_mfma_f32_16x16x32_bf16 v[44:47], v[132:135], v[192:195], v[44:47]
	v_mfma_f32_16x16x32_bf16 v[40:43], v[140:143], v[192:195], v[40:43]
	v_mfma_f32_16x16x32_bf16 v[28:31], v[132:135], v[212:215], v[28:31]
	v_mfma_f32_16x16x32_bf16 v[24:27], v[140:143], v[212:215], v[24:27]
	v_mfma_f32_16x16x32_bf16 v[12:15], v[132:135], v[220:223], v[12:15]
	v_mfma_f32_16x16x32_bf16 v[8:11], v[140:143], v[220:223], v[8:11]
	s_barrier
; #define PG8_STAGE(bufoff, gbase, voff) do { const char* _gb = (const char*)(gbase); asm volatile("" : "+s"(_gb)); _Pragma("unroll") for (int _i = 0; _i < 2; ++_i) { unsigned _vo = (voff)[_i]; asm volatile("" : "+v"(_vo)); \
;         __builtin_amdgcn_global_load_lds((const GAS unsigned*)(_gb + _vo), (LAS unsigned*)(lds + (bufoff) + ldsw + _i * 8192), 16, 0, 0); } } while (0)
; #define PG8_LDA(dst, b, h) do { _Pragma("unroll") for (int m = 0; m < 4; ++m) _Pragma("unroll") for (int k = 0; k < 2; ++k) dst[m][k] = *(const LAS bf16x8*)(lds + PG8_SA(b, h) + aoff + m * 2048 + k * 1024); } while (0)
; #define PG8_LDB(dst, b, h) do { _Pragma("unroll") for (int n = 0; n < 2; ++n) _Pragma("unroll") for (int k = 0; k < 2; ++k) dst[n][k] = *(const LAS bf16x8*)(lds + PG8_SB(b, h) + boff + n * 2048 + k * 1024); } while (0)
; #define PG8_MMA(ai, bj, At, Bt) do { __builtin_amdgcn_s_setprio(1); _Pragma("unroll") for (int m = 0; m < 4; ++m) _Pragma("unroll") for (int n = 0; n < 2; ++n) _Pragma("unroll") for (int k = 0; k < 2; ++k) \
;         acc[ai][bj][m][n] = __builtin_amdgcn_mfma_f32_16x16x32_bf16(Bt[n][k], At[m][k], acc[ai][bj][m][n], 0, 0, 0); __builtin_amdgcn_s_setprio(0); } while (0)
; #define PG8_WAIT_V(n) asm volatile("s_waitcnt vmcnt(" #n ")" ::: "memory")
; #define PG8_WAIT_L(n) asm volatile("s_waitcnt lgkmcnt(" #n ")" ::: "memory")
; #define PG8_BAR __builtin_amdgcn_s_barrier()
; #define PG8_SCHED __builtin_amdgcn_sched_barrier(0)
; template <class Epi, class Ord>
; __device__ __forceinline__ void gemm_phase(LAS unsigned char* lds, const Gemm g, const Ord& S, const Epi& E) {
;     ...
;             PG8_STAGE(PG8_SB(0, 1), b2 + hstep, voffB);
;             PG8_WAIT_V(6); PG8_BAR; PG8_MMA(1, 1, At, B1); PG8_BAR;
;             PG8_LDB(B0, 1, 0); PG8_SCHED; PG8_LDA(At, 1, 0); PG8_STAGE(PG8_SA(0, 1), a2 + hstep, voffA);
;             PG8_WAIT_L(8); PG8_BAR; PG8_WAIT_L(0); PG8_MMA(0, 0, At, B0); PG8_BAR; PG8_SCHED;
;             PG8_LDB(B1, 1, 1); PG8_STAGE(PG8_SB(1, 0), b3, voffB);
;             PG8_BAR; PG8_WAIT_L(0); PG8_MMA(0, 1, At, B1); PG8_BAR;
	s_add_u32 s24, s20, s0
	s_addc_u32 s25, s21, s1
	s_mov_b64 s[82:83], s[24:25]
	v_mov_b32_e32 v128, v200
	s_add_i32 s84, s84, s69
	s_mov_b32 m0, s84
	s_nop 0
	global_load_lds_dwordx4 v128, s[82:83]
	v_mov_b32_e32 v128, v202
	s_add_i32 m0, s84, 0x2000
	s_nop 0
	global_load_lds_dwordx4 v128, s[82:83]
	s_waitcnt vmcnt(6)
	s_barrier
	v_mfma_f32_16x16x32_bf16 v[52:55], v[224:227], v[144:147], v[52:55]
	v_mfma_f32_16x16x32_bf16 v[48:51], v[232:235], v[144:147], v[48:51]
	v_mfma_f32_16x16x32_bf16 v[36:39], v[224:227], v[152:155], v[36:39]
	v_mfma_f32_16x16x32_bf16 v[32:35], v[232:235], v[152:155], v[32:35]
	v_mfma_f32_16x16x32_bf16 v[20:23], v[224:227], v[196:199], v[20:23]
	v_mfma_f32_16x16x32_bf16 v[16:19], v[232:235], v[196:199], v[16:19]
	v_mfma_f32_16x16x32_bf16 v[4:7], v[224:227], v[216:219], v[4:7]
	v_mfma_f32_16x16x32_bf16 v[0:3], v[232:235], v[216:219], v[0:3]
	v_mfma_f32_16x16x32_bf16 v[52:55], v[228:231], v[148:151], v[52:55]
	v_mfma_f32_16x16x32_bf16 v[48:51], v[236:239], v[148:151], v[48:51]
	v_mfma_f32_16x16x32_bf16 v[36:39], v[228:231], v[192:195], v[36:39]
	v_mfma_f32_16x16x32_bf16 v[32:35], v[236:239], v[192:195], v[32:35]
	v_mfma_f32_16x16x32_bf16 v[20:23], v[228:231], v[212:215], v[20:23]
	v_mfma_f32_16x16x32_bf16 v[16:19], v[236:239], v[212:215], v[16:19]
	v_mfma_f32_16x16x32_bf16 v[4:7], v[228:231], v[220:223], v[4:7]
	v_mfma_f32_16x16x32_bf16 v[0:3], v[236:239], v[220:223], v[0:3]
	s_add_i32 s82, 0, 0x18000
	v_add_u32_e32 v140, s82, v204
	s_barrier
	ds_read_b128 v[128:131], v140
	ds_read_b128 v[132:135], v140 offset:1024
	ds_read_b128 v[136:139], v140 offset:2048
	ds_read_b128 v[140:143], v140 offset:3072
	s_add_u32 s22, s22, s0
	s_addc_u32 s23, s23, s1
	v_mov_b32_e32 v168, v157
	s_mov_b32 m0, s72
	ds_read_b128 v[144:147], v206 offset:32768
	ds_read_b128 v[148:151], v206 offset:33792
	ds_read_b128 v[152:155], v206 offset:34816
	ds_read_b128 v[192:195], v206 offset:35840
	ds_read_b128 v[196:199], v206 offset:36864
	ds_read_b128 v[212:215], v206 offset:37888
	ds_read_b128 v[216:219], v206 offset:38912
	ds_read_b128 v[220:223], v206 offset:39936
	s_nop 0
	global_load_lds_dwordx4 v168, s[22:23]
	v_mov_b32_e32 v168, v201
	s_mov_b32 m0, s73
	s_nop 0
	global_load_lds_dwordx4 v168, s[22:23]
	s_waitcnt lgkmcnt(8)
	s_barrier
	s_waitcnt lgkmcnt(0)
	s_waitcnt lgkmcnt(0)
	v_mfma_f32_16x16x32_bf16 v[124:127], v[128:131], v[144:147], v[124:127]
	v_mfma_f32_16x16x32_bf16 v[120:123], v[136:139], v[144:147], v[120:123]
	v_mfma_f32_16x16x32_bf16 v[108:111], v[128:131], v[152:155], v[108:111]
	v_mfma_f32_16x16x32_bf16 v[104:107], v[136:139], v[152:155], v[104:107]
	v_mfma_f32_16x16x32_bf16 v[92:95], v[128:131], v[196:199], v[92:95]
	v_mfma_f32_16x16x32_bf16 v[88:91], v[136:139], v[196:199], v[88:91]
	v_mfma_f32_16x16x32_bf16 v[76:79], v[128:131], v[216:219], v[76:79]
	v_mfma_f32_16x16x32_bf16 v[72:75], v[136:139], v[216:219], v[72:75]
	v_mfma_f32_16x16x32_bf16 v[124:127], v[132:135], v[148:151], v[124:127]
	v_mfma_f32_16x16x32_bf16 v[120:123], v[140:143], v[148:151], v[120:123]
	v_mfma_f32_16x16x32_bf16 v[108:111], v[132:135], v[192:195], v[108:111]
	v_mfma_f32_16x16x32_bf16 v[104:107], v[140:143], v[192:195], v[104:107]
	v_mfma_f32_16x16x32_bf16 v[92:95], v[132:135], v[212:215], v[92:95]
	v_mfma_f32_16x16x32_bf16 v[88:91], v[140:143], v[212:215], v[88:91]
	v_mfma_f32_16x16x32_bf16 v[76:79], v[132:135], v[220:223], v[76:79]
	v_mfma_f32_16x16x32_bf16 v[72:75], v[140:143], v[220:223], v[72:75]
	s_barrier
	s_add_i32 s22, 0, 0x1c000
	v_add_u32_e32 v168, s22, v204
	s_add_u32 s20, s20, 0x80
	ds_read_b128 v[224:227], v168
	ds_read_b128 v[228:231], v168 offset:1024
	ds_read_b128 v[232:235], v168 offset:2048
	ds_read_b128 v[236:239], v168 offset:3072
	s_addc_u32 s21, s21, 0
	v_mov_b32_e32 v168, v200
	s_add_i32 s23, s82, s69
	s_mov_b32 m0, s23
	s_nop 0
	global_load_lds_dwordx4 v168, s[20:21]
	v_mov_b32_e32 v168, v202
	s_add_i32 m0, s23, 0x2000
	s_nop 0
	global_load_lds_dwordx4 v168, s[20:21]
	s_barrier
; #define PG8_STAGE(bufoff, gbase, voff) do { const char* _gb = (const char*)(gbase); asm volatile("" : "+s"(_gb)); _Pragma("unroll") for (int _i = 0; _i < 2; ++_i) { unsigned _vo = (voff)[_i]; asm volatile("" : "+v"(_vo)); \
;         __builtin_amdgcn_global_load_lds((const GAS unsigned*)(_gb + _vo), (LAS unsigned*)(lds + (bufoff) + ldsw + _i * 8192), 16, 0, 0); } } while (0)
; #define PG8_LDA(dst, b, h) do { _Pragma("unroll") for (int m = 0; m < 4; ++m) _Pragma("unroll") for (int k = 0; k < 2; ++k) dst[m][k] = *(const LAS bf16x8*)(lds + PG8_SA(b, h) + aoff + m * 2048 + k * 1024); } while (0)
; #define PG8_MMA(ai, bj, At, Bt) do { __builtin_amdgcn_s_setprio(1); _Pragma("unroll") for (int m = 0; m < 4; ++m) _Pragma("unroll") for (int n = 0; n < 2; ++n) _Pragma("unroll") for (int k = 0; k < 2; ++k) \
;         acc[ai][bj][m][n] = __builtin_amdgcn_mfma_f32_16x16x32_bf16(Bt[n][k], At[m][k], acc[ai][bj][m][n], 0, 0, 0); __builtin_amdgcn_s_setprio(0); } while (0)
; #define PG8_WAIT_V(n) asm volatile("s_waitcnt vmcnt(" #n ")" ::: "memory")
; #define PG8_WAIT_L(n) asm volatile("s_waitcnt lgkmcnt(" #n ")" ::: "memory")
; #define PG8_BAR __builtin_amdgcn_s_barrier()
; #define PG8_SCHED __builtin_amdgcn_sched_barrier(0)
; template <class Epi, class Ord>
; __device__ __forceinline__ void gemm_phase(LAS unsigned char* lds, const Gemm g, const Ord& S, const Epi& E) {
;     ...
;             PG8_BAR; PG8_WAIT_L(0); PG8_MMA(0, 1, At, B1); PG8_BAR;
;             PG8_LDA(At, 1, 1); PG8_STAGE(PG8_SA(1, 0), a3, voffA);
;             PG8_BAR; PG8_WAIT_L(0); PG8_MMA(1, 0, At, B0); PG8_BAR; PG8_SCHED;
;             PG8_STAGE(PG8_SB(1, 1), b3 + hstep, voffB);
;             PG8_WAIT_V(6); PG8_BAR; PG8_MMA(1, 1, At, B1); PG8_BAR;
;         }
	s_waitcnt lgkmcnt(0)
	s_waitcnt lgkmcnt(0)
	v_mfma_f32_16x16x32_bf16 v[116:119], v[224:227], v[144:147], v[116:119]
	v_mfma_f32_16x16x32_bf16 v[112:115], v[232:235], v[144:147], v[112:115]
	v_mfma_f32_16x16x32_bf16 v[100:103], v[224:227], v[152:155], v[100:103]
	v_mfma_f32_16x16x32_bf16 v[96:99], v[232:235], v[152:155], v[96:99]
	v_mfma_f32_16x16x32_bf16 v[84:87], v[224:227], v[196:199], v[84:87]
	v_mfma_f32_16x16x32_bf16 v[80:83], v[232:235], v[196:199], v[80:83]
	v_mfma_f32_16x16x32_bf16 v[68:71], v[224:227], v[216:219], v[68:71]
	v_mfma_f32_16x16x32_bf16 v[64:67], v[232:235], v[216:219], v[64:67]
	v_mfma_f32_16x16x32_bf16 v[116:119], v[228:231], v[148:151], v[116:119]
	v_mfma_f32_16x16x32_bf16 v[112:115], v[236:239], v[148:151], v[112:115]
	v_mfma_f32_16x16x32_bf16 v[100:103], v[228:231], v[192:195], v[100:103]
	v_mfma_f32_16x16x32_bf16 v[96:99], v[236:239], v[192:195], v[96:99]
	v_mfma_f32_16x16x32_bf16 v[84:87], v[228:231], v[212:215], v[84:87]
	v_mfma_f32_16x16x32_bf16 v[80:83], v[236:239], v[212:215], v[80:83]
	v_mfma_f32_16x16x32_bf16 v[68:71], v[228:231], v[220:223], v[68:71]
	v_mfma_f32_16x16x32_bf16 v[64:67], v[236:239], v[220:223], v[64:67]
	v_mov_b32_e32 v168, v157
	s_mov_b32 m0, s79
	s_barrier
	ds_read_b128 v[144:147], v206 offset:49152
	ds_read_b128 v[148:151], v206 offset:50176
	ds_read_b128 v[152:155], v206 offset:51200
	ds_read_b128 v[192:195], v206 offset:52224
	ds_read_b128 v[196:199], v206 offset:53248
	ds_read_b128 v[212:215], v206 offset:54272
	ds_read_b128 v[216:219], v206 offset:55296
	ds_read_b128 v[220:223], v206 offset:56320
	s_nop 0
	global_load_lds_dwordx4 v168, s[12:13]
	v_mov_b32_e32 v168, v201
	s_mov_b32 m0, s80
	s_nop 0
	global_load_lds_dwordx4 v168, s[12:13]
	s_barrier
	s_waitcnt lgkmcnt(0)
	s_waitcnt lgkmcnt(0)
	v_mfma_f32_16x16x32_bf16 v[60:63], v[128:131], v[144:147], v[60:63]
	v_mfma_f32_16x16x32_bf16 v[56:59], v[136:139], v[144:147], v[56:59]
	v_mfma_f32_16x16x32_bf16 v[44:47], v[128:131], v[152:155], v[44:47]
	v_mfma_f32_16x16x32_bf16 v[40:43], v[136:139], v[152:155], v[40:43]
	v_mfma_f32_16x16x32_bf16 v[28:31], v[128:131], v[196:199], v[28:31]
	v_mfma_f32_16x16x32_bf16 v[24:27], v[136:139], v[196:199], v[24:27]
	v_mfma_f32_16x16x32_bf16 v[12:15], v[128:131], v[216:219], v[12:15]
	v_mfma_f32_16x16x32_bf16 v[8:11], v[136:139], v[216:219], v[8:11]
	v_mfma_f32_16x16x32_bf16 v[60:63], v[132:135], v[148:151], v[60:63]
	v_mfma_f32_16x16x32_bf16 v[56:59], v[140:143], v[148:151], v[56:59]
	v_mfma_f32_16x16x32_bf16 v[44:47], v[132:135], v[192:195], v[44:47]
	v_mfma_f32_16x16x32_bf16 v[40:43], v[140:143], v[192:195], v[40:43]
	v_mfma_f32_16x16x32_bf16 v[28:31], v[132:135], v[212:215], v[28:31]
	v_mfma_f32_16x16x32_bf16 v[24:27], v[140:143], v[212:215], v[24:27]
	v_mfma_f32_16x16x32_bf16 v[12:15], v[132:135], v[220:223], v[12:15]
	v_mfma_f32_16x16x32_bf16 v[8:11], v[140:143], v[220:223], v[8:11]
	s_barrier
	s_add_u32 s12, s24, 0x80
	s_addc_u32 s13, s25, 0
	v_mov_b32_e32 v128, v200
	s_add_i32 s20, s22, s69
	s_mov_b32 m0, s20
	s_nop 0
	global_load_lds_dwordx4 v128, s[12:13]
	v_mov_b32_e32 v128, v202
	s_add_i32 m0, s20, 0x2000
	s_nop 0
	global_load_lds_dwordx4 v128, s[12:13]
	s_waitcnt vmcnt(6)
	s_barrier
	v_mfma_f32_16x16x32_bf16 v[52:55], v[224:227], v[144:147], v[52:55]
	v_mfma_f32_16x16x32_bf16 v[48:51], v[232:235], v[144:147], v[48:51]
	v_mfma_f32_16x16x32_bf16 v[36:39], v[224:227], v[152:155], v[36:39]
	v_mfma_f32_16x16x32_bf16 v[32:35], v[232:235], v[152:155], v[32:35]
	v_mfma_f32_16x16x32_bf16 v[20:23], v[224:227], v[196:199], v[20:23]
	v_mfma_f32_16x16x32_bf16 v[16:19], v[232:235], v[196:199], v[16:19]
	v_mfma_f32_16x16x32_bf16 v[4:7], v[224:227], v[216:219], v[4:7]
	v_mfma_f32_16x16x32_bf16 v[0:3], v[232:235], v[216:219], v[0:3]
	v_mfma_f32_16x16x32_bf16 v[52:55], v[228:231], v[148:151], v[52:55]
	v_mfma_f32_16x16x32_bf16 v[48:51], v[236:239], v[148:151], v[48:51]
	v_mfma_f32_16x16x32_bf16 v[36:39], v[228:231], v[192:195], v[36:39]
	v_mfma_f32_16x16x32_bf16 v[32:35], v[236:239], v[192:195], v[32:35]
	v_mfma_f32_16x16x32_bf16 v[20:23], v[228:231], v[212:215], v[20:23]
	v_mfma_f32_16x16x32_bf16 v[16:19], v[236:239], v[212:215], v[16:19]
	v_mfma_f32_16x16x32_bf16 v[4:7], v[228:231], v[220:223], v[4:7]
	v_mfma_f32_16x16x32_bf16 v[0:3], v[236:239], v[220:223], v[0:3]
	s_add_u32 s52, s52, 0x100
	s_addc_u32 s53, s53, 0
	s_add_u32 s56, s56, 0x100
	s_addc_u32 s57, s57, 0
	s_cmp_ge_i32 s95, s77
	s_mov_b32 s12, s95
	s_barrier
	s_cbranch_scc0 .LBB0_269

; #define PG8_STAGE(bufoff, gbase, voff) do { const char* _gb = (const char*)(gbase); asm volatile("" : "+s"(_gb)); _Pragma("unroll") for (int _i = 0; _i < 2; ++_i) { unsigned _vo = (voff)[_i]; asm volatile("" : "+v"(_vo)); \
;         __builtin_amdgcn_global_load_lds((const GAS unsigned*)(_gb + _vo), (LAS unsigned*)(lds + (bufoff) + ldsw + _i * 8192), 16, 0, 0); } } while (0)
; #define PG8_LDA(dst, b, h) do { _Pragma("unroll") for (int m = 0; m < 4; ++m) _Pragma("unroll") for (int k = 0; k < 2; ++k) dst[m][k] = *(const LAS bf16x8*)(lds + PG8_SA(b, h) + aoff + m * 2048 + k * 1024); } while (0)
; #define PG8_LDB(dst, b, h) do { _Pragma("unroll") for (int n = 0; n < 2; ++n) _Pragma("unroll") for (int k = 0; k < 2; ++k) dst[n][k] = *(const LAS bf16x8*)(lds + PG8_SB(b, h) + boff + n * 2048 + k * 1024); } while (0)
; #define PG8_MMA(ai, bj, At, Bt) do { __builtin_amdgcn_s_setprio(1); _Pragma("unroll") for (int m = 0; m < 4; ++m) _Pragma("unroll") for (int n = 0; n < 2; ++n) _Pragma("unroll") for (int k = 0; k < 2; ++k) \
;         acc[ai][bj][m][n] = __builtin_amdgcn_mfma_f32_16x16x32_bf16(Bt[n][k], At[m][k], acc[ai][bj][m][n], 0, 0, 0); __builtin_amdgcn_s_setprio(0); } while (0)
; #define PG8_WAIT_L(n) asm volatile("s_waitcnt lgkmcnt(" #n ")" ::: "memory")
; #define PG8_BAR __builtin_amdgcn_s_barrier()
; #define PG8_SCHED __builtin_amdgcn_sched_barrier(0)
; template <class Epi, class Ord>
; __device__ __forceinline__ void gemm_phase(LAS unsigned char* lds, const Gemm g, const Ord& S, const Epi& E) {
;     ...
;             const bool last = (t == nt - 2);
;             const char* a1 = cA + (size_t)(t + 1) * kstep;
;             const char* a2 = last ? nA : cA + (size_t)(t + 2) * kstep; const char* b2 = last ? nB : cB + (size_t)(t + 2) * kstep;
;             const char* a3 = a2 + kstep; const char* b3 = b2 + kstep;
;             PG8_LDB(B0, 0, 0); PG8_SCHED; PG8_LDA(At, 0, 0); PG8_STAGE(PG8_SA(1, 1), a1 + hstep, voffA);
;             PG8_WAIT_L(8); PG8_BAR; PG8_WAIT_L(0); PG8_MMA(0, 0, At, B0); PG8_BAR; PG8_SCHED;
;             PG8_LDB(B1, 0, 1); PG8_STAGE(PG8_SB(0, 0), b2, voffB);
;             PG8_BAR; PG8_WAIT_L(0); PG8_MMA(0, 1, At, B1); PG8_BAR;
;             PG8_LDA(At, 0, 1); PG8_STAGE(PG8_SA(0, 0), a2, voffA);
;             PG8_BAR; PG8_WAIT_L(0); PG8_MMA(1, 0, At, B0); PG8_BAR; PG8_SCHED;
.LBB0_312:
	s_add_i32 s80, s12, 2
	s_cmp_eq_u32 s71, s12
	s_cselect_b32 s20, s0, s46
	s_cselect_b32 s21, s1, s47
	s_cselect_b32 s16, s44, s78
	s_cselect_b32 s17, s45, s79
	s_add_u32 s12, s20, 0x80
	s_addc_u32 s13, s21, 0
	s_add_i32 s81, 0, 0x10000
	v_add_u32_e32 v136, s81, v216
	ds_read_b128 v[116:119], v136
	ds_read_b128 v[124:127], v136 offset:1024
	ds_read_b128 v[128:131], v136 offset:2048
	ds_read_b128 v[136:139], v136 offset:3072
	s_add_u32 s22, s46, s10
	s_addc_u32 s23, s47, s11
	s_add_u32 s22, s22, 0xffffff80
	s_addc_u32 s23, s23, -1
	v_mov_b32_e32 v206, v211
	ds_read_b128 v[144:147], v168
	ds_read_b128 v[148:151], v168 offset:1024
	ds_read_b128 v[152:155], v168 offset:2048
	ds_read_b128 v[156:159], v168 offset:3072
	ds_read_b128 v[194:197], v168 offset:4096
	ds_read_b128 v[198:201], v168 offset:5120
	ds_read_b128 v[202:205], v168 offset:6144
	ds_read_b128 v[218:221], v168 offset:7168
	s_add_i32 m0, s57, 0xc000
	s_nop 0
	global_load_lds_dwordx4 v206, s[22:23]
	v_mov_b32_e32 v206, v213
	s_add_i32 m0, s57, 0xe000
	s_nop 0
	global_load_lds_dwordx4 v206, s[22:23]
	s_waitcnt lgkmcnt(8)
	s_barrier
	s_waitcnt lgkmcnt(0)
	s_waitcnt lgkmcnt(0)
	v_mfma_f32_16x16x32_bf16 v[140:143], v[116:119], v[144:147], v[140:143]
	v_mfma_f32_16x16x32_bf16 v[132:135], v[128:131], v[144:147], v[132:135]
	v_mfma_f32_16x16x32_bf16 v[108:111], v[116:119], v[152:155], v[108:111]
	v_mfma_f32_16x16x32_bf16 v[104:107], v[128:131], v[152:155], v[104:107]
	v_mfma_f32_16x16x32_bf16 v[92:95], v[116:119], v[194:197], v[92:95]
	v_mfma_f32_16x16x32_bf16 v[88:91], v[128:131], v[194:197], v[88:91]
	v_mfma_f32_16x16x32_bf16 v[76:79], v[116:119], v[202:205], v[76:79]
	v_mfma_f32_16x16x32_bf16 v[72:75], v[128:131], v[202:205], v[72:75]
	v_mfma_f32_16x16x32_bf16 v[140:143], v[124:127], v[148:151], v[140:143]
	v_mfma_f32_16x16x32_bf16 v[132:135], v[136:139], v[148:151], v[132:135]
	v_mfma_f32_16x16x32_bf16 v[108:111], v[124:127], v[156:159], v[108:111]
	v_mfma_f32_16x16x32_bf16 v[104:107], v[136:139], v[156:159], v[104:107]
	v_mfma_f32_16x16x32_bf16 v[92:95], v[124:127], v[198:201], v[92:95]
	v_mfma_f32_16x16x32_bf16 v[88:91], v[136:139], v[198:201], v[88:91]
	v_mfma_f32_16x16x32_bf16 v[76:79], v[124:127], v[218:221], v[76:79]
	v_mfma_f32_16x16x32_bf16 v[72:75], v[136:139], v[218:221], v[72:75]
	s_barrier
	s_add_i32 s84, 0, 0x14000
	v_add_u32_e32 v206, s84, v216
	ds_read_b128 v[222:225], v206
	ds_read_b128 v[226:229], v206 offset:1024
	ds_read_b128 v[230:233], v206 offset:2048
	ds_read_b128 v[234:237], v206 offset:3072
	s_mov_b64 s[22:23], s[16:17]
	v_mov_b32_e32 v206, v212
	s_add_i32 s81, s81, s56
	s_mov_b32 m0, s81
	s_nop 0
	global_load_lds_dwordx4 v206, s[22:23]
	v_mov_b32_e32 v206, v214
	s_add_i32 m0, s81, 0x2000
	s_nop 0
	global_load_lds_dwordx4 v206, s[22:23]
	s_barrier
	s_waitcnt lgkmcnt(0)
	s_waitcnt lgkmcnt(0)
	v_mfma_f32_16x16x32_bf16 v[120:123], v[222:225], v[144:147], v[120:123]
	v_mfma_f32_16x16x32_bf16 v[112:115], v[230:233], v[144:147], v[112:115]
	v_mfma_f32_16x16x32_bf16 v[100:103], v[222:225], v[152:155], v[100:103]
	v_mfma_f32_16x16x32_bf16 v[96:99], v[230:233], v[152:155], v[96:99]
	v_mfma_f32_16x16x32_bf16 v[84:87], v[222:225], v[194:197], v[84:87]
	v_mfma_f32_16x16x32_bf16 v[80:83], v[230:233], v[194:197], v[80:83]
	v_mfma_f32_16x16x32_bf16 v[68:71], v[222:225], v[202:205], v[68:71]
	v_mfma_f32_16x16x32_bf16 v[64:67], v[230:233], v[202:205], v[64:67]
	v_mfma_f32_16x16x32_bf16 v[120:123], v[226:229], v[148:151], v[120:123]
	v_mfma_f32_16x16x32_bf16 v[112:115], v[234:237], v[148:151], v[112:115]
	v_mfma_f32_16x16x32_bf16 v[100:103], v[226:229], v[156:159], v[100:103]
	v_mfma_f32_16x16x32_bf16 v[96:99], v[234:237], v[156:159], v[96:99]
	v_mfma_f32_16x16x32_bf16 v[84:87], v[226:229], v[198:201], v[84:87]
	v_mfma_f32_16x16x32_bf16 v[80:83], v[234:237], v[198:201], v[80:83]
	v_mfma_f32_16x16x32_bf16 v[68:71], v[226:229], v[218:221], v[68:71]
	v_mfma_f32_16x16x32_bf16 v[64:67], v[234:237], v[218:221], v[64:67]
	s_mov_b64 s[22:23], s[20:21]
	v_mov_b32_e32 v206, v211
	s_mov_b32 m0, s57
	s_barrier
	ds_read_b128 v[144:147], v168 offset:16384
	ds_read_b128 v[148:151], v168 offset:17408
	ds_read_b128 v[152:155], v168 offset:18432
	ds_read_b128 v[156:159], v168 offset:19456
	ds_read_b128 v[194:197], v168 offset:20480
	ds_read_b128 v[198:201], v168 offset:21504
	ds_read_b128 v[202:205], v168 offset:22528
	ds_read_b128 v[218:221], v168 offset:23552
	s_nop 0
	global_load_lds_dwordx4 v206, s[22:23]
	v_mov_b32_e32 v206, v213
	s_mov_b32 m0, s62
	s_nop 0
	global_load_lds_dwordx4 v206, s[22:23]
	s_barrier
	s_waitcnt lgkmcnt(0)
	s_waitcnt lgkmcnt(0)
	v_mfma_f32_16x16x32_bf16 v[60:63], v[116:119], v[144:147], v[60:63]
	v_mfma_f32_16x16x32_bf16 v[56:59], v[128:131], v[144:147], v[56:59]
	v_mfma_f32_16x16x32_bf16 v[44:47], v[116:119], v[152:155], v[44:47]
	v_mfma_f32_16x16x32_bf16 v[40:43], v[128:131], v[152:155], v[40:43]
	v_mfma_f32_16x16x32_bf16 v[28:31], v[116:119], v[194:197], v[28:31]
	v_mfma_f32_16x16x32_bf16 v[24:27], v[128:131], v[194:197], v[24:27]
	v_mfma_f32_16x16x32_bf16 v[12:15], v[116:119], v[202:205], v[12:15]
	v_mfma_f32_16x16x32_bf16 v[8:11], v[128:131], v[202:205], v[8:11]
	v_mfma_f32_16x16x32_bf16 v[60:63], v[124:127], v[148:151], v[60:63]
	v_mfma_f32_16x16x32_bf16 v[56:59], v[136:139], v[148:151], v[56:59]
	v_mfma_f32_16x16x32_bf16 v[44:47], v[124:127], v[156:159], v[44:47]
	v_mfma_f32_16x16x32_bf16 v[40:43], v[136:139], v[156:159], v[40:43]
	v_mfma_f32_16x16x32_bf16 v[28:31], v[124:127], v[198:201], v[28:31]
	v_mfma_f32_16x16x32_bf16 v[24:27], v[136:139], v[198:201], v[24:27]
	v_mfma_f32_16x16x32_bf16 v[12:15], v[124:127], v[218:221], v[12:15]
	v_mfma_f32_16x16x32_bf16 v[8:11], v[136:139], v[218:221], v[8:11]
	s_barrier
; #define PG8_STAGE(bufoff, gbase, voff) do { const char* _gb = (const char*)(gbase); asm volatile("" : "+s"(_gb)); _Pragma("unroll") for (int _i = 0; _i < 2; ++_i) { unsigned _vo = (voff)[_i]; asm volatile("" : "+v"(_vo)); \
;         __builtin_amdgcn_global_load_lds((const GAS unsigned*)(_gb + _vo), (LAS unsigned*)(lds + (bufoff) + ldsw + _i * 8192), 16, 0, 0); } } while (0)
; #define PG8_LDA(dst, b, h) do { _Pragma("unroll") for (int m = 0; m < 4; ++m) _Pragma("unroll") for (int k = 0; k < 2; ++k) dst[m][k] = *(const LAS bf16x8*)(lds + PG8_SA(b, h) + aoff + m * 2048 + k * 1024); } while (0)
; #define PG8_LDB(dst, b, h) do { _Pragma("unroll") for (int n = 0; n < 2; ++n) _Pragma("unroll") for (int k = 0; k < 2; ++k) dst[n][k] = *(const LAS bf16x8*)(lds + PG8_SB(b, h) + boff + n * 2048 + k * 1024); } while (0)
; #define PG8_MMA(ai, bj, At, Bt) do { __builtin_amdgcn_s_setprio(1); _Pragma("unroll") for (int m = 0; m < 4; ++m) _Pragma("unroll") for (int n = 0; n < 2; ++n) _Pragma("unroll") for (int k = 0; k < 2; ++k) \
;         acc[ai][bj][m][n] = __builtin_amdgcn_mfma_f32_16x16x32_bf16(Bt[n][k], At[m][k], acc[ai][bj][m][n], 0, 0, 0); __builtin_amdgcn_s_setprio(0); } while (0)
; #define PG8_WAIT_V(n) asm volatile("s_waitcnt vmcnt(" #n ")" ::: "memory")
; #define PG8_WAIT_L(n) asm volatile("s_waitcnt lgkmcnt(" #n ")" ::: "memory")
; #define PG8_BAR __builtin_amdgcn_s_barrier()
; #define PG8_SCHED __builtin_amdgcn_sched_barrier(0)
; template <class Epi, class Ord>
; __device__ __forceinline__ void gemm_phase(LAS unsigned char* lds, const Gemm g, const Ord& S, const Epi& E) {
;     ...
;             PG8_STAGE(PG8_SB(0, 1), b2 + hstep, voffB);
;             PG8_WAIT_V(6); PG8_BAR; PG8_MMA(1, 1, At, B1); PG8_BAR;
;             PG8_LDB(B0, 1, 0); PG8_SCHED; PG8_LDA(At, 1, 0); PG8_STAGE(PG8_SA(0, 1), a2 + hstep, voffA);
;             PG8_WAIT_L(8); PG8_BAR; PG8_WAIT_L(0); PG8_MMA(0, 0, At, B0); PG8_BAR; PG8_SCHED;
;             PG8_LDB(B1, 1, 1); PG8_STAGE(PG8_SB(1, 0), b3, voffB);
;             PG8_BAR; PG8_WAIT_L(0); PG8_MMA(0, 1, At, B1); PG8_BAR;
	s_add_u32 s22, s16, s10
	s_addc_u32 s23, s17, s11
	s_mov_b64 s[82:83], s[22:23]
	v_mov_b32_e32 v116, v212
	s_add_i32 s81, s84, s56
	s_mov_b32 m0, s81
	s_nop 0
	global_load_lds_dwordx4 v116, s[82:83]
	v_mov_b32_e32 v116, v214
	s_add_i32 m0, s81, 0x2000
	s_nop 0
	global_load_lds_dwordx4 v116, s[82:83]
	s_waitcnt vmcnt(6)
	s_barrier
	v_mfma_f32_16x16x32_bf16 v[52:55], v[222:225], v[144:147], v[52:55]
	v_mfma_f32_16x16x32_bf16 v[48:51], v[230:233], v[144:147], v[48:51]
	v_mfma_f32_16x16x32_bf16 v[36:39], v[222:225], v[152:155], v[36:39]
	v_mfma_f32_16x16x32_bf16 v[32:35], v[230:233], v[152:155], v[32:35]
	v_mfma_f32_16x16x32_bf16 v[20:23], v[222:225], v[194:197], v[20:23]
	v_mfma_f32_16x16x32_bf16 v[16:19], v[230:233], v[194:197], v[16:19]
	v_mfma_f32_16x16x32_bf16 v[4:7], v[222:225], v[202:205], v[4:7]
	v_mfma_f32_16x16x32_bf16 v[0:3], v[230:233], v[202:205], v[0:3]
	v_mfma_f32_16x16x32_bf16 v[52:55], v[226:229], v[148:151], v[52:55]
	v_mfma_f32_16x16x32_bf16 v[48:51], v[234:237], v[148:151], v[48:51]
	v_mfma_f32_16x16x32_bf16 v[36:39], v[226:229], v[156:159], v[36:39]
	v_mfma_f32_16x16x32_bf16 v[32:35], v[234:237], v[156:159], v[32:35]
	v_mfma_f32_16x16x32_bf16 v[20:23], v[226:229], v[198:201], v[20:23]
	v_mfma_f32_16x16x32_bf16 v[16:19], v[234:237], v[198:201], v[16:19]
	v_mfma_f32_16x16x32_bf16 v[4:7], v[226:229], v[218:221], v[4:7]
	v_mfma_f32_16x16x32_bf16 v[0:3], v[234:237], v[218:221], v[0:3]
	s_add_i32 s81, 0, 0x18000
	v_add_u32_e32 v136, s81, v216
	s_barrier
	ds_read_b128 v[116:119], v136
	ds_read_b128 v[124:127], v136 offset:1024
	ds_read_b128 v[128:131], v136 offset:2048
	ds_read_b128 v[136:139], v136 offset:3072
	s_add_u32 s20, s20, s10
	s_addc_u32 s21, s21, s11
	v_mov_b32_e32 v206, v211
	s_mov_b32 m0, s64
	ds_read_b128 v[144:147], v168 offset:32768
	ds_read_b128 v[148:151], v168 offset:33792
	ds_read_b128 v[152:155], v168 offset:34816
	ds_read_b128 v[156:159], v168 offset:35840
	ds_read_b128 v[194:197], v168 offset:36864
	ds_read_b128 v[198:201], v168 offset:37888
	ds_read_b128 v[202:205], v168 offset:38912
	ds_read_b128 v[218:221], v168 offset:39936
	s_nop 0
	global_load_lds_dwordx4 v206, s[20:21]
	v_mov_b32_e32 v206, v213
	s_mov_b32 m0, s65
	s_nop 0
	global_load_lds_dwordx4 v206, s[20:21]
	s_waitcnt lgkmcnt(8)
	s_barrier
	s_waitcnt lgkmcnt(0)
	s_waitcnt lgkmcnt(0)
	v_mfma_f32_16x16x32_bf16 v[140:143], v[116:119], v[144:147], v[140:143]
	v_mfma_f32_16x16x32_bf16 v[132:135], v[128:131], v[144:147], v[132:135]
	v_mfma_f32_16x16x32_bf16 v[108:111], v[116:119], v[152:155], v[108:111]
	v_mfma_f32_16x16x32_bf16 v[104:107], v[128:131], v[152:155], v[104:107]
	v_mfma_f32_16x16x32_bf16 v[92:95], v[116:119], v[194:197], v[92:95]
	v_mfma_f32_16x16x32_bf16 v[88:91], v[128:131], v[194:197], v[88:91]
	v_mfma_f32_16x16x32_bf16 v[76:79], v[116:119], v[202:205], v[76:79]
	v_mfma_f32_16x16x32_bf16 v[72:75], v[128:131], v[202:205], v[72:75]
	v_mfma_f32_16x16x32_bf16 v[140:143], v[124:127], v[148:151], v[140:143]
	v_mfma_f32_16x16x32_bf16 v[132:135], v[136:139], v[148:151], v[132:135]
	v_mfma_f32_16x16x32_bf16 v[108:111], v[124:127], v[156:159], v[108:111]
	v_mfma_f32_16x16x32_bf16 v[104:107], v[136:139], v[156:159], v[104:107]
	v_mfma_f32_16x16x32_bf16 v[92:95], v[124:127], v[198:201], v[92:95]
	v_mfma_f32_16x16x32_bf16 v[88:91], v[136:139], v[198:201], v[88:91]
	v_mfma_f32_16x16x32_bf16 v[76:79], v[124:127], v[218:221], v[76:79]
	v_mfma_f32_16x16x32_bf16 v[72:75], v[136:139], v[218:221], v[72:75]
	s_barrier
	s_add_i32 s20, 0, 0x1c000
	v_add_u32_e32 v206, s20, v216
	s_add_u32 s16, s16, 0x80
	ds_read_b128 v[222:225], v206
	ds_read_b128 v[226:229], v206 offset:1024
	ds_read_b128 v[230:233], v206 offset:2048
	ds_read_b128 v[234:237], v206 offset:3072
	s_addc_u32 s17, s17, 0
	v_mov_b32_e32 v206, v212
	s_add_i32 s21, s81, s56
	s_mov_b32 m0, s21
	s_nop 0
	global_load_lds_dwordx4 v206, s[16:17]
	v_mov_b32_e32 v206, v214
	s_add_i32 m0, s21, 0x2000
	s_nop 0
	global_load_lds_dwordx4 v206, s[16:17]
	s_barrier
; #define PG8_STAGE(bufoff, gbase, voff) do { const char* _gb = (const char*)(gbase); asm volatile("" : "+s"(_gb)); _Pragma("unroll") for (int _i = 0; _i < 2; ++_i) { unsigned _vo = (voff)[_i]; asm volatile("" : "+v"(_vo)); \
;         __builtin_amdgcn_global_load_lds((const GAS unsigned*)(_gb + _vo), (LAS unsigned*)(lds + (bufoff) + ldsw + _i * 8192), 16, 0, 0); } } while (0)
; #define PG8_LDA(dst, b, h) do { _Pragma("unroll") for (int m = 0; m < 4; ++m) _Pragma("unroll") for (int k = 0; k < 2; ++k) dst[m][k] = *(const LAS bf16x8*)(lds + PG8_SA(b, h) + aoff + m * 2048 + k * 1024); } while (0)
; #define PG8_MMA(ai, bj, At, Bt) do { __builtin_amdgcn_s_setprio(1); _Pragma("unroll") for (int m = 0; m < 4; ++m) _Pragma("unroll") for (int n = 0; n < 2; ++n) _Pragma("unroll") for (int k = 0; k < 2; ++k) \
;         acc[ai][bj][m][n] = __builtin_amdgcn_mfma_f32_16x16x32_bf16(Bt[n][k], At[m][k], acc[ai][bj][m][n], 0, 0, 0); __builtin_amdgcn_s_setprio(0); } while (0)
; #define PG8_WAIT_V(n) asm volatile("s_waitcnt vmcnt(" #n ")" ::: "memory")
; #define PG8_WAIT_L(n) asm volatile("s_waitcnt lgkmcnt(" #n ")" ::: "memory")
; #define PG8_BAR __builtin_amdgcn_s_barrier()
; #define PG8_SCHED __builtin_amdgcn_sched_barrier(0)
; template <class Epi, class Ord>
; __device__ __forceinline__ void gemm_phase(LAS unsigned char* lds, const Gemm g, const Ord& S, const Epi& E) {
;     ...
;             PG8_BAR; PG8_WAIT_L(0); PG8_MMA(0, 1, At, B1); PG8_BAR;
;             PG8_LDA(At, 1, 1); PG8_STAGE(PG8_SA(1, 0), a3, voffA);
;             PG8_BAR; PG8_WAIT_L(0); PG8_MMA(1, 0, At, B0); PG8_BAR; PG8_SCHED;
;             PG8_STAGE(PG8_SB(1, 1), b3 + hstep, voffB);
;             PG8_WAIT_V(6); PG8_BAR; PG8_MMA(1, 1, At, B1); PG8_BAR;
;         }
	s_waitcnt lgkmcnt(0)
	s_waitcnt lgkmcnt(0)
	v_mfma_f32_16x16x32_bf16 v[120:123], v[222:225], v[144:147], v[120:123]
	v_mfma_f32_16x16x32_bf16 v[112:115], v[230:233], v[144:147], v[112:115]
	v_mfma_f32_16x16x32_bf16 v[100:103], v[222:225], v[152:155], v[100:103]
	v_mfma_f32_16x16x32_bf16 v[96:99], v[230:233], v[152:155], v[96:99]
	v_mfma_f32_16x16x32_bf16 v[84:87], v[222:225], v[194:197], v[84:87]
	v_mfma_f32_16x16x32_bf16 v[80:83], v[230:233], v[194:197], v[80:83]
	v_mfma_f32_16x16x32_bf16 v[68:71], v[222:225], v[202:205], v[68:71]
	v_mfma_f32_16x16x32_bf16 v[64:67], v[230:233], v[202:205], v[64:67]
	v_mfma_f32_16x16x32_bf16 v[120:123], v[226:229], v[148:151], v[120:123]
	v_mfma_f32_16x16x32_bf16 v[112:115], v[234:237], v[148:151], v[112:115]
	v_mfma_f32_16x16x32_bf16 v[100:103], v[226:229], v[156:159], v[100:103]
	v_mfma_f32_16x16x32_bf16 v[96:99], v[234:237], v[156:159], v[96:99]
	v_mfma_f32_16x16x32_bf16 v[84:87], v[226:229], v[198:201], v[84:87]
	v_mfma_f32_16x16x32_bf16 v[80:83], v[234:237], v[198:201], v[80:83]
	v_mfma_f32_16x16x32_bf16 v[68:71], v[226:229], v[218:221], v[68:71]
	v_mfma_f32_16x16x32_bf16 v[64:67], v[234:237], v[218:221], v[64:67]
	v_mov_b32_e32 v206, v211
	s_mov_b32 m0, s69
	s_barrier
	ds_read_b128 v[144:147], v168 offset:49152
	ds_read_b128 v[148:151], v168 offset:50176
	ds_read_b128 v[152:155], v168 offset:51200
	ds_read_b128 v[156:159], v168 offset:52224
	ds_read_b128 v[194:197], v168 offset:53248
	ds_read_b128 v[198:201], v168 offset:54272
	ds_read_b128 v[202:205], v168 offset:55296
	ds_read_b128 v[218:221], v168 offset:56320
	s_nop 0
	global_load_lds_dwordx4 v206, s[12:13]
	v_mov_b32_e32 v206, v213
	s_mov_b32 m0, s70
	s_nop 0
	global_load_lds_dwordx4 v206, s[12:13]
	s_barrier
	s_waitcnt lgkmcnt(0)
	s_waitcnt lgkmcnt(0)
	v_mfma_f32_16x16x32_bf16 v[60:63], v[116:119], v[144:147], v[60:63]
	v_mfma_f32_16x16x32_bf16 v[56:59], v[128:131], v[144:147], v[56:59]
	v_mfma_f32_16x16x32_bf16 v[44:47], v[116:119], v[152:155], v[44:47]
	v_mfma_f32_16x16x32_bf16 v[40:43], v[128:131], v[152:155], v[40:43]
	v_mfma_f32_16x16x32_bf16 v[28:31], v[116:119], v[194:197], v[28:31]
	v_mfma_f32_16x16x32_bf16 v[24:27], v[128:131], v[194:197], v[24:27]
	v_mfma_f32_16x16x32_bf16 v[12:15], v[116:119], v[202:205], v[12:15]
	v_mfma_f32_16x16x32_bf16 v[8:11], v[128:131], v[202:205], v[8:11]
	v_mfma_f32_16x16x32_bf16 v[60:63], v[124:127], v[148:151], v[60:63]
	v_mfma_f32_16x16x32_bf16 v[56:59], v[136:139], v[148:151], v[56:59]
	v_mfma_f32_16x16x32_bf16 v[44:47], v[124:127], v[156:159], v[44:47]
	v_mfma_f32_16x16x32_bf16 v[40:43], v[136:139], v[156:159], v[40:43]
	v_mfma_f32_16x16x32_bf16 v[28:31], v[124:127], v[198:201], v[28:31]
	v_mfma_f32_16x16x32_bf16 v[24:27], v[136:139], v[198:201], v[24:27]
	v_mfma_f32_16x16x32_bf16 v[12:15], v[124:127], v[218:221], v[12:15]
	v_mfma_f32_16x16x32_bf16 v[8:11], v[136:139], v[218:221], v[8:11]
	s_barrier
	s_add_u32 s12, s22, 0x80
	s_addc_u32 s13, s23, 0
	v_mov_b32_e32 v116, v212
	s_add_i32 s16, s20, s56
	s_mov_b32 m0, s16
	s_nop 0
	global_load_lds_dwordx4 v116, s[12:13]
	v_mov_b32_e32 v116, v214
	s_add_i32 m0, s16, 0x2000
	s_nop 0
	global_load_lds_dwordx4 v116, s[12:13]
	s_waitcnt vmcnt(6)
	s_barrier
	v_mfma_f32_16x16x32_bf16 v[52:55], v[222:225], v[144:147], v[52:55]
	v_mfma_f32_16x16x32_bf16 v[48:51], v[230:233], v[144:147], v[48:51]
	v_mfma_f32_16x16x32_bf16 v[36:39], v[222:225], v[152:155], v[36:39]
	v_mfma_f32_16x16x32_bf16 v[32:35], v[230:233], v[152:155], v[32:35]
	v_mfma_f32_16x16x32_bf16 v[20:23], v[222:225], v[194:197], v[20:23]
	v_mfma_f32_16x16x32_bf16 v[16:19], v[230:233], v[194:197], v[16:19]
	v_mfma_f32_16x16x32_bf16 v[4:7], v[222:225], v[202:205], v[4:7]
	v_mfma_f32_16x16x32_bf16 v[0:3], v[230:233], v[202:205], v[0:3]
	v_mfma_f32_16x16x32_bf16 v[52:55], v[226:229], v[148:151], v[52:55]
	v_mfma_f32_16x16x32_bf16 v[48:51], v[234:237], v[148:151], v[48:51]
	v_mfma_f32_16x16x32_bf16 v[36:39], v[226:229], v[156:159], v[36:39]
	v_mfma_f32_16x16x32_bf16 v[32:35], v[234:237], v[156:159], v[32:35]
	v_mfma_f32_16x16x32_bf16 v[20:23], v[226:229], v[198:201], v[20:23]
	v_mfma_f32_16x16x32_bf16 v[16:19], v[234:237], v[198:201], v[16:19]
	v_mfma_f32_16x16x32_bf16 v[4:7], v[226:229], v[218:221], v[4:7]
	v_mfma_f32_16x16x32_bf16 v[0:3], v[234:237], v[218:221], v[0:3]
	s_add_u32 s78, s78, 0x100
	s_addc_u32 s79, s79, 0
	s_add_u32 s46, s46, 0x100
	s_addc_u32 s47, s47, 0
	s_cmp_ge_i32 s80, s68
	s_mov_b32 s12, s80
	s_barrier
	s_cbranch_scc0 .LBB0_312
	s_branch .LBB0_299

; #define PG8_STAGE(bufoff, gbase, voff) do { const char* _gb = (const char*)(gbase); asm volatile("" : "+s"(_gb)); _Pragma("unroll") for (int _i = 0; _i < 2; ++_i) { unsigned _vo = (voff)[_i]; asm volatile("" : "+v"(_vo)); \
;         __builtin_amdgcn_global_load_lds((const GAS unsigned*)(_gb + _vo), (LAS unsigned*)(lds + (bufoff) + ldsw + _i * 8192), 16, 0, 0); } } while (0)
; #define PG8_LDA(dst, b, h) do { _Pragma("unroll") for (int m = 0; m < 4; ++m) _Pragma("unroll") for (int k = 0; k < 2; ++k) dst[m][k] = *(const LAS bf16x8*)(lds + PG8_SA(b, h) + aoff + m * 2048 + k * 1024); } while (0)
; #define PG8_LDB(dst, b, h) do { _Pragma("unroll") for (int n = 0; n < 2; ++n) _Pragma("unroll") for (int k = 0; k < 2; ++k) dst[n][k] = *(const LAS bf16x8*)(lds + PG8_SB(b, h) + boff + n * 2048 + k * 1024); } while (0)
; #define PG8_MMA(ai, bj, At, Bt) do { __builtin_amdgcn_s_setprio(1); _Pragma("unroll") for (int m = 0; m < 4; ++m) _Pragma("unroll") for (int n = 0; n < 2; ++n) _Pragma("unroll") for (int k = 0; k < 2; ++k) \
;         acc[ai][bj][m][n] = __builtin_amdgcn_mfma_f32_16x16x32_bf16(Bt[n][k], At[m][k], acc[ai][bj][m][n], 0, 0, 0); __builtin_amdgcn_s_setprio(0); } while (0)
; #define PG8_WAIT_L(n) asm volatile("s_waitcnt lgkmcnt(" #n ")" ::: "memory")
; #define PG8_BAR __builtin_amdgcn_s_barrier()
; #define PG8_SCHED __builtin_amdgcn_sched_barrier(0)
; template <class Epi, class Ord>
; __device__ __forceinline__ void gemm_phase(LAS unsigned char* lds, const Gemm g, const Ord& S, const Epi& E) {
;     ...
;             const bool last = (t == nt - 2);
;             const char* a1 = cA + (size_t)(t + 1) * kstep;
;             const char* a2 = last ? nA : cA + (size_t)(t + 2) * kstep; const char* b2 = last ? nB : cB + (size_t)(t + 2) * kstep;
;             const char* a3 = a2 + kstep; const char* b3 = b2 + kstep;
;             PG8_LDB(B0, 0, 0); PG8_SCHED; PG8_LDA(At, 0, 0); PG8_STAGE(PG8_SA(1, 1), a1 + hstep, voffA);
;             PG8_WAIT_L(8); PG8_BAR; PG8_WAIT_L(0); PG8_MMA(0, 0, At, B0); PG8_BAR; PG8_SCHED;
;             PG8_LDB(B1, 0, 1); PG8_STAGE(PG8_SB(0, 0), b2, voffB);
;             PG8_BAR; PG8_WAIT_L(0); PG8_MMA(0, 1, At, B1); PG8_BAR;
;             PG8_LDA(At, 0, 1); PG8_STAGE(PG8_SA(0, 0), a2, voffA);
;             PG8_BAR; PG8_WAIT_L(0); PG8_MMA(1, 0, At, B0); PG8_BAR; PG8_SCHED;
.LBB0_498:
	s_add_i32 s80, s12, 2
	s_cmp_eq_u32 s73, s12
	s_cselect_b32 s22, s42, s48
	s_cselect_b32 s23, s43, s49
	s_cselect_b32 s20, s44, s46
	s_cselect_b32 s21, s45, s47
	s_add_u32 s12, s22, 0x80
	s_addc_u32 s13, s23, 0
	s_add_i32 s81, 0, 0x10000
	v_add_u32_e32 v128, s81, v135
	ds_read_b128 v[142:145], v128
	ds_read_b128 v[146:149], v128 offset:1024
	ds_read_b128 v[150:153], v128 offset:2048
	ds_read_b128 v[154:157], v128 offset:3072
	s_add_u32 s24, s48, s0
	s_addc_u32 s25, s49, s1
	s_add_u32 s24, s24, 0xffffff80
	s_addc_u32 s25, s25, -1
	v_mov_b32_e32 v128, v130
	ds_read_b128 v[192:195], v140
	ds_read_b128 v[196:199], v140 offset:1024
	ds_read_b128 v[200:203], v140 offset:2048
	ds_read_b128 v[204:207], v140 offset:3072
	ds_read_b128 v[212:215], v140 offset:4096
	ds_read_b128 v[216:219], v140 offset:5120
	ds_read_b128 v[220:223], v140 offset:6144
	ds_read_b128 v[224:227], v140 offset:7168
	s_add_i32 m0, s64, 0xc000
	s_nop 0
	global_load_lds_dwordx4 v128, s[24:25]
	v_mov_b32_e32 v128, v132
	s_add_i32 m0, s64, 0xe000
	s_nop 0
	global_load_lds_dwordx4 v128, s[24:25]
	s_waitcnt lgkmcnt(8)
	s_barrier
	s_waitcnt lgkmcnt(0)
	s_waitcnt lgkmcnt(0)
	v_mfma_f32_16x16x32_bf16 v[124:127], v[142:145], v[192:195], v[124:127]
	v_mfma_f32_16x16x32_bf16 v[120:123], v[150:153], v[192:195], v[120:123]
	v_mfma_f32_16x16x32_bf16 v[108:111], v[142:145], v[200:203], v[108:111]
	v_mfma_f32_16x16x32_bf16 v[104:107], v[150:153], v[200:203], v[104:107]
	v_mfma_f32_16x16x32_bf16 v[92:95], v[142:145], v[212:215], v[92:95]
	v_mfma_f32_16x16x32_bf16 v[88:91], v[150:153], v[212:215], v[88:91]
	v_mfma_f32_16x16x32_bf16 v[76:79], v[142:145], v[220:223], v[76:79]
	v_mfma_f32_16x16x32_bf16 v[72:75], v[150:153], v[220:223], v[72:75]
	v_mfma_f32_16x16x32_bf16 v[124:127], v[146:149], v[196:199], v[124:127]
	v_mfma_f32_16x16x32_bf16 v[120:123], v[154:157], v[196:199], v[120:123]
	v_mfma_f32_16x16x32_bf16 v[108:111], v[146:149], v[204:207], v[108:111]
	v_mfma_f32_16x16x32_bf16 v[104:107], v[154:157], v[204:207], v[104:107]
	v_mfma_f32_16x16x32_bf16 v[92:95], v[146:149], v[216:219], v[92:95]
	v_mfma_f32_16x16x32_bf16 v[88:91], v[154:157], v[216:219], v[88:91]
	v_mfma_f32_16x16x32_bf16 v[76:79], v[146:149], v[224:227], v[76:79]
	v_mfma_f32_16x16x32_bf16 v[72:75], v[154:157], v[224:227], v[72:75]
	s_barrier
	s_add_i32 s84, 0, 0x14000
	v_add_u32_e32 v128, s84, v135
	ds_read_b128 v[228:231], v128
	ds_read_b128 v[232:235], v128 offset:1024
	ds_read_b128 v[236:239], v128 offset:2048
	ds_read_b128 v[240:243], v128 offset:3072
	s_mov_b64 s[24:25], s[20:21]
	v_mov_b32_e32 v128, v131
	s_add_i32 s81, s81, s57
	s_mov_b32 m0, s81
	s_nop 0
	global_load_lds_dwordx4 v128, s[24:25]
	v_mov_b32_e32 v128, v133
	s_add_i32 m0, s81, 0x2000
	s_nop 0
	global_load_lds_dwordx4 v128, s[24:25]
	s_barrier
	s_waitcnt lgkmcnt(0)
	s_waitcnt lgkmcnt(0)
	v_mfma_f32_16x16x32_bf16 v[116:119], v[228:231], v[192:195], v[116:119]
	v_mfma_f32_16x16x32_bf16 v[112:115], v[236:239], v[192:195], v[112:115]
	v_mfma_f32_16x16x32_bf16 v[100:103], v[228:231], v[200:203], v[100:103]
	v_mfma_f32_16x16x32_bf16 v[96:99], v[236:239], v[200:203], v[96:99]
	v_mfma_f32_16x16x32_bf16 v[84:87], v[228:231], v[212:215], v[84:87]
	v_mfma_f32_16x16x32_bf16 v[80:83], v[236:239], v[212:215], v[80:83]
	v_mfma_f32_16x16x32_bf16 v[68:71], v[228:231], v[220:223], v[68:71]
	v_mfma_f32_16x16x32_bf16 v[64:67], v[236:239], v[220:223], v[64:67]
	v_mfma_f32_16x16x32_bf16 v[116:119], v[232:235], v[196:199], v[116:119]
	v_mfma_f32_16x16x32_bf16 v[112:115], v[240:243], v[196:199], v[112:115]
	v_mfma_f32_16x16x32_bf16 v[100:103], v[232:235], v[204:207], v[100:103]
	v_mfma_f32_16x16x32_bf16 v[96:99], v[240:243], v[204:207], v[96:99]
	v_mfma_f32_16x16x32_bf16 v[84:87], v[232:235], v[216:219], v[84:87]
	v_mfma_f32_16x16x32_bf16 v[80:83], v[240:243], v[216:219], v[80:83]
	v_mfma_f32_16x16x32_bf16 v[68:71], v[232:235], v[224:227], v[68:71]
	v_mfma_f32_16x16x32_bf16 v[64:67], v[240:243], v[224:227], v[64:67]
	s_mov_b64 s[24:25], s[22:23]
	v_mov_b32_e32 v128, v130
	s_mov_b32 m0, s64
	s_barrier
	ds_read_b128 v[192:195], v140 offset:16384
	ds_read_b128 v[196:199], v140 offset:17408
	ds_read_b128 v[200:203], v140 offset:18432
	ds_read_b128 v[204:207], v140 offset:19456
	ds_read_b128 v[212:215], v140 offset:20480
	ds_read_b128 v[216:219], v140 offset:21504
	ds_read_b128 v[220:223], v140 offset:22528
	ds_read_b128 v[224:227], v140 offset:23552
	s_nop 0
	global_load_lds_dwordx4 v128, s[24:25]
	v_mov_b32_e32 v128, v132
	s_mov_b32 m0, s65
	s_nop 0
	global_load_lds_dwordx4 v128, s[24:25]
	s_barrier
	s_waitcnt lgkmcnt(0)
	s_waitcnt lgkmcnt(0)
	v_mfma_f32_16x16x32_bf16 v[60:63], v[142:145], v[192:195], v[60:63]
	v_mfma_f32_16x16x32_bf16 v[56:59], v[150:153], v[192:195], v[56:59]
	v_mfma_f32_16x16x32_bf16 v[44:47], v[142:145], v[200:203], v[44:47]
	v_mfma_f32_16x16x32_bf16 v[40:43], v[150:153], v[200:203], v[40:43]
	v_mfma_f32_16x16x32_bf16 v[28:31], v[142:145], v[212:215], v[28:31]
	v_mfma_f32_16x16x32_bf16 v[24:27], v[150:153], v[212:215], v[24:27]
	v_mfma_f32_16x16x32_bf16 v[12:15], v[142:145], v[220:223], v[12:15]
	v_mfma_f32_16x16x32_bf16 v[8:11], v[150:153], v[220:223], v[8:11]
	v_mfma_f32_16x16x32_bf16 v[60:63], v[146:149], v[196:199], v[60:63]
	v_mfma_f32_16x16x32_bf16 v[56:59], v[154:157], v[196:199], v[56:59]
	v_mfma_f32_16x16x32_bf16 v[44:47], v[146:149], v[204:207], v[44:47]
	v_mfma_f32_16x16x32_bf16 v[40:43], v[154:157], v[204:207], v[40:43]
	v_mfma_f32_16x16x32_bf16 v[28:31], v[146:149], v[216:219], v[28:31]
	v_mfma_f32_16x16x32_bf16 v[24:27], v[154:157], v[216:219], v[24:27]
	v_mfma_f32_16x16x32_bf16 v[12:15], v[146:149], v[224:227], v[12:15]
	v_mfma_f32_16x16x32_bf16 v[8:11], v[154:157], v[224:227], v[8:11]
	s_barrier
; #define PG8_STAGE(bufoff, gbase, voff) do { const char* _gb = (const char*)(gbase); asm volatile("" : "+s"(_gb)); _Pragma("unroll") for (int _i = 0; _i < 2; ++_i) { unsigned _vo = (voff)[_i]; asm volatile("" : "+v"(_vo)); \
;         __builtin_amdgcn_global_load_lds((const GAS unsigned*)(_gb + _vo), (LAS unsigned*)(lds + (bufoff) + ldsw + _i * 8192), 16, 0, 0); } } while (0)
; #define PG8_LDA(dst, b, h) do { _Pragma("unroll") for (int m = 0; m < 4; ++m) _Pragma("unroll") for (int k = 0; k < 2; ++k) dst[m][k] = *(const LAS bf16x8*)(lds + PG8_SA(b, h) + aoff + m * 2048 + k * 1024); } while (0)
; #define PG8_LDB(dst, b, h) do { _Pragma("unroll") for (int n = 0; n < 2; ++n) _Pragma("unroll") for (int k = 0; k < 2; ++k) dst[n][k] = *(const LAS bf16x8*)(lds + PG8_SB(b, h) + boff + n * 2048 + k * 1024); } while (0)
; #define PG8_MMA(ai, bj, At, Bt) do { __builtin_amdgcn_s_setprio(1); _Pragma("unroll") for (int m = 0; m < 4; ++m) _Pragma("unroll") for (int n = 0; n < 2; ++n) _Pragma("unroll") for (int k = 0; k < 2; ++k) \
;         acc[ai][bj][m][n] = __builtin_amdgcn_mfma_f32_16x16x32_bf16(Bt[n][k], At[m][k], acc[ai][bj][m][n], 0, 0, 0); __builtin_amdgcn_s_setprio(0); } while (0)
; #define PG8_WAIT_V(n) asm volatile("s_waitcnt vmcnt(" #n ")" ::: "memory")
; #define PG8_WAIT_L(n) asm volatile("s_waitcnt lgkmcnt(" #n ")" ::: "memory")
; #define PG8_BAR __builtin_amdgcn_s_barrier()
; #define PG8_SCHED __builtin_amdgcn_sched_barrier(0)
; template <class Epi, class Ord>
; __device__ __forceinline__ void gemm_phase(LAS unsigned char* lds, const Gemm g, const Ord& S, const Epi& E) {
;     ...
;             PG8_STAGE(PG8_SB(0, 1), b2 + hstep, voffB);
;             PG8_WAIT_V(6); PG8_BAR; PG8_MMA(1, 1, At, B1); PG8_BAR;
;             PG8_LDB(B0, 1, 0); PG8_SCHED; PG8_LDA(At, 1, 0); PG8_STAGE(PG8_SA(0, 1), a2 + hstep, voffA);
;             PG8_WAIT_L(8); PG8_BAR; PG8_WAIT_L(0); PG8_MMA(0, 0, At, B0); PG8_BAR; PG8_SCHED;
;             PG8_LDB(B1, 1, 1); PG8_STAGE(PG8_SB(1, 0), b3, voffB);
	s_add_u32 s24, s20, s0
	s_addc_u32 s25, s21, s1
	s_mov_b64 s[82:83], s[24:25]
	v_mov_b32_e32 v128, v131
	s_add_i32 s81, s84, s57
	s_mov_b32 m0, s81
	s_nop 0
	global_load_lds_dwordx4 v128, s[82:83]
	v_mov_b32_e32 v128, v133
	s_add_i32 m0, s81, 0x2000
	s_nop 0
	global_load_lds_dwordx4 v128, s[82:83]
	s_waitcnt vmcnt(6)
	s_barrier
	v_mfma_f32_16x16x32_bf16 v[52:55], v[228:231], v[192:195], v[52:55]
	v_mfma_f32_16x16x32_bf16 v[48:51], v[236:239], v[192:195], v[48:51]
	v_mfma_f32_16x16x32_bf16 v[36:39], v[228:231], v[200:203], v[36:39]
	v_mfma_f32_16x16x32_bf16 v[32:35], v[236:239], v[200:203], v[32:35]
	v_mfma_f32_16x16x32_bf16 v[20:23], v[228:231], v[212:215], v[20:23]
	v_mfma_f32_16x16x32_bf16 v[16:19], v[236:239], v[212:215], v[16:19]
	v_mfma_f32_16x16x32_bf16 v[4:7], v[228:231], v[220:223], v[4:7]
	v_mfma_f32_16x16x32_bf16 v[0:3], v[236:239], v[220:223], v[0:3]
	v_mfma_f32_16x16x32_bf16 v[52:55], v[232:235], v[196:199], v[52:55]
	v_mfma_f32_16x16x32_bf16 v[48:51], v[240:243], v[196:199], v[48:51]
	v_mfma_f32_16x16x32_bf16 v[36:39], v[232:235], v[204:207], v[36:39]
	v_mfma_f32_16x16x32_bf16 v[32:35], v[240:243], v[204:207], v[32:35]
	v_mfma_f32_16x16x32_bf16 v[20:23], v[232:235], v[216:219], v[20:23]
	v_mfma_f32_16x16x32_bf16 v[16:19], v[240:243], v[216:219], v[16:19]
	v_mfma_f32_16x16x32_bf16 v[4:7], v[232:235], v[224:227], v[4:7]
	v_mfma_f32_16x16x32_bf16 v[0:3], v[240:243], v[224:227], v[0:3]
	s_add_i32 s81, 0, 0x18000
	v_add_u32_e32 v128, s81, v135
	s_barrier
	ds_read_b128 v[142:145], v128
	ds_read_b128 v[146:149], v128 offset:1024
	ds_read_b128 v[150:153], v128 offset:2048
	ds_read_b128 v[154:157], v128 offset:3072
	s_add_u32 s22, s22, s0
	s_addc_u32 s23, s23, s1
	v_mov_b32_e32 v128, v130
	s_mov_b32 m0, s68
	ds_read_b128 v[192:195], v140 offset:32768
	ds_read_b128 v[196:199], v140 offset:33792
	ds_read_b128 v[200:203], v140 offset:34816
	ds_read_b128 v[204:207], v140 offset:35840
	ds_read_b128 v[212:215], v140 offset:36864
	ds_read_b128 v[216:219], v140 offset:37888
	ds_read_b128 v[220:223], v140 offset:38912
	ds_read_b128 v[224:227], v140 offset:39936
	s_nop 0
	global_load_lds_dwordx4 v128, s[22:23]
	v_mov_b32_e32 v128, v132
	s_mov_b32 m0, s69
	s_nop 0
	global_load_lds_dwordx4 v128, s[22:23]
	s_waitcnt lgkmcnt(8)
	s_barrier
	s_waitcnt lgkmcnt(0)
	s_waitcnt lgkmcnt(0)
	v_mfma_f32_16x16x32_bf16 v[124:127], v[142:145], v[192:195], v[124:127]
	v_mfma_f32_16x16x32_bf16 v[120:123], v[150:153], v[192:195], v[120:123]
	v_mfma_f32_16x16x32_bf16 v[108:111], v[142:145], v[200:203], v[108:111]
	v_mfma_f32_16x16x32_bf16 v[104:107], v[150:153], v[200:203], v[104:107]
	v_mfma_f32_16x16x32_bf16 v[92:95], v[142:145], v[212:215], v[92:95]
	v_mfma_f32_16x16x32_bf16 v[88:91], v[150:153], v[212:215], v[88:91]
	v_mfma_f32_16x16x32_bf16 v[76:79], v[142:145], v[220:223], v[76:79]
	v_mfma_f32_16x16x32_bf16 v[72:75], v[150:153], v[220:223], v[72:75]
	v_mfma_f32_16x16x32_bf16 v[124:127], v[146:149], v[196:199], v[124:127]
	v_mfma_f32_16x16x32_bf16 v[120:123], v[154:157], v[196:199], v[120:123]
	v_mfma_f32_16x16x32_bf16 v[108:111], v[146:149], v[204:207], v[108:111]
	v_mfma_f32_16x16x32_bf16 v[104:107], v[154:157], v[204:207], v[104:107]
	v_mfma_f32_16x16x32_bf16 v[92:95], v[146:149], v[216:219], v[92:95]
	v_mfma_f32_16x16x32_bf16 v[88:91], v[154:157], v[216:219], v[88:91]
	v_mfma_f32_16x16x32_bf16 v[76:79], v[146:149], v[224:227], v[76:79]
	v_mfma_f32_16x16x32_bf16 v[72:75], v[154:157], v[224:227], v[72:75]
	s_barrier
	s_add_i32 s22, 0, 0x1c000
	v_add_u32_e32 v128, s22, v135
	s_add_u32 s20, s20, 0x80
	ds_read_b128 v[228:231], v128
	ds_read_b128 v[232:235], v128 offset:1024
	ds_read_b128 v[236:239], v128 offset:2048
	ds_read_b128 v[240:243], v128 offset:3072
	s_addc_u32 s21, s21, 0
	v_mov_b32_e32 v128, v131
	s_add_i32 s23, s81, s57
	s_mov_b32 m0, s23
	s_nop 0
	global_load_lds_dwordx4 v128, s[20:21]
	v_mov_b32_e32 v128, v133
	s_add_i32 m0, s23, 0x2000
	s_nop 0
	global_load_lds_dwordx4 v128, s[20:21]
	s_barrier
; #define PG8_STAGE(bufoff, gbase, voff) do { const char* _gb = (const char*)(gbase); asm volatile("" : "+s"(_gb)); _Pragma("unroll") for (int _i = 0; _i < 2; ++_i) { unsigned _vo = (voff)[_i]; asm volatile("" : "+v"(_vo)); \
;         __builtin_amdgcn_global_load_lds((const GAS unsigned*)(_gb + _vo), (LAS unsigned*)(lds + (bufoff) + ldsw + _i * 8192), 16, 0, 0); } } while (0)
; #define PG8_LDA(dst, b, h) do { _Pragma("unroll") for (int m = 0; m < 4; ++m) _Pragma("unroll") for (int k = 0; k < 2; ++k) dst[m][k] = *(const LAS bf16x8*)(lds + PG8_SA(b, h) + aoff + m * 2048 + k * 1024); } while (0)
; #define PG8_MMA(ai, bj, At, Bt) do { __builtin_amdgcn_s_setprio(1); _Pragma("unroll") for (int m = 0; m < 4; ++m) _Pragma("unroll") for (int n = 0; n < 2; ++n) _Pragma("unroll") for (int k = 0; k < 2; ++k) \
;         acc[ai][bj][m][n] = __builtin_amdgcn_mfma_f32_16x16x32_bf16(Bt[n][k], At[m][k], acc[ai][bj][m][n], 0, 0, 0); __builtin_amdgcn_s_setprio(0); } while (0)
; #define PG8_WAIT_V(n) asm volatile("s_waitcnt vmcnt(" #n ")" ::: "memory")
; #define PG8_WAIT_L(n) asm volatile("s_waitcnt lgkmcnt(" #n ")" ::: "memory")
; #define PG8_BAR __builtin_amdgcn_s_barrier()
; #define PG8_SCHED __builtin_amdgcn_sched_barrier(0)
; template <class Epi, class Ord>
; __device__ __forceinline__ void gemm_phase(LAS unsigned char* lds, const Gemm g, const Ord& S, const Epi& E) {
;     ...
;         for (int t = 0; t < nt; t += 2) {
;             const bool last = (t == nt - 2);
;             const char* a1 = cA + (size_t)(t + 1) * kstep;
;             const char* a2 = last ? nA : cA + (size_t)(t + 2) * kstep; const char* b2 = last ? nB : cB + (size_t)(t + 2) * kstep;
;     ...
;             PG8_BAR; PG8_WAIT_L(0); PG8_MMA(0, 1, At, B1); PG8_BAR;
;             PG8_LDA(At, 1, 1); PG8_STAGE(PG8_SA(1, 0), a3, voffA);
;             PG8_BAR; PG8_WAIT_L(0); PG8_MMA(1, 0, At, B0); PG8_BAR; PG8_SCHED;
;             PG8_STAGE(PG8_SB(1, 1), b3 + hstep, voffB);
;             PG8_WAIT_V(6); PG8_BAR; PG8_MMA(1, 1, At, B1); PG8_BAR;
	s_waitcnt lgkmcnt(0)
	s_waitcnt lgkmcnt(0)
	v_mfma_f32_16x16x32_bf16 v[116:119], v[228:231], v[192:195], v[116:119]
	v_mfma_f32_16x16x32_bf16 v[112:115], v[236:239], v[192:195], v[112:115]
	v_mfma_f32_16x16x32_bf16 v[100:103], v[228:231], v[200:203], v[100:103]
	v_mfma_f32_16x16x32_bf16 v[96:99], v[236:239], v[200:203], v[96:99]
	v_mfma_f32_16x16x32_bf16 v[84:87], v[228:231], v[212:215], v[84:87]
	v_mfma_f32_16x16x32_bf16 v[80:83], v[236:239], v[212:215], v[80:83]
	v_mfma_f32_16x16x32_bf16 v[68:71], v[228:231], v[220:223], v[68:71]
	v_mfma_f32_16x16x32_bf16 v[64:67], v[236:239], v[220:223], v[64:67]
	v_mfma_f32_16x16x32_bf16 v[116:119], v[232:235], v[196:199], v[116:119]
	v_mfma_f32_16x16x32_bf16 v[112:115], v[240:243], v[196:199], v[112:115]
	v_mfma_f32_16x16x32_bf16 v[100:103], v[232:235], v[204:207], v[100:103]
	v_mfma_f32_16x16x32_bf16 v[96:99], v[240:243], v[204:207], v[96:99]
	v_mfma_f32_16x16x32_bf16 v[84:87], v[232:235], v[216:219], v[84:87]
	v_mfma_f32_16x16x32_bf16 v[80:83], v[240:243], v[216:219], v[80:83]
	v_mfma_f32_16x16x32_bf16 v[68:71], v[232:235], v[224:227], v[68:71]
	v_mfma_f32_16x16x32_bf16 v[64:67], v[240:243], v[224:227], v[64:67]
	v_mov_b32_e32 v128, v130
	s_mov_b32 m0, s71
	s_barrier
	ds_read_b128 v[192:195], v140 offset:49152
	ds_read_b128 v[196:199], v140 offset:50176
	ds_read_b128 v[200:203], v140 offset:51200
	ds_read_b128 v[204:207], v140 offset:52224
	ds_read_b128 v[212:215], v140 offset:53248
	ds_read_b128 v[216:219], v140 offset:54272
	ds_read_b128 v[220:223], v140 offset:55296
	ds_read_b128 v[224:227], v140 offset:56320
	s_nop 0
	global_load_lds_dwordx4 v128, s[12:13]
	v_mov_b32_e32 v128, v132
	s_mov_b32 m0, s72
	s_nop 0
	global_load_lds_dwordx4 v128, s[12:13]
	s_barrier
	s_waitcnt lgkmcnt(0)
	s_waitcnt lgkmcnt(0)
	v_mfma_f32_16x16x32_bf16 v[60:63], v[142:145], v[192:195], v[60:63]
	v_mfma_f32_16x16x32_bf16 v[56:59], v[150:153], v[192:195], v[56:59]
	v_mfma_f32_16x16x32_bf16 v[44:47], v[142:145], v[200:203], v[44:47]
	v_mfma_f32_16x16x32_bf16 v[40:43], v[150:153], v[200:203], v[40:43]
	v_mfma_f32_16x16x32_bf16 v[28:31], v[142:145], v[212:215], v[28:31]
	v_mfma_f32_16x16x32_bf16 v[24:27], v[150:153], v[212:215], v[24:27]
	v_mfma_f32_16x16x32_bf16 v[12:15], v[142:145], v[220:223], v[12:15]
	v_mfma_f32_16x16x32_bf16 v[8:11], v[150:153], v[220:223], v[8:11]
	v_mfma_f32_16x16x32_bf16 v[60:63], v[146:149], v[196:199], v[60:63]
	v_mfma_f32_16x16x32_bf16 v[56:59], v[154:157], v[196:199], v[56:59]
	v_mfma_f32_16x16x32_bf16 v[44:47], v[146:149], v[204:207], v[44:47]
	v_mfma_f32_16x16x32_bf16 v[40:43], v[154:157], v[204:207], v[40:43]
	v_mfma_f32_16x16x32_bf16 v[28:31], v[146:149], v[216:219], v[28:31]
	v_mfma_f32_16x16x32_bf16 v[24:27], v[154:157], v[216:219], v[24:27]
	v_mfma_f32_16x16x32_bf16 v[12:15], v[146:149], v[224:227], v[12:15]
	v_mfma_f32_16x16x32_bf16 v[8:11], v[154:157], v[224:227], v[8:11]
	s_barrier
	s_add_u32 s12, s24, 0x80
	s_addc_u32 s13, s25, 0
	v_mov_b32_e32 v128, v131
	s_add_i32 s20, s22, s57
	s_mov_b32 m0, s20
	s_nop 0
	global_load_lds_dwordx4 v128, s[12:13]
	v_mov_b32_e32 v128, v133
	s_add_i32 m0, s20, 0x2000
	s_nop 0
	global_load_lds_dwordx4 v128, s[12:13]
	s_waitcnt vmcnt(6)
	s_barrier
	v_mfma_f32_16x16x32_bf16 v[52:55], v[228:231], v[192:195], v[52:55]
	v_mfma_f32_16x16x32_bf16 v[48:51], v[236:239], v[192:195], v[48:51]
	v_mfma_f32_16x16x32_bf16 v[36:39], v[228:231], v[200:203], v[36:39]
	v_mfma_f32_16x16x32_bf16 v[32:35], v[236:239], v[200:203], v[32:35]
	v_mfma_f32_16x16x32_bf16 v[20:23], v[228:231], v[212:215], v[20:23]
	v_mfma_f32_16x16x32_bf16 v[16:19], v[236:239], v[212:215], v[16:19]
	v_mfma_f32_16x16x32_bf16 v[4:7], v[228:231], v[220:223], v[4:7]
	v_mfma_f32_16x16x32_bf16 v[0:3], v[236:239], v[220:223], v[0:3]
	v_mfma_f32_16x16x32_bf16 v[52:55], v[232:235], v[196:199], v[52:55]
	v_mfma_f32_16x16x32_bf16 v[48:51], v[240:243], v[196:199], v[48:51]
	v_mfma_f32_16x16x32_bf16 v[36:39], v[232:235], v[204:207], v[36:39]
	v_mfma_f32_16x16x32_bf16 v[32:35], v[240:243], v[204:207], v[32:35]
	v_mfma_f32_16x16x32_bf16 v[20:23], v[232:235], v[216:219], v[20:23]
	v_mfma_f32_16x16x32_bf16 v[16:19], v[240:243], v[216:219], v[16:19]
	v_mfma_f32_16x16x32_bf16 v[4:7], v[232:235], v[224:227], v[4:7]
	v_mfma_f32_16x16x32_bf16 v[0:3], v[240:243], v[224:227], v[0:3]
	s_add_u32 s46, s46, 0x100
	s_addc_u32 s47, s47, 0
	s_add_u32 s48, s48, 0x100
	s_addc_u32 s49, s49, 0
	s_cmp_ge_i32 s80, s70
	s_mov_b32 s12, s80
	s_barrier
	s_cbranch_scc0 .LBB0_498
	s_branch .LBB0_484

; #define PG8_STAGE(bufoff, gbase, voff) do { const char* _gb = (const char*)(gbase); asm volatile("" : "+s"(_gb)); _Pragma("unroll") for (int _i = 0; _i < 2; ++_i) { unsigned _vo = (voff)[_i]; asm volatile("" : "+v"(_vo)); \
;         __builtin_amdgcn_global_load_lds((const GAS unsigned*)(_gb + _vo), (LAS unsigned*)(lds + (bufoff) + ldsw + _i * 8192), 16, 0, 0); } } while (0)
; #define PG8_LDA(dst, b, h) do { _Pragma("unroll") for (int m = 0; m < 4; ++m) _Pragma("unroll") for (int k = 0; k < 2; ++k) dst[m][k] = *(const LAS bf16x8*)(lds + PG8_SA(b, h) + aoff + m * 2048 + k * 1024); } while (0)
; #define PG8_LDB(dst, b, h) do { _Pragma("unroll") for (int n = 0; n < 2; ++n) _Pragma("unroll") for (int k = 0; k < 2; ++k) dst[n][k] = *(const LAS bf16x8*)(lds + PG8_SB(b, h) + boff + n * 2048 + k * 1024); } while (0)
; #define PG8_MMA(ai, bj, At, Bt) do { __builtin_amdgcn_s_setprio(1); _Pragma("unroll") for (int m = 0; m < 4; ++m) _Pragma("unroll") for (int n = 0; n < 2; ++n) _Pragma("unroll") for (int k = 0; k < 2; ++k) \
;         acc[ai][bj][m][n] = __builtin_amdgcn_mfma_f32_16x16x32_bf16(Bt[n][k], At[m][k], acc[ai][bj][m][n], 0, 0, 0); __builtin_amdgcn_s_setprio(0); } while (0)
; #define PG8_WAIT_L(n) asm volatile("s_waitcnt lgkmcnt(" #n ")" ::: "memory")
; #define PG8_BAR __builtin_amdgcn_s_barrier()
; #define PG8_SCHED __builtin_amdgcn_sched_barrier(0)
; template <class Epi, class Ord>
; __device__ __forceinline__ void gemm_phase(LAS unsigned char* lds, const Gemm g, const Ord& S, const Epi& E) {
;     ...
;             const bool last = (t == nt - 2);
;             const char* a1 = cA + (size_t)(t + 1) * kstep;
;             const char* a2 = last ? nA : cA + (size_t)(t + 2) * kstep; const char* b2 = last ? nB : cB + (size_t)(t + 2) * kstep;
;             const char* a3 = a2 + kstep; const char* b3 = b2 + kstep;
;             PG8_LDB(B0, 0, 0); PG8_SCHED; PG8_LDA(At, 0, 0); PG8_STAGE(PG8_SA(1, 1), a1 + hstep, voffA);
;             PG8_WAIT_L(8); PG8_BAR; PG8_WAIT_L(0); PG8_MMA(0, 0, At, B0); PG8_BAR; PG8_SCHED;
;             PG8_LDB(B1, 0, 1); PG8_STAGE(PG8_SB(0, 0), b2, voffB);
;             PG8_BAR; PG8_WAIT_L(0); PG8_MMA(0, 1, At, B1); PG8_BAR;
;             PG8_LDA(At, 0, 1); PG8_STAGE(PG8_SA(0, 0), a2, voffA);
;             PG8_BAR; PG8_WAIT_L(0); PG8_MMA(1, 0, At, B0); PG8_BAR; PG8_SCHED;
.LBB0_528:
	s_add_i32 s56, s12, 2
	s_cmp_eq_u32 s81, s12
	s_cselect_b32 s22, s0, s52
	s_cselect_b32 s23, s1, s53
	s_cselect_b32 s20, s16, s48
	s_cselect_b32 s21, s17, s49
	s_add_u32 s12, s22, 0x80
	s_addc_u32 s13, s23, 0
	s_add_i32 s57, 0, 0x10000
	v_add_u32_e32 v144, s57, v204
	ds_read_b128 v[132:135], v144
	ds_read_b128 v[136:139], v144 offset:1024
	ds_read_b128 v[140:143], v144 offset:2048
	ds_read_b128 v[144:147], v144 offset:3072
	s_add_u32 s24, s52, s10
	s_addc_u32 s25, s53, s11
	s_add_u32 s24, s24, 0xffffff80
	s_addc_u32 s25, s25, -1
	v_mov_b32_e32 v168, v129
	ds_read_b128 v[148:151], v206
	ds_read_b128 v[152:155], v206 offset:1024
	ds_read_b128 v[156:159], v206 offset:2048
	ds_read_b128 v[192:195], v206 offset:3072
	ds_read_b128 v[196:199], v206 offset:4096
	ds_read_b128 v[212:215], v206 offset:5120
	ds_read_b128 v[216:219], v206 offset:6144
	ds_read_b128 v[220:223], v206 offset:7168
	s_add_i32 m0, s69, 0xc000
	s_nop 0
	global_load_lds_dwordx4 v168, s[24:25]
	v_mov_b32_e32 v168, v201
	s_add_i32 m0, s69, 0xe000
	s_nop 0
	global_load_lds_dwordx4 v168, s[24:25]
	s_waitcnt lgkmcnt(8)
	s_barrier
	s_waitcnt lgkmcnt(0)
	s_waitcnt lgkmcnt(0)
	v_mfma_f32_16x16x32_bf16 v[124:127], v[132:135], v[148:151], v[124:127]
	v_mfma_f32_16x16x32_bf16 v[120:123], v[140:143], v[148:151], v[120:123]
	v_mfma_f32_16x16x32_bf16 v[116:119], v[132:135], v[156:159], v[116:119]
	v_mfma_f32_16x16x32_bf16 v[112:115], v[140:143], v[156:159], v[112:115]
	v_mfma_f32_16x16x32_bf16 v[100:103], v[132:135], v[196:199], v[100:103]
	v_mfma_f32_16x16x32_bf16 v[96:99], v[140:143], v[196:199], v[96:99]
	v_mfma_f32_16x16x32_bf16 v[84:87], v[132:135], v[216:219], v[84:87]
	v_mfma_f32_16x16x32_bf16 v[80:83], v[140:143], v[216:219], v[80:83]
	v_mfma_f32_16x16x32_bf16 v[124:127], v[136:139], v[152:155], v[124:127]
	v_mfma_f32_16x16x32_bf16 v[120:123], v[144:147], v[152:155], v[120:123]
	v_mfma_f32_16x16x32_bf16 v[116:119], v[136:139], v[192:195], v[116:119]
	v_mfma_f32_16x16x32_bf16 v[112:115], v[144:147], v[192:195], v[112:115]
	v_mfma_f32_16x16x32_bf16 v[100:103], v[136:139], v[212:215], v[100:103]
	v_mfma_f32_16x16x32_bf16 v[96:99], v[144:147], v[212:215], v[96:99]
	v_mfma_f32_16x16x32_bf16 v[84:87], v[136:139], v[220:223], v[84:87]
	v_mfma_f32_16x16x32_bf16 v[80:83], v[144:147], v[220:223], v[80:83]
	s_barrier
	s_add_i32 s84, 0, 0x14000
	v_add_u32_e32 v168, s84, v204
	ds_read_b128 v[224:227], v168
	ds_read_b128 v[228:231], v168 offset:1024
	ds_read_b128 v[232:235], v168 offset:2048
	ds_read_b128 v[236:239], v168 offset:3072
	s_mov_b64 s[24:25], s[20:21]
	v_mov_b32_e32 v168, v200
	s_add_i32 s57, s57, s68
	s_mov_b32 m0, s57
	s_nop 0
	global_load_lds_dwordx4 v168, s[24:25]
	v_mov_b32_e32 v168, v202
	s_add_i32 m0, s57, 0x2000
	s_nop 0
	global_load_lds_dwordx4 v168, s[24:25]
	s_barrier
	s_waitcnt lgkmcnt(0)
	s_waitcnt lgkmcnt(0)
	v_mfma_f32_16x16x32_bf16 v[108:111], v[224:227], v[148:151], v[108:111]
	v_mfma_f32_16x16x32_bf16 v[104:107], v[232:235], v[148:151], v[104:107]
	v_mfma_f32_16x16x32_bf16 v[92:95], v[224:227], v[156:159], v[92:95]
	v_mfma_f32_16x16x32_bf16 v[88:91], v[232:235], v[156:159], v[88:91]
	v_mfma_f32_16x16x32_bf16 v[76:79], v[224:227], v[196:199], v[76:79]
	v_mfma_f32_16x16x32_bf16 v[72:75], v[232:235], v[196:199], v[72:75]
	v_mfma_f32_16x16x32_bf16 v[68:71], v[224:227], v[216:219], v[68:71]
	v_mfma_f32_16x16x32_bf16 v[64:67], v[232:235], v[216:219], v[64:67]
	v_mfma_f32_16x16x32_bf16 v[108:111], v[228:231], v[152:155], v[108:111]
	v_mfma_f32_16x16x32_bf16 v[104:107], v[236:239], v[152:155], v[104:107]
	v_mfma_f32_16x16x32_bf16 v[92:95], v[228:231], v[192:195], v[92:95]
	v_mfma_f32_16x16x32_bf16 v[88:91], v[236:239], v[192:195], v[88:91]
	v_mfma_f32_16x16x32_bf16 v[76:79], v[228:231], v[212:215], v[76:79]
	v_mfma_f32_16x16x32_bf16 v[72:75], v[236:239], v[212:215], v[72:75]
	v_mfma_f32_16x16x32_bf16 v[68:71], v[228:231], v[220:223], v[68:71]
	v_mfma_f32_16x16x32_bf16 v[64:67], v[236:239], v[220:223], v[64:67]
	s_mov_b64 s[24:25], s[22:23]
	v_mov_b32_e32 v168, v129
	s_mov_b32 m0, s69
	s_barrier
	ds_read_b128 v[148:151], v206 offset:16384
	ds_read_b128 v[152:155], v206 offset:17408
	ds_read_b128 v[156:159], v206 offset:18432
	ds_read_b128 v[192:195], v206 offset:19456
	ds_read_b128 v[196:199], v206 offset:20480
	ds_read_b128 v[212:215], v206 offset:21504
	ds_read_b128 v[216:219], v206 offset:22528
	ds_read_b128 v[220:223], v206 offset:23552
	s_nop 0
	global_load_lds_dwordx4 v168, s[24:25]
	v_mov_b32_e32 v168, v201
	s_mov_b32 m0, s70
	s_nop 0
	global_load_lds_dwordx4 v168, s[24:25]
	s_barrier
	s_waitcnt lgkmcnt(0)
	s_waitcnt lgkmcnt(0)
	v_mfma_f32_16x16x32_bf16 v[60:63], v[132:135], v[148:151], v[60:63]
	v_mfma_f32_16x16x32_bf16 v[56:59], v[140:143], v[148:151], v[56:59]
	v_mfma_f32_16x16x32_bf16 v[52:55], v[132:135], v[156:159], v[52:55]
	v_mfma_f32_16x16x32_bf16 v[48:51], v[140:143], v[156:159], v[48:51]
	v_mfma_f32_16x16x32_bf16 v[40:43], v[132:135], v[196:199], v[40:43]
	v_mfma_f32_16x16x32_bf16 v[32:35], v[140:143], v[196:199], v[32:35]
	v_mfma_f32_16x16x32_bf16 v[24:27], v[132:135], v[216:219], v[24:27]
	v_mfma_f32_16x16x32_bf16 v[16:19], v[140:143], v[216:219], v[16:19]
	v_mfma_f32_16x16x32_bf16 v[60:63], v[136:139], v[152:155], v[60:63]
	v_mfma_f32_16x16x32_bf16 v[56:59], v[144:147], v[152:155], v[56:59]
	v_mfma_f32_16x16x32_bf16 v[52:55], v[136:139], v[192:195], v[52:55]
	v_mfma_f32_16x16x32_bf16 v[48:51], v[144:147], v[192:195], v[48:51]
	v_mfma_f32_16x16x32_bf16 v[40:43], v[136:139], v[212:215], v[40:43]
	v_mfma_f32_16x16x32_bf16 v[32:35], v[144:147], v[212:215], v[32:35]
	v_mfma_f32_16x16x32_bf16 v[24:27], v[136:139], v[220:223], v[24:27]
	v_mfma_f32_16x16x32_bf16 v[16:19], v[144:147], v[220:223], v[16:19]
	s_barrier
; #define PG8_STAGE(bufoff, gbase, voff) do { const char* _gb = (const char*)(gbase); asm volatile("" : "+s"(_gb)); _Pragma("unroll") for (int _i = 0; _i < 2; ++_i) { unsigned _vo = (voff)[_i]; asm volatile("" : "+v"(_vo)); \
;         __builtin_amdgcn_global_load_lds((const GAS unsigned*)(_gb + _vo), (LAS unsigned*)(lds + (bufoff) + ldsw + _i * 8192), 16, 0, 0); } } while (0)
; #define PG8_LDA(dst, b, h) do { _Pragma("unroll") for (int m = 0; m < 4; ++m) _Pragma("unroll") for (int k = 0; k < 2; ++k) dst[m][k] = *(const LAS bf16x8*)(lds + PG8_SA(b, h) + aoff + m * 2048 + k * 1024); } while (0)
; #define PG8_LDB(dst, b, h) do { _Pragma("unroll") for (int n = 0; n < 2; ++n) _Pragma("unroll") for (int k = 0; k < 2; ++k) dst[n][k] = *(const LAS bf16x8*)(lds + PG8_SB(b, h) + boff + n * 2048 + k * 1024); } while (0)
; #define PG8_MMA(ai, bj, At, Bt) do { __builtin_amdgcn_s_setprio(1); _Pragma("unroll") for (int m = 0; m < 4; ++m) _Pragma("unroll") for (int n = 0; n < 2; ++n) _Pragma("unroll") for (int k = 0; k < 2; ++k) \
;         acc[ai][bj][m][n] = __builtin_amdgcn_mfma_f32_16x16x32_bf16(Bt[n][k], At[m][k], acc[ai][bj][m][n], 0, 0, 0); __builtin_amdgcn_s_setprio(0); } while (0)
; #define PG8_WAIT_V(n) asm volatile("s_waitcnt vmcnt(" #n ")" ::: "memory")
; #define PG8_WAIT_L(n) asm volatile("s_waitcnt lgkmcnt(" #n ")" ::: "memory")
; #define PG8_BAR __builtin_amdgcn_s_barrier()
; #define PG8_SCHED __builtin_amdgcn_sched_barrier(0)
; template <class Epi, class Ord>
; __device__ __forceinline__ void gemm_phase(LAS unsigned char* lds, const Gemm g, const Ord& S, const Epi& E) {
;     ...
;             PG8_STAGE(PG8_SB(0, 1), b2 + hstep, voffB);
;             PG8_WAIT_V(6); PG8_BAR; PG8_MMA(1, 1, At, B1); PG8_BAR;
;             PG8_LDB(B0, 1, 0); PG8_SCHED; PG8_LDA(At, 1, 0); PG8_STAGE(PG8_SA(0, 1), a2 + hstep, voffA);
;             PG8_WAIT_L(8); PG8_BAR; PG8_WAIT_L(0); PG8_MMA(0, 0, At, B0); PG8_BAR; PG8_SCHED;
;             PG8_LDB(B1, 1, 1); PG8_STAGE(PG8_SB(1, 0), b3, voffB);
;             PG8_BAR; PG8_WAIT_L(0); PG8_MMA(0, 1, At, B1); PG8_BAR;
;             PG8_LDA(At, 1, 1); PG8_STAGE(PG8_SA(1, 0), a3, voffA);
	s_add_u32 s24, s20, s10
	s_addc_u32 s25, s21, s11
	s_mov_b64 s[82:83], s[24:25]
	v_mov_b32_e32 v132, v200
	s_add_i32 s57, s84, s68
	s_mov_b32 m0, s57
	s_nop 0
	global_load_lds_dwordx4 v132, s[82:83]
	v_mov_b32_e32 v132, v202
	s_add_i32 m0, s57, 0x2000
	s_nop 0
	global_load_lds_dwordx4 v132, s[82:83]
	s_waitcnt vmcnt(6)
	s_barrier
	v_mfma_f32_16x16x32_bf16 v[44:47], v[224:227], v[148:151], v[44:47]
	v_mfma_f32_16x16x32_bf16 v[36:39], v[232:235], v[148:151], v[36:39]
	v_mfma_f32_16x16x32_bf16 v[28:31], v[224:227], v[156:159], v[28:31]
	v_mfma_f32_16x16x32_bf16 v[20:23], v[232:235], v[156:159], v[20:23]
	v_mfma_f32_16x16x32_bf16 v[12:15], v[224:227], v[196:199], v[12:15]
	v_mfma_f32_16x16x32_bf16 v[8:11], v[232:235], v[196:199], v[8:11]
	v_mfma_f32_16x16x32_bf16 v[4:7], v[224:227], v[216:219], v[4:7]
	v_mfma_f32_16x16x32_bf16 v[0:3], v[232:235], v[216:219], v[0:3]
	v_mfma_f32_16x16x32_bf16 v[44:47], v[228:231], v[152:155], v[44:47]
	v_mfma_f32_16x16x32_bf16 v[36:39], v[236:239], v[152:155], v[36:39]
	v_mfma_f32_16x16x32_bf16 v[28:31], v[228:231], v[192:195], v[28:31]
	v_mfma_f32_16x16x32_bf16 v[20:23], v[236:239], v[192:195], v[20:23]
	v_mfma_f32_16x16x32_bf16 v[12:15], v[228:231], v[212:215], v[12:15]
	v_mfma_f32_16x16x32_bf16 v[8:11], v[236:239], v[212:215], v[8:11]
	v_mfma_f32_16x16x32_bf16 v[4:7], v[228:231], v[220:223], v[4:7]
	v_mfma_f32_16x16x32_bf16 v[0:3], v[236:239], v[220:223], v[0:3]
	s_add_i32 s57, 0, 0x18000
	v_add_u32_e32 v144, s57, v204
	s_barrier
	ds_read_b128 v[132:135], v144
	ds_read_b128 v[136:139], v144 offset:1024
	ds_read_b128 v[140:143], v144 offset:2048
	ds_read_b128 v[144:147], v144 offset:3072
	s_add_u32 s22, s22, s10
	s_addc_u32 s23, s23, s11
	v_mov_b32_e32 v168, v129
	s_mov_b32 m0, s71
	ds_read_b128 v[148:151], v206 offset:32768
	ds_read_b128 v[152:155], v206 offset:33792
	ds_read_b128 v[156:159], v206 offset:34816
	ds_read_b128 v[192:195], v206 offset:35840
	ds_read_b128 v[196:199], v206 offset:36864
	ds_read_b128 v[212:215], v206 offset:37888
	ds_read_b128 v[216:219], v206 offset:38912
	ds_read_b128 v[220:223], v206 offset:39936
	s_nop 0
	global_load_lds_dwordx4 v168, s[22:23]
	v_mov_b32_e32 v168, v201
	s_mov_b32 m0, s72
	s_nop 0
	global_load_lds_dwordx4 v168, s[22:23]
	s_waitcnt lgkmcnt(8)
	s_barrier
	s_waitcnt lgkmcnt(0)
	s_waitcnt lgkmcnt(0)
	v_mfma_f32_16x16x32_bf16 v[124:127], v[132:135], v[148:151], v[124:127]
	v_mfma_f32_16x16x32_bf16 v[120:123], v[140:143], v[148:151], v[120:123]
	v_mfma_f32_16x16x32_bf16 v[116:119], v[132:135], v[156:159], v[116:119]
	v_mfma_f32_16x16x32_bf16 v[112:115], v[140:143], v[156:159], v[112:115]
	v_mfma_f32_16x16x32_bf16 v[100:103], v[132:135], v[196:199], v[100:103]
	v_mfma_f32_16x16x32_bf16 v[96:99], v[140:143], v[196:199], v[96:99]
	v_mfma_f32_16x16x32_bf16 v[84:87], v[132:135], v[216:219], v[84:87]
	v_mfma_f32_16x16x32_bf16 v[80:83], v[140:143], v[216:219], v[80:83]
	v_mfma_f32_16x16x32_bf16 v[124:127], v[136:139], v[152:155], v[124:127]
	v_mfma_f32_16x16x32_bf16 v[120:123], v[144:147], v[152:155], v[120:123]
	v_mfma_f32_16x16x32_bf16 v[116:119], v[136:139], v[192:195], v[116:119]
	v_mfma_f32_16x16x32_bf16 v[112:115], v[144:147], v[192:195], v[112:115]
	v_mfma_f32_16x16x32_bf16 v[100:103], v[136:139], v[212:215], v[100:103]
	v_mfma_f32_16x16x32_bf16 v[96:99], v[144:147], v[212:215], v[96:99]
	v_mfma_f32_16x16x32_bf16 v[84:87], v[136:139], v[220:223], v[84:87]
	v_mfma_f32_16x16x32_bf16 v[80:83], v[144:147], v[220:223], v[80:83]
	s_barrier
	s_add_i32 s22, 0, 0x1c000
	v_add_u32_e32 v168, s22, v204
	s_add_u32 s20, s20, 0x80
	ds_read_b128 v[224:227], v168
	ds_read_b128 v[228:231], v168 offset:1024
	ds_read_b128 v[232:235], v168 offset:2048
	ds_read_b128 v[236:239], v168 offset:3072
	s_addc_u32 s21, s21, 0
	v_mov_b32_e32 v168, v200
	s_add_i32 s23, s57, s68
	s_mov_b32 m0, s23
	s_nop 0
	global_load_lds_dwordx4 v168, s[20:21]
	v_mov_b32_e32 v168, v202
	s_add_i32 m0, s23, 0x2000
	s_nop 0
	global_load_lds_dwordx4 v168, s[20:21]
	s_barrier
	s_waitcnt lgkmcnt(0)
	s_waitcnt lgkmcnt(0)
	v_mfma_f32_16x16x32_bf16 v[108:111], v[224:227], v[148:151], v[108:111]
	v_mfma_f32_16x16x32_bf16 v[104:107], v[232:235], v[148:151], v[104:107]
	v_mfma_f32_16x16x32_bf16 v[92:95], v[224:227], v[156:159], v[92:95]
	v_mfma_f32_16x16x32_bf16 v[88:91], v[232:235], v[156:159], v[88:91]
	v_mfma_f32_16x16x32_bf16 v[76:79], v[224:227], v[196:199], v[76:79]
	v_mfma_f32_16x16x32_bf16 v[72:75], v[232:235], v[196:199], v[72:75]
	v_mfma_f32_16x16x32_bf16 v[68:71], v[224:227], v[216:219], v[68:71]
	v_mfma_f32_16x16x32_bf16 v[64:67], v[232:235], v[216:219], v[64:67]
	v_mfma_f32_16x16x32_bf16 v[108:111], v[228:231], v[152:155], v[108:111]
	v_mfma_f32_16x16x32_bf16 v[104:107], v[236:239], v[152:155], v[104:107]
	v_mfma_f32_16x16x32_bf16 v[92:95], v[228:231], v[192:195], v[92:95]
	v_mfma_f32_16x16x32_bf16 v[88:91], v[236:239], v[192:195], v[88:91]
	v_mfma_f32_16x16x32_bf16 v[76:79], v[228:231], v[212:215], v[76:79]
	v_mfma_f32_16x16x32_bf16 v[72:75], v[236:239], v[212:215], v[72:75]
	v_mfma_f32_16x16x32_bf16 v[68:71], v[228:231], v[220:223], v[68:71]
	v_mfma_f32_16x16x32_bf16 v[64:67], v[236:239], v[220:223], v[64:67]
	v_mov_b32_e32 v168, v129
	s_mov_b32 m0, s78
	s_barrier
	ds_read_b128 v[148:151], v206 offset:49152
	ds_read_b128 v[152:155], v206 offset:50176
	ds_read_b128 v[156:159], v206 offset:51200
	ds_read_b128 v[192:195], v206 offset:52224
	ds_read_b128 v[196:199], v206 offset:53248
	ds_read_b128 v[212:215], v206 offset:54272
	ds_read_b128 v[216:219], v206 offset:55296
	ds_read_b128 v[220:223], v206 offset:56320
	s_nop 0
	global_load_lds_dwordx4 v168, s[12:13]
	v_mov_b32_e32 v168, v201
	s_mov_b32 m0, s79
	s_nop 0
	global_load_lds_dwordx4 v168, s[12:13]
	s_barrier
; #define PG8_STAGE(bufoff, gbase, voff) do { const char* _gb = (const char*)(gbase); asm volatile("" : "+s"(_gb)); _Pragma("unroll") for (int _i = 0; _i < 2; ++_i) { unsigned _vo = (voff)[_i]; asm volatile("" : "+v"(_vo)); \
;         __builtin_amdgcn_global_load_lds((const GAS unsigned*)(_gb + _vo), (LAS unsigned*)(lds + (bufoff) + ldsw + _i * 8192), 16, 0, 0); } } while (0)
; #define PG8_MMA(ai, bj, At, Bt) do { __builtin_amdgcn_s_setprio(1); _Pragma("unroll") for (int m = 0; m < 4; ++m) _Pragma("unroll") for (int n = 0; n < 2; ++n) _Pragma("unroll") for (int k = 0; k < 2; ++k) \
;         acc[ai][bj][m][n] = __builtin_amdgcn_mfma_f32_16x16x32_bf16(Bt[n][k], At[m][k], acc[ai][bj][m][n], 0, 0, 0); __builtin_amdgcn_s_setprio(0); } while (0)
; #define PG8_WAIT_V(n) asm volatile("s_waitcnt vmcnt(" #n ")" ::: "memory")
; #define PG8_WAIT_L(n) asm volatile("s_waitcnt lgkmcnt(" #n ")" ::: "memory")
; #define PG8_BAR __builtin_amdgcn_s_barrier()
; #define PG8_SCHED __builtin_amdgcn_sched_barrier(0)
; template <class Epi, class Ord>
; __device__ __forceinline__ void gemm_phase(LAS unsigned char* lds, const Gemm g, const Ord& S, const Epi& E) {
;     ...
;             PG8_BAR; PG8_WAIT_L(0); PG8_MMA(1, 0, At, B0); PG8_BAR; PG8_SCHED;
;             PG8_STAGE(PG8_SB(1, 1), b3 + hstep, voffB);
;             PG8_WAIT_V(6); PG8_BAR; PG8_MMA(1, 1, At, B1); PG8_BAR;
;     template <int NM> __device__ __forceinline__ void round(const AccT& acc, const Unit& u, int ai, int m0, int wr, int wc, int fr, int fq) const {
;     ...
;                 if (MODE == 0) { d0 = acc[ai][bj][m][0] * alpha; d1 = acc[ai][bj][m][1] * alpha; }
	s_waitcnt lgkmcnt(0)
	s_waitcnt lgkmcnt(0)
	v_mfma_f32_16x16x32_bf16 v[60:63], v[132:135], v[148:151], v[60:63]
	v_mfma_f32_16x16x32_bf16 v[56:59], v[140:143], v[148:151], v[56:59]
	v_mfma_f32_16x16x32_bf16 v[52:55], v[132:135], v[156:159], v[52:55]
	v_mfma_f32_16x16x32_bf16 v[48:51], v[140:143], v[156:159], v[48:51]
	v_mfma_f32_16x16x32_bf16 v[40:43], v[132:135], v[196:199], v[40:43]
	v_mfma_f32_16x16x32_bf16 v[32:35], v[140:143], v[196:199], v[32:35]
	v_mfma_f32_16x16x32_bf16 v[24:27], v[132:135], v[216:219], v[24:27]
	v_mfma_f32_16x16x32_bf16 v[16:19], v[140:143], v[216:219], v[16:19]
	v_mfma_f32_16x16x32_bf16 v[60:63], v[136:139], v[152:155], v[60:63]
	v_mfma_f32_16x16x32_bf16 v[56:59], v[144:147], v[152:155], v[56:59]
	v_mfma_f32_16x16x32_bf16 v[52:55], v[136:139], v[192:195], v[52:55]
	v_mfma_f32_16x16x32_bf16 v[48:51], v[144:147], v[192:195], v[48:51]
	v_mfma_f32_16x16x32_bf16 v[40:43], v[136:139], v[212:215], v[40:43]
	v_mfma_f32_16x16x32_bf16 v[32:35], v[144:147], v[212:215], v[32:35]
	v_mfma_f32_16x16x32_bf16 v[24:27], v[136:139], v[220:223], v[24:27]
	v_mfma_f32_16x16x32_bf16 v[16:19], v[144:147], v[220:223], v[16:19]
	s_barrier
	s_add_u32 s12, s24, 0x80
	s_addc_u32 s13, s25, 0
	v_mov_b32_e32 v132, v200
	s_add_i32 s20, s22, s68
	s_mov_b32 m0, s20
	s_nop 0
	global_load_lds_dwordx4 v132, s[12:13]
	v_mov_b32_e32 v132, v202
	s_add_i32 m0, s20, 0x2000
	s_nop 0
	global_load_lds_dwordx4 v132, s[12:13]
	s_waitcnt vmcnt(6)
	s_barrier
	v_mfma_f32_16x16x32_bf16 v[44:47], v[224:227], v[148:151], v[44:47]
	v_mfma_f32_16x16x32_bf16 v[36:39], v[232:235], v[148:151], v[36:39]
	v_mfma_f32_16x16x32_bf16 v[28:31], v[224:227], v[156:159], v[28:31]
	v_mfma_f32_16x16x32_bf16 v[20:23], v[232:235], v[156:159], v[20:23]
	v_mfma_f32_16x16x32_bf16 v[12:15], v[224:227], v[196:199], v[12:15]
	v_mfma_f32_16x16x32_bf16 v[8:11], v[232:235], v[196:199], v[8:11]
	v_mfma_f32_16x16x32_bf16 v[4:7], v[224:227], v[216:219], v[4:7]
	v_mfma_f32_16x16x32_bf16 v[0:3], v[232:235], v[216:219], v[0:3]
	v_mfma_f32_16x16x32_bf16 v[44:47], v[228:231], v[152:155], v[44:47]
	v_mfma_f32_16x16x32_bf16 v[36:39], v[236:239], v[152:155], v[36:39]
	v_mfma_f32_16x16x32_bf16 v[28:31], v[228:231], v[192:195], v[28:31]
	v_mfma_f32_16x16x32_bf16 v[20:23], v[236:239], v[192:195], v[20:23]
	v_mfma_f32_16x16x32_bf16 v[12:15], v[228:231], v[212:215], v[12:15]
	v_mfma_f32_16x16x32_bf16 v[8:11], v[236:239], v[212:215], v[8:11]
	v_mfma_f32_16x16x32_bf16 v[4:7], v[228:231], v[220:223], v[4:7]
	v_mfma_f32_16x16x32_bf16 v[0:3], v[236:239], v[220:223], v[0:3]
	s_add_u32 s48, s48, 0x100
	s_addc_u32 s49, s49, 0
	s_add_u32 s52, s52, 0x100
	s_addc_u32 s53, s53, 0
	s_cmp_ge_i32 s56, s76
	s_mov_b32 s12, s56
	s_barrier
	s_cbranch_scc0 .LBB0_528
	v_pk_mul_f32 v[154:155], v[126:127], 0.5 op_sel_hi:[1,0]
	v_pk_mul_f32 v[192:193], v[124:125], 0.5 op_sel_hi:[1,0]
	v_pk_mul_f32 v[156:157], v[122:123], 0.5 op_sel_hi:[1,0]
	v_pk_mul_f32 v[158:159], v[120:121], 0.5 op_sel_hi:[1,0]
	v_pk_mul_f32 v[150:151], v[110:111], 0.5 op_sel_hi:[1,0]
	v_pk_mul_f32 v[152:153], v[108:109], 0.5 op_sel_hi:[1,0]
	v_pk_mul_f32 v[126:127], v[106:107], 0.5 op_sel_hi:[1,0]
	v_pk_mul_f32 v[124:125], v[104:105], 0.5 op_sel_hi:[1,0]
	v_pk_mul_f32 v[146:147], v[118:119], 0.5 op_sel_hi:[1,0]
	v_pk_mul_f32 v[144:145], v[116:117], 0.5 op_sel_hi:[1,0]
	v_pk_mul_f32 v[142:143], v[114:115], 0.5 op_sel_hi:[1,0]
	v_pk_mul_f32 v[140:141], v[112:113], 0.5 op_sel_hi:[1,0]
	v_pk_mul_f32 v[138:139], v[94:95], 0.5 op_sel_hi:[1,0]
	v_pk_mul_f32 v[136:137], v[92:93], 0.5 op_sel_hi:[1,0]
	v_pk_mul_f32 v[134:135], v[90:91], 0.5 op_sel_hi:[1,0]
	v_pk_mul_f32 v[132:133], v[88:89], 0.5 op_sel_hi:[1,0]
	v_pk_mul_f32 v[122:123], v[102:103], 0.5 op_sel_hi:[1,0]
	v_pk_mul_f32 v[120:121], v[100:101], 0.5 op_sel_hi:[1,0]
	v_pk_mul_f32 v[118:119], v[98:99], 0.5 op_sel_hi:[1,0]
	v_pk_mul_f32 v[116:117], v[96:97], 0.5 op_sel_hi:[1,0]
	v_pk_mul_f32 v[114:115], v[78:79], 0.5 op_sel_hi:[1,0]
	v_pk_mul_f32 v[112:113], v[76:77], 0.5 op_sel_hi:[1,0]
	v_pk_mul_f32 v[110:111], v[74:75], 0.5 op_sel_hi:[1,0]
	v_pk_mul_f32 v[108:109], v[72:73], 0.5 op_sel_hi:[1,0]
	v_pk_mul_f32 v[106:107], v[86:87], 0.5 op_sel_hi:[1,0]
	v_pk_mul_f32 v[104:105], v[84:85], 0.5 op_sel_hi:[1,0]
	v_pk_mul_f32 v[102:103], v[82:83], 0.5 op_sel_hi:[1,0]
	v_pk_mul_f32 v[100:101], v[80:81], 0.5 op_sel_hi:[1,0]
	v_pk_mul_f32 v[98:99], v[70:71], 0.5 op_sel_hi:[1,0]
	v_pk_mul_f32 v[96:97], v[68:69], 0.5 op_sel_hi:[1,0]
	v_pk_mul_f32 v[94:95], v[66:67], 0.5 op_sel_hi:[1,0]
	v_pk_mul_f32 v[92:93], v[64:65], 0.5 op_sel_hi:[1,0]
	v_pk_mul_f32 v[86:87], v[62:63], 0.5 op_sel_hi:[1,0]
	v_pk_mul_f32 v[90:91], v[60:61], 0.5 op_sel_hi:[1,0]
	v_pk_mul_f32 v[84:85], v[58:59], 0.5 op_sel_hi:[1,0]
	v_pk_mul_f32 v[88:89], v[56:57], 0.5 op_sel_hi:[1,0]
	v_pk_mul_f32 v[80:81], v[46:47], 0.5 op_sel_hi:[1,0]
	v_pk_mul_f32 v[82:83], v[44:45], 0.5 op_sel_hi:[1,0]
	v_pk_mul_f32 v[78:79], v[38:39], 0.5 op_sel_hi:[1,0]
	v_pk_mul_f32 v[76:77], v[36:37], 0.5 op_sel_hi:[1,0]
	v_pk_mul_f32 v[74:75], v[54:55], 0.5 op_sel_hi:[1,0]
	v_pk_mul_f32 v[72:73], v[52:53], 0.5 op_sel_hi:[1,0]
	v_pk_mul_f32 v[70:71], v[50:51], 0.5 op_sel_hi:[1,0]
	v_pk_mul_f32 v[68:69], v[48:49], 0.5 op_sel_hi:[1,0]
	v_pk_mul_f32 v[66:67], v[30:31], 0.5 op_sel_hi:[1,0]
	v_pk_mul_f32 v[64:65], v[28:29], 0.5 op_sel_hi:[1,0]
	v_pk_mul_f32 v[62:63], v[22:23], 0.5 op_sel_hi:[1,0]
	v_pk_mul_f32 v[60:61], v[20:21], 0.5 op_sel_hi:[1,0]
	v_pk_mul_f32 v[58:59], v[42:43], 0.5 op_sel_hi:[1,0]
	v_pk_mul_f32 v[56:57], v[40:41], 0.5 op_sel_hi:[1,0]
	v_pk_mul_f32 v[54:55], v[34:35], 0.5 op_sel_hi:[1,0]
	v_pk_mul_f32 v[52:53], v[32:33], 0.5 op_sel_hi:[1,0]
	v_pk_mul_f32 v[50:51], v[14:15], 0.5 op_sel_hi:[1,0]
	v_pk_mul_f32 v[48:49], v[12:13], 0.5 op_sel_hi:[1,0]
	v_pk_mul_f32 v[46:47], v[10:11], 0.5 op_sel_hi:[1,0]
	v_pk_mul_f32 v[44:45], v[8:9], 0.5 op_sel_hi:[1,0]
	v_pk_mul_f32 v[42:43], v[26:27], 0.5 op_sel_hi:[1,0]
	v_pk_mul_f32 v[40:41], v[24:25], 0.5 op_sel_hi:[1,0]
	v_pk_mul_f32 v[38:39], v[18:19], 0.5 op_sel_hi:[1,0]
	v_pk_mul_f32 v[36:37], v[16:17], 0.5 op_sel_hi:[1,0]
	v_pk_mul_f32 v[34:35], v[6:7], 0.5 op_sel_hi:[1,0]
	v_pk_mul_f32 v[32:33], v[4:5], 0.5 op_sel_hi:[1,0]
	v_pk_mul_f32 v[30:31], v[2:3], 0.5 op_sel_hi:[1,0]
	v_pk_mul_f32 v[28:29], v[0:1], 0.5 op_sel_hi:[1,0]

; #define PG8_STAGE(bufoff, gbase, voff) do { const char* _gb = (const char*)(gbase); asm volatile("" : "+s"(_gb)); _Pragma("unroll") for (int _i = 0; _i < 2; ++_i) { unsigned _vo = (voff)[_i]; asm volatile("" : "+v"(_vo)); \
;         __builtin_amdgcn_global_load_lds((const GAS unsigned*)(_gb + _vo), (LAS unsigned*)(lds + (bufoff) + ldsw + _i * 8192), 16, 0, 0); } } while (0)
; #define PG8_LDA(dst, b, h) do { _Pragma("unroll") for (int m = 0; m < 4; ++m) _Pragma("unroll") for (int k = 0; k < 2; ++k) dst[m][k] = *(const LAS bf16x8*)(lds + PG8_SA(b, h) + aoff + m * 2048 + k * 1024); } while (0)
; #define PG8_LDB(dst, b, h) do { _Pragma("unroll") for (int n = 0; n < 2; ++n) _Pragma("unroll") for (int k = 0; k < 2; ++k) dst[n][k] = *(const LAS bf16x8*)(lds + PG8_SB(b, h) + boff + n * 2048 + k * 1024); } while (0)
; #define PG8_MMA(ai, bj, At, Bt) do { __builtin_amdgcn_s_setprio(1); _Pragma("unroll") for (int m = 0; m < 4; ++m) _Pragma("unroll") for (int n = 0; n < 2; ++n) _Pragma("unroll") for (int k = 0; k < 2; ++k) \
;         acc[ai][bj][m][n] = __builtin_amdgcn_mfma_f32_16x16x32_bf16(Bt[n][k], At[m][k], acc[ai][bj][m][n], 0, 0, 0); __builtin_amdgcn_s_setprio(0); } while (0)
; #define PG8_WAIT_L(n) asm volatile("s_waitcnt lgkmcnt(" #n ")" ::: "memory")
; #define PG8_BAR __builtin_amdgcn_s_barrier()
; #define PG8_SCHED __builtin_amdgcn_sched_barrier(0)
; template <class Epi, class Ord>
; __device__ __forceinline__ void gemm_phase(LAS unsigned char* lds, const Gemm g, const Ord& S, const Epi& E) {
;     ...
;             const bool last = (t == nt - 2);
;             const char* a1 = cA + (size_t)(t + 1) * kstep;
;             const char* a2 = last ? nA : cA + (size_t)(t + 2) * kstep; const char* b2 = last ? nB : cB + (size_t)(t + 2) * kstep;
;             const char* a3 = a2 + kstep; const char* b3 = b2 + kstep;
;             PG8_LDB(B0, 0, 0); PG8_SCHED; PG8_LDA(At, 0, 0); PG8_STAGE(PG8_SA(1, 1), a1 + hstep, voffA);
;             PG8_WAIT_L(8); PG8_BAR; PG8_WAIT_L(0); PG8_MMA(0, 0, At, B0); PG8_BAR; PG8_SCHED;
;             PG8_LDB(B1, 0, 1); PG8_STAGE(PG8_SB(0, 0), b2, voffB);
;             PG8_BAR; PG8_WAIT_L(0); PG8_MMA(0, 1, At, B1); PG8_BAR;
;             PG8_LDA(At, 0, 1); PG8_STAGE(PG8_SA(0, 0), a2, voffA);
;             PG8_BAR; PG8_WAIT_L(0); PG8_MMA(1, 0, At, B0); PG8_BAR; PG8_SCHED;
.LBB0_576:
	s_add_i32 s92, s12, 2
	s_cmp_eq_u32 s72, s12
	s_cselect_b32 s20, s0, s46
	s_cselect_b32 s21, s1, s47
	s_cselect_b32 s16, s48, s90
	s_cselect_b32 s17, s49, s91
	s_add_u32 s12, s20, 0x80
	s_addc_u32 s13, s21, 0
	s_add_i32 s82, 0, 0x10000
	v_add_u32_e32 v140, s82, v197
	ds_read_b128 v[128:131], v140
	ds_read_b128 v[132:135], v140 offset:1024
	ds_read_b128 v[136:139], v140 offset:2048
	ds_read_b128 v[140:143], v140 offset:3072
	s_add_u32 s22, s46, s52
	s_addc_u32 s23, s47, s53
	s_add_u32 s22, s22, 0xffffff80
	s_addc_u32 s23, s23, -1
	v_mov_b32_e32 v158, v151
	ds_read_b128 v[144:147], v202
	ds_read_b128 v[204:207], v202 offset:1024
	ds_read_b128 v[212:215], v202 offset:2048
	ds_read_b128 v[216:219], v202 offset:3072
	ds_read_b128 v[220:223], v202 offset:4096
	ds_read_b128 v[224:227], v202 offset:5120
	ds_read_b128 v[228:231], v202 offset:6144
	ds_read_b128 v[232:235], v202 offset:7168
	s_add_i32 m0, s37, 0xc000
	s_nop 0
	global_load_lds_dwordx4 v158, s[22:23]
	v_mov_b32_e32 v158, v195
	s_add_i32 m0, s37, 0xe000
	s_nop 0
	global_load_lds_dwordx4 v158, s[22:23]
	s_waitcnt lgkmcnt(8)
	s_barrier
	s_waitcnt lgkmcnt(0)
	s_waitcnt lgkmcnt(0)
	v_mfma_f32_16x16x32_bf16 v[124:127], v[128:131], v[144:147], v[124:127]
	v_mfma_f32_16x16x32_bf16 v[120:123], v[136:139], v[144:147], v[120:123]
	v_mfma_f32_16x16x32_bf16 v[108:111], v[128:131], v[212:215], v[108:111]
	v_mfma_f32_16x16x32_bf16 v[104:107], v[136:139], v[212:215], v[104:107]
	v_mfma_f32_16x16x32_bf16 v[92:95], v[128:131], v[220:223], v[92:95]
	v_mfma_f32_16x16x32_bf16 v[88:91], v[136:139], v[220:223], v[88:91]
	v_mfma_f32_16x16x32_bf16 v[76:79], v[128:131], v[228:231], v[76:79]
	v_mfma_f32_16x16x32_bf16 v[72:75], v[136:139], v[228:231], v[72:75]
	v_mfma_f32_16x16x32_bf16 v[124:127], v[132:135], v[204:207], v[124:127]
	v_mfma_f32_16x16x32_bf16 v[120:123], v[140:143], v[204:207], v[120:123]
	v_mfma_f32_16x16x32_bf16 v[108:111], v[132:135], v[216:219], v[108:111]
	v_mfma_f32_16x16x32_bf16 v[104:107], v[140:143], v[216:219], v[104:107]
	v_mfma_f32_16x16x32_bf16 v[92:95], v[132:135], v[224:227], v[92:95]
	v_mfma_f32_16x16x32_bf16 v[88:91], v[140:143], v[224:227], v[88:91]
	v_mfma_f32_16x16x32_bf16 v[76:79], v[132:135], v[232:235], v[76:79]
	v_mfma_f32_16x16x32_bf16 v[72:75], v[140:143], v[232:235], v[72:75]
	s_barrier
	s_add_i32 s84, 0, 0x14000
	v_add_u32_e32 v158, s84, v197
	ds_read_b128 v[236:239], v158
	ds_read_b128 v[240:243], v158 offset:1024
	ds_read_b128 v[244:247], v158 offset:2048
	ds_read_b128 v[248:251], v158 offset:3072
	s_mov_b64 s[22:23], s[16:17]
	v_mov_b32_e32 v158, v194
	s_add_i32 s82, s82, s36
	s_mov_b32 m0, s82
	s_nop 0
	global_load_lds_dwordx4 v158, s[22:23]
	v_mov_b32_e32 v158, v196
	s_add_i32 m0, s82, 0x2000
	s_nop 0
	global_load_lds_dwordx4 v158, s[22:23]
	s_barrier
	s_waitcnt lgkmcnt(0)
	s_waitcnt lgkmcnt(0)
	v_mfma_f32_16x16x32_bf16 v[116:119], v[236:239], v[144:147], v[116:119]
	v_mfma_f32_16x16x32_bf16 v[112:115], v[244:247], v[144:147], v[112:115]
	v_mfma_f32_16x16x32_bf16 v[100:103], v[236:239], v[212:215], v[100:103]
	v_mfma_f32_16x16x32_bf16 v[96:99], v[244:247], v[212:215], v[96:99]
	v_mfma_f32_16x16x32_bf16 v[84:87], v[236:239], v[220:223], v[84:87]
	v_mfma_f32_16x16x32_bf16 v[80:83], v[244:247], v[220:223], v[80:83]
	v_mfma_f32_16x16x32_bf16 v[68:71], v[236:239], v[228:231], v[68:71]
	v_mfma_f32_16x16x32_bf16 v[64:67], v[244:247], v[228:231], v[64:67]
	v_mfma_f32_16x16x32_bf16 v[116:119], v[240:243], v[204:207], v[116:119]
	v_mfma_f32_16x16x32_bf16 v[112:115], v[248:251], v[204:207], v[112:115]
	v_mfma_f32_16x16x32_bf16 v[100:103], v[240:243], v[216:219], v[100:103]
	v_mfma_f32_16x16x32_bf16 v[96:99], v[248:251], v[216:219], v[96:99]
	v_mfma_f32_16x16x32_bf16 v[84:87], v[240:243], v[224:227], v[84:87]
	v_mfma_f32_16x16x32_bf16 v[80:83], v[248:251], v[224:227], v[80:83]
	v_mfma_f32_16x16x32_bf16 v[68:71], v[240:243], v[232:235], v[68:71]
	v_mfma_f32_16x16x32_bf16 v[64:67], v[248:251], v[232:235], v[64:67]
	s_mov_b64 s[22:23], s[20:21]
	v_mov_b32_e32 v158, v151
	s_mov_b32 m0, s37
	s_barrier
	ds_read_b128 v[144:147], v202 offset:16384
	ds_read_b128 v[204:207], v202 offset:17408
	ds_read_b128 v[212:215], v202 offset:18432
	ds_read_b128 v[216:219], v202 offset:19456
	ds_read_b128 v[220:223], v202 offset:20480
	ds_read_b128 v[224:227], v202 offset:21504
	ds_read_b128 v[228:231], v202 offset:22528
	ds_read_b128 v[232:235], v202 offset:23552
	s_nop 0
	global_load_lds_dwordx4 v158, s[22:23]
	v_mov_b32_e32 v158, v195
	s_mov_b32 m0, s68
	s_nop 0
	global_load_lds_dwordx4 v158, s[22:23]
	s_barrier
	s_waitcnt lgkmcnt(0)
	s_waitcnt lgkmcnt(0)
	v_mfma_f32_16x16x32_bf16 v[60:63], v[128:131], v[144:147], v[60:63]
	v_mfma_f32_16x16x32_bf16 v[56:59], v[136:139], v[144:147], v[56:59]
	v_mfma_f32_16x16x32_bf16 v[44:47], v[128:131], v[212:215], v[44:47]
	v_mfma_f32_16x16x32_bf16 v[40:43], v[136:139], v[212:215], v[40:43]
	v_mfma_f32_16x16x32_bf16 v[28:31], v[128:131], v[220:223], v[28:31]
	v_mfma_f32_16x16x32_bf16 v[24:27], v[136:139], v[220:223], v[24:27]
	v_mfma_f32_16x16x32_bf16 v[12:15], v[128:131], v[228:231], v[12:15]
	v_mfma_f32_16x16x32_bf16 v[8:11], v[136:139], v[228:231], v[8:11]
	v_mfma_f32_16x16x32_bf16 v[60:63], v[132:135], v[204:207], v[60:63]
	v_mfma_f32_16x16x32_bf16 v[56:59], v[140:143], v[204:207], v[56:59]
	v_mfma_f32_16x16x32_bf16 v[44:47], v[132:135], v[216:219], v[44:47]
	v_mfma_f32_16x16x32_bf16 v[40:43], v[140:143], v[216:219], v[40:43]
	v_mfma_f32_16x16x32_bf16 v[28:31], v[132:135], v[224:227], v[28:31]
	v_mfma_f32_16x16x32_bf16 v[24:27], v[140:143], v[224:227], v[24:27]
	v_mfma_f32_16x16x32_bf16 v[12:15], v[132:135], v[232:235], v[12:15]
	v_mfma_f32_16x16x32_bf16 v[8:11], v[140:143], v[232:235], v[8:11]
	s_barrier
; #define PG8_STAGE(bufoff, gbase, voff) do { const char* _gb = (const char*)(gbase); asm volatile("" : "+s"(_gb)); _Pragma("unroll") for (int _i = 0; _i < 2; ++_i) { unsigned _vo = (voff)[_i]; asm volatile("" : "+v"(_vo)); \
;         __builtin_amdgcn_global_load_lds((const GAS unsigned*)(_gb + _vo), (LAS unsigned*)(lds + (bufoff) + ldsw + _i * 8192), 16, 0, 0); } } while (0)
; #define PG8_LDA(dst, b, h) do { _Pragma("unroll") for (int m = 0; m < 4; ++m) _Pragma("unroll") for (int k = 0; k < 2; ++k) dst[m][k] = *(const LAS bf16x8*)(lds + PG8_SA(b, h) + aoff + m * 2048 + k * 1024); } while (0)
; #define PG8_LDB(dst, b, h) do { _Pragma("unroll") for (int n = 0; n < 2; ++n) _Pragma("unroll") for (int k = 0; k < 2; ++k) dst[n][k] = *(const LAS bf16x8*)(lds + PG8_SB(b, h) + boff + n * 2048 + k * 1024); } while (0)
; #define PG8_MMA(ai, bj, At, Bt) do { __builtin_amdgcn_s_setprio(1); _Pragma("unroll") for (int m = 0; m < 4; ++m) _Pragma("unroll") for (int n = 0; n < 2; ++n) _Pragma("unroll") for (int k = 0; k < 2; ++k) \
;         acc[ai][bj][m][n] = __builtin_amdgcn_mfma_f32_16x16x32_bf16(Bt[n][k], At[m][k], acc[ai][bj][m][n], 0, 0, 0); __builtin_amdgcn_s_setprio(0); } while (0)
; #define PG8_WAIT_V(n) asm volatile("s_waitcnt vmcnt(" #n ")" ::: "memory")
; #define PG8_WAIT_L(n) asm volatile("s_waitcnt lgkmcnt(" #n ")" ::: "memory")
; #define PG8_BAR __builtin_amdgcn_s_barrier()
; #define PG8_SCHED __builtin_amdgcn_sched_barrier(0)
; template <class Epi, class Ord>
; __device__ __forceinline__ void gemm_phase(LAS unsigned char* lds, const Gemm g, const Ord& S, const Epi& E) {
;     ...
;             PG8_STAGE(PG8_SB(0, 1), b2 + hstep, voffB);
;             PG8_WAIT_V(6); PG8_BAR; PG8_MMA(1, 1, At, B1); PG8_BAR;
;             PG8_LDB(B0, 1, 0); PG8_SCHED; PG8_LDA(At, 1, 0); PG8_STAGE(PG8_SA(0, 1), a2 + hstep, voffA);
;             PG8_WAIT_L(8); PG8_BAR; PG8_WAIT_L(0); PG8_MMA(0, 0, At, B0); PG8_BAR; PG8_SCHED;
;             PG8_LDB(B1, 1, 1); PG8_STAGE(PG8_SB(1, 0), b3, voffB);
	s_add_u32 s22, s16, s52
	s_addc_u32 s23, s17, s53
	s_mov_b64 s[82:83], s[22:23]
	v_mov_b32_e32 v128, v194
	s_add_i32 s84, s84, s36
	s_mov_b32 m0, s84
	s_nop 0
	global_load_lds_dwordx4 v128, s[82:83]
	v_mov_b32_e32 v128, v196
	s_add_i32 m0, s84, 0x2000
	s_nop 0
	global_load_lds_dwordx4 v128, s[82:83]
	s_waitcnt vmcnt(6)
	s_barrier
	v_mfma_f32_16x16x32_bf16 v[52:55], v[236:239], v[144:147], v[52:55]
	v_mfma_f32_16x16x32_bf16 v[48:51], v[244:247], v[144:147], v[48:51]
	v_mfma_f32_16x16x32_bf16 v[36:39], v[236:239], v[212:215], v[36:39]
	v_mfma_f32_16x16x32_bf16 v[32:35], v[244:247], v[212:215], v[32:35]
	v_mfma_f32_16x16x32_bf16 v[20:23], v[236:239], v[220:223], v[20:23]
	v_mfma_f32_16x16x32_bf16 v[16:19], v[244:247], v[220:223], v[16:19]
	v_mfma_f32_16x16x32_bf16 v[4:7], v[236:239], v[228:231], v[4:7]
	v_mfma_f32_16x16x32_bf16 v[0:3], v[244:247], v[228:231], v[0:3]
	v_mfma_f32_16x16x32_bf16 v[52:55], v[240:243], v[204:207], v[52:55]
	v_mfma_f32_16x16x32_bf16 v[48:51], v[248:251], v[204:207], v[48:51]
	v_mfma_f32_16x16x32_bf16 v[36:39], v[240:243], v[216:219], v[36:39]
	v_mfma_f32_16x16x32_bf16 v[32:35], v[248:251], v[216:219], v[32:35]
	v_mfma_f32_16x16x32_bf16 v[20:23], v[240:243], v[224:227], v[20:23]
	v_mfma_f32_16x16x32_bf16 v[16:19], v[248:251], v[224:227], v[16:19]
	v_mfma_f32_16x16x32_bf16 v[4:7], v[240:243], v[232:235], v[4:7]
	v_mfma_f32_16x16x32_bf16 v[0:3], v[248:251], v[232:235], v[0:3]
	s_add_i32 s82, 0, 0x18000
	v_add_u32_e32 v140, s82, v197
	s_barrier
	ds_read_b128 v[128:131], v140
	ds_read_b128 v[132:135], v140 offset:1024
	ds_read_b128 v[136:139], v140 offset:2048
	ds_read_b128 v[140:143], v140 offset:3072
	s_add_u32 s20, s20, s52
	s_addc_u32 s21, s21, s53
	v_mov_b32_e32 v158, v151
	s_mov_b32 m0, s69
	ds_read_b128 v[144:147], v202 offset:32768
	ds_read_b128 v[204:207], v202 offset:33792
	ds_read_b128 v[212:215], v202 offset:34816
	ds_read_b128 v[216:219], v202 offset:35840
	ds_read_b128 v[220:223], v202 offset:36864
	ds_read_b128 v[224:227], v202 offset:37888
	ds_read_b128 v[228:231], v202 offset:38912
	ds_read_b128 v[232:235], v202 offset:39936
	s_nop 0
	global_load_lds_dwordx4 v158, s[20:21]
	v_mov_b32_e32 v158, v195
	s_mov_b32 m0, s64
	s_nop 0
	global_load_lds_dwordx4 v158, s[20:21]
	s_waitcnt lgkmcnt(8)
	s_barrier
	s_waitcnt lgkmcnt(0)
	s_waitcnt lgkmcnt(0)
	v_mfma_f32_16x16x32_bf16 v[124:127], v[128:131], v[144:147], v[124:127]
	v_mfma_f32_16x16x32_bf16 v[120:123], v[136:139], v[144:147], v[120:123]
	v_mfma_f32_16x16x32_bf16 v[108:111], v[128:131], v[212:215], v[108:111]
	v_mfma_f32_16x16x32_bf16 v[104:107], v[136:139], v[212:215], v[104:107]
	v_mfma_f32_16x16x32_bf16 v[92:95], v[128:131], v[220:223], v[92:95]
	v_mfma_f32_16x16x32_bf16 v[88:91], v[136:139], v[220:223], v[88:91]
	v_mfma_f32_16x16x32_bf16 v[76:79], v[128:131], v[228:231], v[76:79]
	v_mfma_f32_16x16x32_bf16 v[72:75], v[136:139], v[228:231], v[72:75]
	v_mfma_f32_16x16x32_bf16 v[124:127], v[132:135], v[204:207], v[124:127]
	v_mfma_f32_16x16x32_bf16 v[120:123], v[140:143], v[204:207], v[120:123]
	v_mfma_f32_16x16x32_bf16 v[108:111], v[132:135], v[216:219], v[108:111]
	v_mfma_f32_16x16x32_bf16 v[104:107], v[140:143], v[216:219], v[104:107]
	v_mfma_f32_16x16x32_bf16 v[92:95], v[132:135], v[224:227], v[92:95]
	v_mfma_f32_16x16x32_bf16 v[88:91], v[140:143], v[224:227], v[88:91]
	v_mfma_f32_16x16x32_bf16 v[76:79], v[132:135], v[232:235], v[76:79]
	v_mfma_f32_16x16x32_bf16 v[72:75], v[140:143], v[232:235], v[72:75]
	s_barrier
	s_add_i32 s20, 0, 0x1c000
	v_add_u32_e32 v158, s20, v197
	s_add_u32 s16, s16, 0x80
	ds_read_b128 v[236:239], v158
	ds_read_b128 v[240:243], v158 offset:1024
	ds_read_b128 v[244:247], v158 offset:2048
	ds_read_b128 v[248:251], v158 offset:3072
	s_addc_u32 s17, s17, 0
	v_mov_b32_e32 v158, v194
	s_add_i32 s21, s82, s36
	s_mov_b32 m0, s21
	s_nop 0
	global_load_lds_dwordx4 v158, s[16:17]
	v_mov_b32_e32 v158, v196
	s_add_i32 m0, s21, 0x2000
	s_nop 0
	global_load_lds_dwordx4 v158, s[16:17]
	s_barrier
; #define PG8_STAGE(bufoff, gbase, voff) do { const char* _gb = (const char*)(gbase); asm volatile("" : "+s"(_gb)); _Pragma("unroll") for (int _i = 0; _i < 2; ++_i) { unsigned _vo = (voff)[_i]; asm volatile("" : "+v"(_vo)); \
;         __builtin_amdgcn_global_load_lds((const GAS unsigned*)(_gb + _vo), (LAS unsigned*)(lds + (bufoff) + ldsw + _i * 8192), 16, 0, 0); } } while (0)
; #define PG8_LDA(dst, b, h) do { _Pragma("unroll") for (int m = 0; m < 4; ++m) _Pragma("unroll") for (int k = 0; k < 2; ++k) dst[m][k] = *(const LAS bf16x8*)(lds + PG8_SA(b, h) + aoff + m * 2048 + k * 1024); } while (0)
; #define PG8_MMA(ai, bj, At, Bt) do { __builtin_amdgcn_s_setprio(1); _Pragma("unroll") for (int m = 0; m < 4; ++m) _Pragma("unroll") for (int n = 0; n < 2; ++n) _Pragma("unroll") for (int k = 0; k < 2; ++k) \
;         acc[ai][bj][m][n] = __builtin_amdgcn_mfma_f32_16x16x32_bf16(Bt[n][k], At[m][k], acc[ai][bj][m][n], 0, 0, 0); __builtin_amdgcn_s_setprio(0); } while (0)
; #define PG8_WAIT_V(n) asm volatile("s_waitcnt vmcnt(" #n ")" ::: "memory")
; #define PG8_WAIT_L(n) asm volatile("s_waitcnt lgkmcnt(" #n ")" ::: "memory")
; #define PG8_BAR __builtin_amdgcn_s_barrier()
; #define PG8_SCHED __builtin_amdgcn_sched_barrier(0)
; template <class Epi, class Ord>
; __device__ __forceinline__ void gemm_phase(LAS unsigned char* lds, const Gemm g, const Ord& S, const Epi& E) {
;     ...
;         for (int t = 0; t < nt; t += 2) {
;             const bool last = (t == nt - 2);
;             const char* a1 = cA + (size_t)(t + 1) * kstep;
;             const char* a2 = last ? nA : cA + (size_t)(t + 2) * kstep; const char* b2 = last ? nB : cB + (size_t)(t + 2) * kstep;
;     ...
;             PG8_BAR; PG8_WAIT_L(0); PG8_MMA(0, 1, At, B1); PG8_BAR;
;             PG8_LDA(At, 1, 1); PG8_STAGE(PG8_SA(1, 0), a3, voffA);
;             PG8_BAR; PG8_WAIT_L(0); PG8_MMA(1, 0, At, B0); PG8_BAR; PG8_SCHED;
;             PG8_STAGE(PG8_SB(1, 1), b3 + hstep, voffB);
;             PG8_WAIT_V(6); PG8_BAR; PG8_MMA(1, 1, At, B1); PG8_BAR;
	s_waitcnt lgkmcnt(0)
	s_waitcnt lgkmcnt(0)
	v_mfma_f32_16x16x32_bf16 v[116:119], v[236:239], v[144:147], v[116:119]
	v_mfma_f32_16x16x32_bf16 v[112:115], v[244:247], v[144:147], v[112:115]
	v_mfma_f32_16x16x32_bf16 v[100:103], v[236:239], v[212:215], v[100:103]
	v_mfma_f32_16x16x32_bf16 v[96:99], v[244:247], v[212:215], v[96:99]
	v_mfma_f32_16x16x32_bf16 v[84:87], v[236:239], v[220:223], v[84:87]
	v_mfma_f32_16x16x32_bf16 v[80:83], v[244:247], v[220:223], v[80:83]
	v_mfma_f32_16x16x32_bf16 v[68:71], v[236:239], v[228:231], v[68:71]
	v_mfma_f32_16x16x32_bf16 v[64:67], v[244:247], v[228:231], v[64:67]
	v_mfma_f32_16x16x32_bf16 v[116:119], v[240:243], v[204:207], v[116:119]
	v_mfma_f32_16x16x32_bf16 v[112:115], v[248:251], v[204:207], v[112:115]
	v_mfma_f32_16x16x32_bf16 v[100:103], v[240:243], v[216:219], v[100:103]
	v_mfma_f32_16x16x32_bf16 v[96:99], v[248:251], v[216:219], v[96:99]
	v_mfma_f32_16x16x32_bf16 v[84:87], v[240:243], v[224:227], v[84:87]
	v_mfma_f32_16x16x32_bf16 v[80:83], v[248:251], v[224:227], v[80:83]
	v_mfma_f32_16x16x32_bf16 v[68:71], v[240:243], v[232:235], v[68:71]
	v_mfma_f32_16x16x32_bf16 v[64:67], v[248:251], v[232:235], v[64:67]
	v_mov_b32_e32 v158, v151
	s_mov_b32 m0, s73
	s_barrier
	ds_read_b128 v[144:147], v202 offset:49152
	ds_read_b128 v[204:207], v202 offset:50176
	ds_read_b128 v[212:215], v202 offset:51200
	ds_read_b128 v[216:219], v202 offset:52224
	ds_read_b128 v[220:223], v202 offset:53248
	ds_read_b128 v[224:227], v202 offset:54272
	ds_read_b128 v[228:231], v202 offset:55296
	ds_read_b128 v[232:235], v202 offset:56320
	s_nop 0
	global_load_lds_dwordx4 v158, s[12:13]
	v_mov_b32_e32 v158, v195
	s_mov_b32 m0, s74
	s_nop 0
	global_load_lds_dwordx4 v158, s[12:13]
	s_barrier
	s_waitcnt lgkmcnt(0)
	s_waitcnt lgkmcnt(0)
	v_mfma_f32_16x16x32_bf16 v[60:63], v[128:131], v[144:147], v[60:63]
	v_mfma_f32_16x16x32_bf16 v[56:59], v[136:139], v[144:147], v[56:59]
	v_mfma_f32_16x16x32_bf16 v[44:47], v[128:131], v[212:215], v[44:47]
	v_mfma_f32_16x16x32_bf16 v[40:43], v[136:139], v[212:215], v[40:43]
	v_mfma_f32_16x16x32_bf16 v[28:31], v[128:131], v[220:223], v[28:31]
	v_mfma_f32_16x16x32_bf16 v[24:27], v[136:139], v[220:223], v[24:27]
	v_mfma_f32_16x16x32_bf16 v[12:15], v[128:131], v[228:231], v[12:15]
	v_mfma_f32_16x16x32_bf16 v[8:11], v[136:139], v[228:231], v[8:11]
	v_mfma_f32_16x16x32_bf16 v[60:63], v[132:135], v[204:207], v[60:63]
	v_mfma_f32_16x16x32_bf16 v[56:59], v[140:143], v[204:207], v[56:59]
	v_mfma_f32_16x16x32_bf16 v[44:47], v[132:135], v[216:219], v[44:47]
	v_mfma_f32_16x16x32_bf16 v[40:43], v[140:143], v[216:219], v[40:43]
	v_mfma_f32_16x16x32_bf16 v[28:31], v[132:135], v[224:227], v[28:31]
	v_mfma_f32_16x16x32_bf16 v[24:27], v[140:143], v[224:227], v[24:27]
	v_mfma_f32_16x16x32_bf16 v[12:15], v[132:135], v[232:235], v[12:15]
	v_mfma_f32_16x16x32_bf16 v[8:11], v[140:143], v[232:235], v[8:11]
	s_barrier
	s_add_u32 s12, s22, 0x80
	s_addc_u32 s13, s23, 0
	v_mov_b32_e32 v128, v194
	s_add_i32 s16, s20, s36
	s_mov_b32 m0, s16
	s_nop 0
	global_load_lds_dwordx4 v128, s[12:13]
	v_mov_b32_e32 v128, v196
	s_add_i32 m0, s16, 0x2000
	s_nop 0
	global_load_lds_dwordx4 v128, s[12:13]
	s_waitcnt vmcnt(6)
	s_barrier
	v_mfma_f32_16x16x32_bf16 v[52:55], v[236:239], v[144:147], v[52:55]
	v_mfma_f32_16x16x32_bf16 v[48:51], v[244:247], v[144:147], v[48:51]
	v_mfma_f32_16x16x32_bf16 v[36:39], v[236:239], v[212:215], v[36:39]
	v_mfma_f32_16x16x32_bf16 v[32:35], v[244:247], v[212:215], v[32:35]
	v_mfma_f32_16x16x32_bf16 v[20:23], v[236:239], v[220:223], v[20:23]
	v_mfma_f32_16x16x32_bf16 v[16:19], v[244:247], v[220:223], v[16:19]
	v_mfma_f32_16x16x32_bf16 v[4:7], v[236:239], v[228:231], v[4:7]
	v_mfma_f32_16x16x32_bf16 v[0:3], v[244:247], v[228:231], v[0:3]
	v_mfma_f32_16x16x32_bf16 v[52:55], v[240:243], v[204:207], v[52:55]
	v_mfma_f32_16x16x32_bf16 v[48:51], v[248:251], v[204:207], v[48:51]
	v_mfma_f32_16x16x32_bf16 v[36:39], v[240:243], v[216:219], v[36:39]
	v_mfma_f32_16x16x32_bf16 v[32:35], v[248:251], v[216:219], v[32:35]
	v_mfma_f32_16x16x32_bf16 v[20:23], v[240:243], v[224:227], v[20:23]
	v_mfma_f32_16x16x32_bf16 v[16:19], v[248:251], v[224:227], v[16:19]
	v_mfma_f32_16x16x32_bf16 v[4:7], v[240:243], v[232:235], v[4:7]
	v_mfma_f32_16x16x32_bf16 v[0:3], v[248:251], v[232:235], v[0:3]
	s_add_u32 s90, s90, 0x100
	s_addc_u32 s91, s91, 0
	s_add_u32 s46, s46, 0x100
	s_addc_u32 s47, s47, 0
	s_cmp_ge_i32 s92, s76
	s_mov_b32 s12, s92
	s_barrier
	s_cbranch_scc0 .LBB0_576

; #define PG8_STAGE(bufoff, gbase, voff) do { const char* _gb = (const char*)(gbase); asm volatile("" : "+s"(_gb)); _Pragma("unroll") for (int _i = 0; _i < 2; ++_i) { unsigned _vo = (voff)[_i]; asm volatile("" : "+v"(_vo)); \
;         __builtin_amdgcn_global_load_lds((const GAS unsigned*)(_gb + _vo), (LAS unsigned*)(lds + (bufoff) + ldsw + _i * 8192), 16, 0, 0); } } while (0)
; #define PG8_LDA(dst, b, h) do { _Pragma("unroll") for (int m = 0; m < 4; ++m) _Pragma("unroll") for (int k = 0; k < 2; ++k) dst[m][k] = *(const LAS bf16x8*)(lds + PG8_SA(b, h) + aoff + m * 2048 + k * 1024); } while (0)
; #define PG8_LDB(dst, b, h) do { _Pragma("unroll") for (int n = 0; n < 2; ++n) _Pragma("unroll") for (int k = 0; k < 2; ++k) dst[n][k] = *(const LAS bf16x8*)(lds + PG8_SB(b, h) + boff + n * 2048 + k * 1024); } while (0)
; #define PG8_MMA(ai, bj, At, Bt) do { __builtin_amdgcn_s_setprio(1); _Pragma("unroll") for (int m = 0; m < 4; ++m) _Pragma("unroll") for (int n = 0; n < 2; ++n) _Pragma("unroll") for (int k = 0; k < 2; ++k) \
;         acc[ai][bj][m][n] = __builtin_amdgcn_mfma_f32_16x16x32_bf16(Bt[n][k], At[m][k], acc[ai][bj][m][n], 0, 0, 0); __builtin_amdgcn_s_setprio(0); } while (0)
; #define PG8_WAIT_L(n) asm volatile("s_waitcnt lgkmcnt(" #n ")" ::: "memory")
; #define PG8_BAR __builtin_amdgcn_s_barrier()
; #define PG8_SCHED __builtin_amdgcn_sched_barrier(0)
; template <class Epi, class Ord>
; __device__ __forceinline__ void gemm_phase(LAS unsigned char* lds, const Gemm g, const Ord& S, const Epi& E) {
;     ...
;             const bool last = (t == nt - 2);
;             const char* a1 = cA + (size_t)(t + 1) * kstep;
;             const char* a2 = last ? nA : cA + (size_t)(t + 2) * kstep; const char* b2 = last ? nB : cB + (size_t)(t + 2) * kstep;
;             const char* a3 = a2 + kstep; const char* b3 = b2 + kstep;
;             PG8_LDB(B0, 0, 0); PG8_SCHED; PG8_LDA(At, 0, 0); PG8_STAGE(PG8_SA(1, 1), a1 + hstep, voffA);
;             PG8_WAIT_L(8); PG8_BAR; PG8_WAIT_L(0); PG8_MMA(0, 0, At, B0); PG8_BAR; PG8_SCHED;
;             PG8_LDB(B1, 0, 1); PG8_STAGE(PG8_SB(0, 0), b2, voffB);
;             PG8_BAR; PG8_WAIT_L(0); PG8_MMA(0, 1, At, B1); PG8_BAR;
;             PG8_LDA(At, 0, 1); PG8_STAGE(PG8_SA(0, 0), a2, voffA);
;             PG8_BAR; PG8_WAIT_L(0); PG8_MMA(1, 0, At, B0); PG8_BAR; PG8_SCHED;
.LBB0_613:
	s_add_i32 s74, s12, 2
	s_cmp_eq_u32 s67, s12
	s_cselect_b32 s22, s38, s46
	s_cselect_b32 s23, s39, s47
	s_cselect_b32 s20, s42, s44
	s_cselect_b32 s21, s43, s45
	s_add_u32 s12, s22, 0x80
	s_addc_u32 s13, s23, 0
	s_add_i32 s75, 0, 0x10000
	v_add_u32_e32 v152, s75, v133
	ds_read_b128 v[140:143], v152
	ds_read_b128 v[144:147], v152 offset:1024
	ds_read_b128 v[148:151], v152 offset:2048
	ds_read_b128 v[152:155], v152 offset:3072
	s_add_u32 s24, s46, s0
	s_addc_u32 s25, s47, s1
	s_add_u32 s24, s24, 0xffffff80
	s_addc_u32 s25, s25, -1
	v_mov_b32_e32 v168, v128
	ds_read_b128 v[156:159], v139
	ds_read_b128 v[192:195], v139 offset:1024
	ds_read_b128 v[196:199], v139 offset:2048
	ds_read_b128 v[200:203], v139 offset:3072
	ds_read_b128 v[204:207], v139 offset:4096
	ds_read_b128 v[212:215], v139 offset:5120
	ds_read_b128 v[216:219], v139 offset:6144
	ds_read_b128 v[220:223], v139 offset:7168
	s_add_i32 m0, s53, 0xc000
	s_nop 0
	global_load_lds_dwordx4 v168, s[24:25]
	v_mov_b32_e32 v168, v130
	s_add_i32 m0, s53, 0xe000
	s_nop 0
	global_load_lds_dwordx4 v168, s[24:25]
	s_waitcnt lgkmcnt(8)
	s_barrier
	s_waitcnt lgkmcnt(0)
	s_waitcnt lgkmcnt(0)
	v_mfma_f32_16x16x32_bf16 v[120:123], v[140:143], v[156:159], v[120:123]
	v_mfma_f32_16x16x32_bf16 v[112:115], v[148:151], v[156:159], v[112:115]
	v_mfma_f32_16x16x32_bf16 v[104:107], v[140:143], v[196:199], v[104:107]
	v_mfma_f32_16x16x32_bf16 v[96:99], v[148:151], v[196:199], v[96:99]
	v_mfma_f32_16x16x32_bf16 v[88:91], v[140:143], v[204:207], v[88:91]
	v_mfma_f32_16x16x32_bf16 v[80:83], v[148:151], v[204:207], v[80:83]
	v_mfma_f32_16x16x32_bf16 v[72:75], v[140:143], v[216:219], v[72:75]
	v_mfma_f32_16x16x32_bf16 v[64:67], v[148:151], v[216:219], v[64:67]
	v_mfma_f32_16x16x32_bf16 v[120:123], v[144:147], v[192:195], v[120:123]
	v_mfma_f32_16x16x32_bf16 v[112:115], v[152:155], v[192:195], v[112:115]
	v_mfma_f32_16x16x32_bf16 v[104:107], v[144:147], v[200:203], v[104:107]
	v_mfma_f32_16x16x32_bf16 v[96:99], v[152:155], v[200:203], v[96:99]
	v_mfma_f32_16x16x32_bf16 v[88:91], v[144:147], v[212:215], v[88:91]
	v_mfma_f32_16x16x32_bf16 v[80:83], v[152:155], v[212:215], v[80:83]
	v_mfma_f32_16x16x32_bf16 v[72:75], v[144:147], v[220:223], v[72:75]
	v_mfma_f32_16x16x32_bf16 v[64:67], v[152:155], v[220:223], v[64:67]
	s_barrier
	s_add_i32 s78, 0, 0x14000
	v_add_u32_e32 v168, s78, v133
	ds_read_b128 v[224:227], v168
	ds_read_b128 v[228:231], v168 offset:1024
	ds_read_b128 v[232:235], v168 offset:2048
	ds_read_b128 v[236:239], v168 offset:3072
	s_mov_b64 s[24:25], s[20:21]
	v_mov_b32_e32 v168, v129
	s_add_i32 s75, s75, s52
	s_mov_b32 m0, s75
	s_nop 0
	global_load_lds_dwordx4 v168, s[24:25]
	v_mov_b32_e32 v168, v131
	s_add_i32 m0, s75, 0x2000
	s_nop 0
	global_load_lds_dwordx4 v168, s[24:25]
	s_barrier
	s_waitcnt lgkmcnt(0)
	s_waitcnt lgkmcnt(0)
	v_mfma_f32_16x16x32_bf16 v[124:127], v[224:227], v[156:159], v[124:127]
	v_mfma_f32_16x16x32_bf16 v[116:119], v[232:235], v[156:159], v[116:119]
	v_mfma_f32_16x16x32_bf16 v[108:111], v[224:227], v[196:199], v[108:111]
	v_mfma_f32_16x16x32_bf16 v[100:103], v[232:235], v[196:199], v[100:103]
	v_mfma_f32_16x16x32_bf16 v[92:95], v[224:227], v[204:207], v[92:95]
	v_mfma_f32_16x16x32_bf16 v[84:87], v[232:235], v[204:207], v[84:87]
	v_mfma_f32_16x16x32_bf16 v[76:79], v[224:227], v[216:219], v[76:79]
	v_mfma_f32_16x16x32_bf16 v[68:71], v[232:235], v[216:219], v[68:71]
	v_mfma_f32_16x16x32_bf16 v[124:127], v[228:231], v[192:195], v[124:127]
	v_mfma_f32_16x16x32_bf16 v[116:119], v[236:239], v[192:195], v[116:119]
	v_mfma_f32_16x16x32_bf16 v[108:111], v[228:231], v[200:203], v[108:111]
	v_mfma_f32_16x16x32_bf16 v[100:103], v[236:239], v[200:203], v[100:103]
	v_mfma_f32_16x16x32_bf16 v[92:95], v[228:231], v[212:215], v[92:95]
	v_mfma_f32_16x16x32_bf16 v[84:87], v[236:239], v[212:215], v[84:87]
	v_mfma_f32_16x16x32_bf16 v[76:79], v[228:231], v[220:223], v[76:79]
	v_mfma_f32_16x16x32_bf16 v[68:71], v[236:239], v[220:223], v[68:71]
	s_mov_b64 s[24:25], s[22:23]
	v_mov_b32_e32 v168, v128
	s_mov_b32 m0, s53
	s_barrier
	ds_read_b128 v[156:159], v139 offset:16384
	ds_read_b128 v[192:195], v139 offset:17408
	ds_read_b128 v[196:199], v139 offset:18432
	ds_read_b128 v[200:203], v139 offset:19456
	ds_read_b128 v[204:207], v139 offset:20480
	ds_read_b128 v[212:215], v139 offset:21504
	ds_read_b128 v[216:219], v139 offset:22528
	ds_read_b128 v[220:223], v139 offset:23552
	s_nop 0
	global_load_lds_dwordx4 v168, s[24:25]
	v_mov_b32_e32 v168, v130
	s_mov_b32 m0, s56
	s_nop 0
	global_load_lds_dwordx4 v168, s[24:25]
	s_barrier
	s_waitcnt lgkmcnt(0)
	s_waitcnt lgkmcnt(0)
	v_mfma_f32_16x16x32_bf16 v[56:59], v[140:143], v[156:159], v[56:59]
	v_mfma_f32_16x16x32_bf16 v[48:51], v[148:151], v[156:159], v[48:51]
	v_mfma_f32_16x16x32_bf16 v[40:43], v[140:143], v[196:199], v[40:43]
	v_mfma_f32_16x16x32_bf16 v[32:35], v[148:151], v[196:199], v[32:35]
	v_mfma_f32_16x16x32_bf16 v[24:27], v[140:143], v[204:207], v[24:27]
	v_mfma_f32_16x16x32_bf16 v[16:19], v[148:151], v[204:207], v[16:19]
	v_mfma_f32_16x16x32_bf16 v[8:11], v[140:143], v[216:219], v[8:11]
	v_mfma_f32_16x16x32_bf16 v[0:3], v[148:151], v[216:219], v[0:3]
	v_mfma_f32_16x16x32_bf16 v[56:59], v[144:147], v[192:195], v[56:59]
	v_mfma_f32_16x16x32_bf16 v[48:51], v[152:155], v[192:195], v[48:51]
	v_mfma_f32_16x16x32_bf16 v[40:43], v[144:147], v[200:203], v[40:43]
	v_mfma_f32_16x16x32_bf16 v[32:35], v[152:155], v[200:203], v[32:35]
	v_mfma_f32_16x16x32_bf16 v[24:27], v[144:147], v[212:215], v[24:27]
	v_mfma_f32_16x16x32_bf16 v[16:19], v[152:155], v[212:215], v[16:19]
	v_mfma_f32_16x16x32_bf16 v[8:11], v[144:147], v[220:223], v[8:11]
	v_mfma_f32_16x16x32_bf16 v[0:3], v[152:155], v[220:223], v[0:3]
	s_barrier
; #define PG8_STAGE(bufoff, gbase, voff) do { const char* _gb = (const char*)(gbase); asm volatile("" : "+s"(_gb)); _Pragma("unroll") for (int _i = 0; _i < 2; ++_i) { unsigned _vo = (voff)[_i]; asm volatile("" : "+v"(_vo)); \
;         __builtin_amdgcn_global_load_lds((const GAS unsigned*)(_gb + _vo), (LAS unsigned*)(lds + (bufoff) + ldsw + _i * 8192), 16, 0, 0); } } while (0)
; #define PG8_LDA(dst, b, h) do { _Pragma("unroll") for (int m = 0; m < 4; ++m) _Pragma("unroll") for (int k = 0; k < 2; ++k) dst[m][k] = *(const LAS bf16x8*)(lds + PG8_SA(b, h) + aoff + m * 2048 + k * 1024); } while (0)
; #define PG8_LDB(dst, b, h) do { _Pragma("unroll") for (int n = 0; n < 2; ++n) _Pragma("unroll") for (int k = 0; k < 2; ++k) dst[n][k] = *(const LAS bf16x8*)(lds + PG8_SB(b, h) + boff + n * 2048 + k * 1024); } while (0)
; #define PG8_MMA(ai, bj, At, Bt) do { __builtin_amdgcn_s_setprio(1); _Pragma("unroll") for (int m = 0; m < 4; ++m) _Pragma("unroll") for (int n = 0; n < 2; ++n) _Pragma("unroll") for (int k = 0; k < 2; ++k) \
;         acc[ai][bj][m][n] = __builtin_amdgcn_mfma_f32_16x16x32_bf16(Bt[n][k], At[m][k], acc[ai][bj][m][n], 0, 0, 0); __builtin_amdgcn_s_setprio(0); } while (0)
; #define PG8_WAIT_V(n) asm volatile("s_waitcnt vmcnt(" #n ")" ::: "memory")
; #define PG8_WAIT_L(n) asm volatile("s_waitcnt lgkmcnt(" #n ")" ::: "memory")
; #define PG8_BAR __builtin_amdgcn_s_barrier()
; #define PG8_SCHED __builtin_amdgcn_sched_barrier(0)
; template <class Epi, class Ord>
; __device__ __forceinline__ void gemm_phase(LAS unsigned char* lds, const Gemm g, const Ord& S, const Epi& E) {
;     ...
;             PG8_STAGE(PG8_SB(0, 1), b2 + hstep, voffB);
;             PG8_WAIT_V(6); PG8_BAR; PG8_MMA(1, 1, At, B1); PG8_BAR;
;             PG8_LDB(B0, 1, 0); PG8_SCHED; PG8_LDA(At, 1, 0); PG8_STAGE(PG8_SA(0, 1), a2 + hstep, voffA);
;             PG8_WAIT_L(8); PG8_BAR; PG8_WAIT_L(0); PG8_MMA(0, 0, At, B0); PG8_BAR; PG8_SCHED;
;             PG8_LDB(B1, 1, 1); PG8_STAGE(PG8_SB(1, 0), b3, voffB);
	s_add_u32 s24, s20, s0
	s_addc_u32 s25, s21, s1
	s_mov_b64 s[76:77], s[24:25]
	v_mov_b32_e32 v140, v129
	s_add_i32 s75, s78, s52
	s_mov_b32 m0, s75
	s_nop 0
	global_load_lds_dwordx4 v140, s[76:77]
	v_mov_b32_e32 v140, v131
	s_add_i32 m0, s75, 0x2000
	s_nop 0
	global_load_lds_dwordx4 v140, s[76:77]
	s_waitcnt vmcnt(6)
	s_barrier
	v_mfma_f32_16x16x32_bf16 v[60:63], v[224:227], v[156:159], v[60:63]
	v_mfma_f32_16x16x32_bf16 v[52:55], v[232:235], v[156:159], v[52:55]
	v_mfma_f32_16x16x32_bf16 v[44:47], v[224:227], v[196:199], v[44:47]
	v_mfma_f32_16x16x32_bf16 v[36:39], v[232:235], v[196:199], v[36:39]
	v_mfma_f32_16x16x32_bf16 v[28:31], v[224:227], v[204:207], v[28:31]
	v_mfma_f32_16x16x32_bf16 v[20:23], v[232:235], v[204:207], v[20:23]
	v_mfma_f32_16x16x32_bf16 v[12:15], v[224:227], v[216:219], v[12:15]
	v_mfma_f32_16x16x32_bf16 v[4:7], v[232:235], v[216:219], v[4:7]
	v_mfma_f32_16x16x32_bf16 v[60:63], v[228:231], v[192:195], v[60:63]
	v_mfma_f32_16x16x32_bf16 v[52:55], v[236:239], v[192:195], v[52:55]
	v_mfma_f32_16x16x32_bf16 v[44:47], v[228:231], v[200:203], v[44:47]
	v_mfma_f32_16x16x32_bf16 v[36:39], v[236:239], v[200:203], v[36:39]
	v_mfma_f32_16x16x32_bf16 v[28:31], v[228:231], v[212:215], v[28:31]
	v_mfma_f32_16x16x32_bf16 v[20:23], v[236:239], v[212:215], v[20:23]
	v_mfma_f32_16x16x32_bf16 v[12:15], v[228:231], v[220:223], v[12:15]
	v_mfma_f32_16x16x32_bf16 v[4:7], v[236:239], v[220:223], v[4:7]
	s_add_i32 s75, 0, 0x18000
	v_add_u32_e32 v152, s75, v133
	s_barrier
	ds_read_b128 v[140:143], v152
	ds_read_b128 v[144:147], v152 offset:1024
	ds_read_b128 v[148:151], v152 offset:2048
	ds_read_b128 v[152:155], v152 offset:3072
	s_add_u32 s22, s22, s0
	s_addc_u32 s23, s23, s1
	v_mov_b32_e32 v168, v128
	s_mov_b32 m0, s57
	ds_read_b128 v[156:159], v139 offset:32768
	ds_read_b128 v[192:195], v139 offset:33792
	ds_read_b128 v[196:199], v139 offset:34816
	ds_read_b128 v[200:203], v139 offset:35840
	ds_read_b128 v[204:207], v139 offset:36864
	ds_read_b128 v[212:215], v139 offset:37888
	ds_read_b128 v[216:219], v139 offset:38912
	ds_read_b128 v[220:223], v139 offset:39936
	s_nop 0
	global_load_lds_dwordx4 v168, s[22:23]
	v_mov_b32_e32 v168, v130
	s_mov_b32 m0, s62
	s_nop 0
	global_load_lds_dwordx4 v168, s[22:23]
	s_waitcnt lgkmcnt(8)
	s_barrier
	s_waitcnt lgkmcnt(0)
	s_waitcnt lgkmcnt(0)
	v_mfma_f32_16x16x32_bf16 v[120:123], v[140:143], v[156:159], v[120:123]
	v_mfma_f32_16x16x32_bf16 v[112:115], v[148:151], v[156:159], v[112:115]
	v_mfma_f32_16x16x32_bf16 v[104:107], v[140:143], v[196:199], v[104:107]
	v_mfma_f32_16x16x32_bf16 v[96:99], v[148:151], v[196:199], v[96:99]
	v_mfma_f32_16x16x32_bf16 v[88:91], v[140:143], v[204:207], v[88:91]
	v_mfma_f32_16x16x32_bf16 v[80:83], v[148:151], v[204:207], v[80:83]
	v_mfma_f32_16x16x32_bf16 v[72:75], v[140:143], v[216:219], v[72:75]
	v_mfma_f32_16x16x32_bf16 v[64:67], v[148:151], v[216:219], v[64:67]
	v_mfma_f32_16x16x32_bf16 v[120:123], v[144:147], v[192:195], v[120:123]
	v_mfma_f32_16x16x32_bf16 v[112:115], v[152:155], v[192:195], v[112:115]
	v_mfma_f32_16x16x32_bf16 v[104:107], v[144:147], v[200:203], v[104:107]
	v_mfma_f32_16x16x32_bf16 v[96:99], v[152:155], v[200:203], v[96:99]
	v_mfma_f32_16x16x32_bf16 v[88:91], v[144:147], v[212:215], v[88:91]
	v_mfma_f32_16x16x32_bf16 v[80:83], v[152:155], v[212:215], v[80:83]
	v_mfma_f32_16x16x32_bf16 v[72:75], v[144:147], v[220:223], v[72:75]
	v_mfma_f32_16x16x32_bf16 v[64:67], v[152:155], v[220:223], v[64:67]
	s_barrier
	s_add_i32 s22, 0, 0x1c000
	v_add_u32_e32 v168, s22, v133
	s_add_u32 s20, s20, 0x80
	ds_read_b128 v[224:227], v168
	ds_read_b128 v[228:231], v168 offset:1024
	ds_read_b128 v[232:235], v168 offset:2048
	ds_read_b128 v[236:239], v168 offset:3072
	s_addc_u32 s21, s21, 0
	v_mov_b32_e32 v168, v129
	s_add_i32 s23, s75, s52
	s_mov_b32 m0, s23
	s_nop 0
	global_load_lds_dwordx4 v168, s[20:21]
	v_mov_b32_e32 v168, v131
	s_add_i32 m0, s23, 0x2000
	s_nop 0
	global_load_lds_dwordx4 v168, s[20:21]
	s_barrier
; #define PG8_STAGE(bufoff, gbase, voff) do { const char* _gb = (const char*)(gbase); asm volatile("" : "+s"(_gb)); _Pragma("unroll") for (int _i = 0; _i < 2; ++_i) { unsigned _vo = (voff)[_i]; asm volatile("" : "+v"(_vo)); \
;         __builtin_amdgcn_global_load_lds((const GAS unsigned*)(_gb + _vo), (LAS unsigned*)(lds + (bufoff) + ldsw + _i * 8192), 16, 0, 0); } } while (0)
; #define PG8_LDA(dst, b, h) do { _Pragma("unroll") for (int m = 0; m < 4; ++m) _Pragma("unroll") for (int k = 0; k < 2; ++k) dst[m][k] = *(const LAS bf16x8*)(lds + PG8_SA(b, h) + aoff + m * 2048 + k * 1024); } while (0)
; #define PG8_MMA(ai, bj, At, Bt) do { __builtin_amdgcn_s_setprio(1); _Pragma("unroll") for (int m = 0; m < 4; ++m) _Pragma("unroll") for (int n = 0; n < 2; ++n) _Pragma("unroll") for (int k = 0; k < 2; ++k) \
;         acc[ai][bj][m][n] = __builtin_amdgcn_mfma_f32_16x16x32_bf16(Bt[n][k], At[m][k], acc[ai][bj][m][n], 0, 0, 0); __builtin_amdgcn_s_setprio(0); } while (0)
; #define PG8_WAIT_V(n) asm volatile("s_waitcnt vmcnt(" #n ")" ::: "memory")
; #define PG8_WAIT_L(n) asm volatile("s_waitcnt lgkmcnt(" #n ")" ::: "memory")
; #define PG8_BAR __builtin_amdgcn_s_barrier()
; #define PG8_SCHED __builtin_amdgcn_sched_barrier(0)
; template <class Epi, class Ord>
; __device__ __forceinline__ void gemm_phase(LAS unsigned char* lds, const Gemm g, const Ord& S, const Epi& E) {
;     ...
;         for (int t = 0; t < nt; t += 2) {
;             const bool last = (t == nt - 2);
;             const char* a1 = cA + (size_t)(t + 1) * kstep;
;             const char* a2 = last ? nA : cA + (size_t)(t + 2) * kstep; const char* b2 = last ? nB : cB + (size_t)(t + 2) * kstep;
;     ...
;             PG8_BAR; PG8_WAIT_L(0); PG8_MMA(0, 1, At, B1); PG8_BAR;
;             PG8_LDA(At, 1, 1); PG8_STAGE(PG8_SA(1, 0), a3, voffA);
;             PG8_BAR; PG8_WAIT_L(0); PG8_MMA(1, 0, At, B0); PG8_BAR; PG8_SCHED;
;             PG8_STAGE(PG8_SB(1, 1), b3 + hstep, voffB);
;             PG8_WAIT_V(6); PG8_BAR; PG8_MMA(1, 1, At, B1); PG8_BAR;
	s_waitcnt lgkmcnt(0)
	s_waitcnt lgkmcnt(0)
	v_mfma_f32_16x16x32_bf16 v[124:127], v[224:227], v[156:159], v[124:127]
	v_mfma_f32_16x16x32_bf16 v[116:119], v[232:235], v[156:159], v[116:119]
	v_mfma_f32_16x16x32_bf16 v[108:111], v[224:227], v[196:199], v[108:111]
	v_mfma_f32_16x16x32_bf16 v[100:103], v[232:235], v[196:199], v[100:103]
	v_mfma_f32_16x16x32_bf16 v[92:95], v[224:227], v[204:207], v[92:95]
	v_mfma_f32_16x16x32_bf16 v[84:87], v[232:235], v[204:207], v[84:87]
	v_mfma_f32_16x16x32_bf16 v[76:79], v[224:227], v[216:219], v[76:79]
	v_mfma_f32_16x16x32_bf16 v[68:71], v[232:235], v[216:219], v[68:71]
	v_mfma_f32_16x16x32_bf16 v[124:127], v[228:231], v[192:195], v[124:127]
	v_mfma_f32_16x16x32_bf16 v[116:119], v[236:239], v[192:195], v[116:119]
	v_mfma_f32_16x16x32_bf16 v[108:111], v[228:231], v[200:203], v[108:111]
	v_mfma_f32_16x16x32_bf16 v[100:103], v[236:239], v[200:203], v[100:103]
	v_mfma_f32_16x16x32_bf16 v[92:95], v[228:231], v[212:215], v[92:95]
	v_mfma_f32_16x16x32_bf16 v[84:87], v[236:239], v[212:215], v[84:87]
	v_mfma_f32_16x16x32_bf16 v[76:79], v[228:231], v[220:223], v[76:79]
	v_mfma_f32_16x16x32_bf16 v[68:71], v[236:239], v[220:223], v[68:71]
	v_mov_b32_e32 v168, v128
	s_mov_b32 m0, s65
	s_barrier
	ds_read_b128 v[156:159], v139 offset:49152
	ds_read_b128 v[192:195], v139 offset:50176
	ds_read_b128 v[196:199], v139 offset:51200
	ds_read_b128 v[200:203], v139 offset:52224
	ds_read_b128 v[204:207], v139 offset:53248
	ds_read_b128 v[212:215], v139 offset:54272
	ds_read_b128 v[216:219], v139 offset:55296
	ds_read_b128 v[220:223], v139 offset:56320
	s_nop 0
	global_load_lds_dwordx4 v168, s[12:13]
	v_mov_b32_e32 v168, v130
	s_mov_b32 m0, s66
	s_nop 0
	global_load_lds_dwordx4 v168, s[12:13]
	s_barrier
	s_waitcnt lgkmcnt(0)
	s_waitcnt lgkmcnt(0)
	v_mfma_f32_16x16x32_bf16 v[56:59], v[140:143], v[156:159], v[56:59]
	v_mfma_f32_16x16x32_bf16 v[48:51], v[148:151], v[156:159], v[48:51]
	v_mfma_f32_16x16x32_bf16 v[40:43], v[140:143], v[196:199], v[40:43]
	v_mfma_f32_16x16x32_bf16 v[32:35], v[148:151], v[196:199], v[32:35]
	v_mfma_f32_16x16x32_bf16 v[24:27], v[140:143], v[204:207], v[24:27]
	v_mfma_f32_16x16x32_bf16 v[16:19], v[148:151], v[204:207], v[16:19]
	v_mfma_f32_16x16x32_bf16 v[8:11], v[140:143], v[216:219], v[8:11]
	v_mfma_f32_16x16x32_bf16 v[0:3], v[148:151], v[216:219], v[0:3]
	v_mfma_f32_16x16x32_bf16 v[56:59], v[144:147], v[192:195], v[56:59]
	v_mfma_f32_16x16x32_bf16 v[48:51], v[152:155], v[192:195], v[48:51]
	v_mfma_f32_16x16x32_bf16 v[40:43], v[144:147], v[200:203], v[40:43]
	v_mfma_f32_16x16x32_bf16 v[32:35], v[152:155], v[200:203], v[32:35]
	v_mfma_f32_16x16x32_bf16 v[24:27], v[144:147], v[212:215], v[24:27]
	v_mfma_f32_16x16x32_bf16 v[16:19], v[152:155], v[212:215], v[16:19]
	v_mfma_f32_16x16x32_bf16 v[8:11], v[144:147], v[220:223], v[8:11]
	v_mfma_f32_16x16x32_bf16 v[0:3], v[152:155], v[220:223], v[0:3]
	s_barrier
	s_add_u32 s12, s24, 0x80
	s_addc_u32 s13, s25, 0
	v_mov_b32_e32 v140, v129
	s_add_i32 s20, s22, s52
	s_mov_b32 m0, s20
	s_nop 0
	global_load_lds_dwordx4 v140, s[12:13]
	v_mov_b32_e32 v140, v131
	s_add_i32 m0, s20, 0x2000
	s_nop 0
	global_load_lds_dwordx4 v140, s[12:13]
	s_waitcnt vmcnt(6)
	s_barrier
	v_mfma_f32_16x16x32_bf16 v[60:63], v[224:227], v[156:159], v[60:63]
	v_mfma_f32_16x16x32_bf16 v[52:55], v[232:235], v[156:159], v[52:55]
	v_mfma_f32_16x16x32_bf16 v[44:47], v[224:227], v[196:199], v[44:47]
	v_mfma_f32_16x16x32_bf16 v[36:39], v[232:235], v[196:199], v[36:39]
	v_mfma_f32_16x16x32_bf16 v[28:31], v[224:227], v[204:207], v[28:31]
	v_mfma_f32_16x16x32_bf16 v[20:23], v[232:235], v[204:207], v[20:23]
	v_mfma_f32_16x16x32_bf16 v[12:15], v[224:227], v[216:219], v[12:15]
	v_mfma_f32_16x16x32_bf16 v[4:7], v[232:235], v[216:219], v[4:7]
	v_mfma_f32_16x16x32_bf16 v[60:63], v[228:231], v[192:195], v[60:63]
	v_mfma_f32_16x16x32_bf16 v[52:55], v[236:239], v[192:195], v[52:55]
	v_mfma_f32_16x16x32_bf16 v[44:47], v[228:231], v[200:203], v[44:47]
	v_mfma_f32_16x16x32_bf16 v[36:39], v[236:239], v[200:203], v[36:39]
	v_mfma_f32_16x16x32_bf16 v[28:31], v[228:231], v[212:215], v[28:31]
	v_mfma_f32_16x16x32_bf16 v[20:23], v[236:239], v[212:215], v[20:23]
	v_mfma_f32_16x16x32_bf16 v[12:15], v[228:231], v[220:223], v[12:15]
	v_mfma_f32_16x16x32_bf16 v[4:7], v[236:239], v[220:223], v[4:7]
	s_add_u32 s44, s44, 0x100
	s_addc_u32 s45, s45, 0
	s_add_u32 s46, s46, 0x100
	s_addc_u32 s47, s47, 0
	s_cmp_ge_i32 s74, s64
	s_mov_b32 s12, s74
	s_barrier
	s_cbranch_scc0 .LBB0_613
	s_branch .LBB0_603
